# GEMM M-phase: removed back-to-back s_setprio 0/1 flip between the two 16-MFMA halves and the duplicate lgkmcnt(0) after the barrier
# baseline (speedup 1.0000x reference)
; #define PG8_STAGE(bufoff, gbase, voff) do { _Pragma("unroll") for (int _i = 0; _i < 2; ++_i) \
;         dma16((const char*)(gbase), (voff)[_i], ldsb + (bufoff) + ldsw + _i * 8192); } while (0)
; #define PG8_LDA(dst, b, h) do { const int a1_ = opqv(aoff0) ^ 64; _Pragma("unroll") for (int m = 0; m < 4; ++m) { dst[m][0] = *(const LAS bf16x8*)(lds + PG8_SA(b, h) + aoff0 + m * 2048); dst[m][1] = *(const LAS bf16x8*)(lds + PG8_SA(b, h) + a1_ + m * 2048); } } while (0)
; #define PG8_LDB(dst, b, h) do { const int b1_ = opqv(boff0) ^ 64; _Pragma("unroll") for (int n = 0; n < 2; ++n) { dst[n][0] = *(const LAS bf16x8*)(lds + PG8_SB(b, h) + boff0 + n * 2048); dst[n][1] = *(const LAS bf16x8*)(lds + PG8_SB(b, h) + b1_ + n * 2048); } } while (0)
; #define PG8_MMA(ai, bj, At, Bt) do { __builtin_amdgcn_s_setprio(1); _Pragma("unroll") for (int m = 0; m < 4; ++m) _Pragma("unroll") for (int n = 0; n < 2; ++n) _Pragma("unroll") for (int k = 0; k < 2; ++k) \
;         acc[ai][bj][m][n] = __builtin_amdgcn_mfma_f32_16x16x32_bf16(Bt[n][k], At[m][k], acc[ai][bj][m][n], 0, 0, 0); __builtin_amdgcn_s_setprio(0); } while (0)
; #define PG8_WAIT_V(n) asm volatile("s_waitcnt vmcnt(" #n ")" ::: "memory")
; #define PG8_WAIT_L(n) asm volatile("s_waitcnt lgkmcnt(" #n ")" ::: "memory")
; #define PG8_BAR __builtin_amdgcn_s_barrier()
; #define PG8_SCHED __builtin_amdgcn_sched_barrier(0)
; template <class Epi>
; __device__ __forceinline__ void gemm_phase(LAS unsigned char* lds, const Gemm g, const StaticOrder& S, const Epi& E, int wave_) {
;     ...
;             const char* a2 = last ? nA : cA + (size_t)(t + 2) * kstep; const char* b2 = last ? nB : cB + (size_t)(t + 2) * kstep;
;             const char* a3 = a2 + kstep; const char* b3 = b2 + kstep;
;             PG8_STAGE(PG8_SA(1, 1), a1 + hstepA, voffA); PG8_LDB(B0, 0, 0); PG8_LDB(B1, 0, 1); PG8_SCHED; PG8_LDA(At, 0, 0);
;             PG8_WAIT_V(8); PG8_WAIT_L(0); PG8_BAR; PG8_MMA(0, 0, At, B0); PG8_MMA(0, 1, At, B1); PG8_BAR; PG8_SCHED;
;             PG8_STAGE(PG8_SB(0, 0), b2, voffB); PG8_STAGE(PG8_SB(0, 1), b2 + hstepB, voffB); PG8_STAGE(PG8_SA(0, 0), a2, voffA); PG8_LDA(At, 0, 1);
;             PG8_WAIT_V(8); PG8_WAIT_L(0); PG8_BAR; PG8_MMA(1, 0, At, B0); PG8_MMA(1, 1, At, B1); PG8_BAR; PG8_SCHED;
.LBB0_191:
	s_add_u32 s18, s12, 0xfff80080
	s_addc_u32 s19, s13, -1
	s_cmp_eq_u32 s49, 28
	s_cselect_b32 s26, s45, s18
	v_mov_b32_e32 v128, v139
	s_cselect_b32 s27, s7, s19
	s_cselect_b32 s24, s46, s47
	s_cselect_b32 s25, s5, s48
	s_add_u32 s18, s26, 0x80
	v_xad_u32 v128, v128, 64, s23
	v_add_u32_e32 v141, s23, v139
	s_addc_u32 s19, s27, 0
	ds_read_b128 v[130:133], v141
	ds_read_b128 v[142:145], v141 offset:2048
	ds_read_b128 v[146:149], v128
	ds_read_b128 v[150:153], v128 offset:2048
	v_mov_b32_e32 v128, v139
	s_add_i32 s52, 0, 0x14000
	v_add_u32_e32 v141, s52, v139
	v_xad_u32 v128, v128, 64, s52
	ds_read_b128 v[154:157], v141
	ds_read_b128 v[158:161], v141 offset:2048
	ds_read_b128 v[162:165], v128
	ds_read_b128 v[166:169], v128 offset:2048
	v_mov_b32_e32 v128, v138
	v_add_u32_e32 v141, 0, v138
	v_xad_u32 v128, v128, 64, 0
	ds_read_b128 v[170:173], v141
	ds_read_b128 v[174:177], v141 offset:2048
	ds_read_b128 v[178:181], v128
	ds_read_b128 v[192:195], v128 offset:2048
	ds_read_b128 v[196:199], v141 offset:4096
	ds_read_b128 v[200:203], v141 offset:6144
	ds_read_b128 v[204:207], v128 offset:4096
	ds_read_b128 v[208:211], v128 offset:6144
	s_mov_b32 m0, s14
	s_nop 0
	global_load_lds_dwordx4 v129, s[12:13]
	s_mov_b32 m0, s15
	s_nop 0
	global_load_lds_dwordx4 v135, s[12:13]
	s_waitcnt vmcnt(8)
	s_waitcnt lgkmcnt(0)
	s_barrier
	s_setprio 1
	v_mfma_f32_16x16x32_bf16 v[124:127], v[130:133], v[170:173], v[124:127]
	v_mfma_f32_16x16x32_bf16 v[120:123], v[142:145], v[170:173], v[120:123]
	v_mfma_f32_16x16x32_bf16 v[112:115], v[130:133], v[174:177], v[112:115]
	v_mfma_f32_16x16x32_bf16 v[104:107], v[142:145], v[174:177], v[104:107]
	v_mfma_f32_16x16x32_bf16 v[96:99], v[130:133], v[196:199], v[96:99]
	v_mfma_f32_16x16x32_bf16 v[88:91], v[142:145], v[196:199], v[88:91]
	v_mfma_f32_16x16x32_bf16 v[80:83], v[130:133], v[200:203], v[80:83]
	v_mfma_f32_16x16x32_bf16 v[72:75], v[142:145], v[200:203], v[72:75]
	v_mfma_f32_16x16x32_bf16 v[124:127], v[146:149], v[178:181], v[124:127]
	v_mfma_f32_16x16x32_bf16 v[120:123], v[150:153], v[178:181], v[120:123]
	v_mfma_f32_16x16x32_bf16 v[112:115], v[146:149], v[192:195], v[112:115]
	v_mfma_f32_16x16x32_bf16 v[104:107], v[150:153], v[192:195], v[104:107]
	v_mfma_f32_16x16x32_bf16 v[96:99], v[146:149], v[204:207], v[96:99]
	v_mfma_f32_16x16x32_bf16 v[88:91], v[150:153], v[204:207], v[88:91]
	v_mfma_f32_16x16x32_bf16 v[80:83], v[146:149], v[208:211], v[80:83]
	v_mfma_f32_16x16x32_bf16 v[72:75], v[150:153], v[208:211], v[72:75]
	v_mfma_f32_16x16x32_bf16 v[116:119], v[154:157], v[170:173], v[116:119]
	v_mfma_f32_16x16x32_bf16 v[108:111], v[158:161], v[170:173], v[108:111]
	v_mfma_f32_16x16x32_bf16 v[100:103], v[154:157], v[174:177], v[100:103]
	v_mfma_f32_16x16x32_bf16 v[92:95], v[158:161], v[174:177], v[92:95]
	v_mfma_f32_16x16x32_bf16 v[84:87], v[154:157], v[196:199], v[84:87]
	v_mfma_f32_16x16x32_bf16 v[76:79], v[158:161], v[196:199], v[76:79]
	v_mfma_f32_16x16x32_bf16 v[68:71], v[154:157], v[200:203], v[68:71]
	v_mfma_f32_16x16x32_bf16 v[64:67], v[158:161], v[200:203], v[64:67]
	v_mfma_f32_16x16x32_bf16 v[116:119], v[162:165], v[178:181], v[116:119]
	v_mfma_f32_16x16x32_bf16 v[108:111], v[166:169], v[178:181], v[108:111]
	v_mfma_f32_16x16x32_bf16 v[100:103], v[162:165], v[192:195], v[100:103]
	v_mfma_f32_16x16x32_bf16 v[92:95], v[166:169], v[192:195], v[92:95]
	v_mfma_f32_16x16x32_bf16 v[84:87], v[162:165], v[204:207], v[84:87]
	v_mfma_f32_16x16x32_bf16 v[76:79], v[166:169], v[204:207], v[76:79]
	v_mfma_f32_16x16x32_bf16 v[68:71], v[162:165], v[208:211], v[68:71]
	v_mfma_f32_16x16x32_bf16 v[64:67], v[166:169], v[208:211], v[64:67]
	s_setprio 0
	s_barrier
	s_add_u32 s54, s24, 0x80000
	s_addc_u32 s55, s25, 0
	v_mov_b32_e32 v128, v138
	s_nop 0
	s_nop 0
	s_nop 0
	v_xad_u32 v128, v128, 64, 0
	ds_read_b128 v[170:173], v141 offset:16384
	ds_read_b128 v[174:177], v141 offset:18432
	ds_read_b128 v[178:181], v128 offset:16384
	ds_read_b128 v[192:195], v128 offset:18432
	ds_read_b128 v[196:199], v141 offset:20480
	ds_read_b128 v[200:203], v141 offset:22528
	ds_read_b128 v[204:207], v128 offset:20480
	ds_read_b128 v[208:211], v128 offset:22528
	s_mov_b32 m0, s80
	s_nop 0
	global_load_lds_dwordx4 v134, s[24:25]
	s_mov_b32 m0, s81
	s_nop 0
	global_load_lds_dwordx4 v136, s[24:25]
	s_mov_b32 m0, s29
	s_nop 0
	global_load_lds_dwordx4 v134, s[54:55]
	s_mov_b32 m0, s88
	s_nop 0
	global_load_lds_dwordx4 v136, s[54:55]
	s_mov_b32 m0, s76
	s_nop 0
	global_load_lds_dwordx4 v129, s[26:27]
	s_mov_b32 m0, s89
	s_nop 0
	global_load_lds_dwordx4 v135, s[26:27]
	s_waitcnt vmcnt(8)
	s_waitcnt lgkmcnt(0)
	s_barrier
; #define PG8_STAGE(bufoff, gbase, voff) do { _Pragma("unroll") for (int _i = 0; _i < 2; ++_i) \
;         dma16((const char*)(gbase), (voff)[_i], ldsb + (bufoff) + ldsw + _i * 8192); } while (0)
; #define PG8_LDA(dst, b, h) do { const int a1_ = opqv(aoff0) ^ 64; _Pragma("unroll") for (int m = 0; m < 4; ++m) { dst[m][0] = *(const LAS bf16x8*)(lds + PG8_SA(b, h) + aoff0 + m * 2048); dst[m][1] = *(const LAS bf16x8*)(lds + PG8_SA(b, h) + a1_ + m * 2048); } } while (0)
; #define PG8_LDB(dst, b, h) do { const int b1_ = opqv(boff0) ^ 64; _Pragma("unroll") for (int n = 0; n < 2; ++n) { dst[n][0] = *(const LAS bf16x8*)(lds + PG8_SB(b, h) + boff0 + n * 2048); dst[n][1] = *(const LAS bf16x8*)(lds + PG8_SB(b, h) + b1_ + n * 2048); } } while (0)
; #define PG8_MMA(ai, bj, At, Bt) do { __builtin_amdgcn_s_setprio(1); _Pragma("unroll") for (int m = 0; m < 4; ++m) _Pragma("unroll") for (int n = 0; n < 2; ++n) _Pragma("unroll") for (int k = 0; k < 2; ++k) \
;         acc[ai][bj][m][n] = __builtin_amdgcn_mfma_f32_16x16x32_bf16(Bt[n][k], At[m][k], acc[ai][bj][m][n], 0, 0, 0); __builtin_amdgcn_s_setprio(0); } while (0)
; #define PG8_WAIT_V(n) asm volatile("s_waitcnt vmcnt(" #n ")" ::: "memory")
; #define PG8_WAIT_L(n) asm volatile("s_waitcnt lgkmcnt(" #n ")" ::: "memory")
; #define PG8_BAR __builtin_amdgcn_s_barrier()
; #define PG8_SCHED __builtin_amdgcn_sched_barrier(0)
; template <class Epi>
; __device__ __forceinline__ void gemm_phase(LAS unsigned char* lds, const Gemm g, const StaticOrder& S, const Epi& E, int wave_) {
;     ...
;             PG8_WAIT_V(8); PG8_WAIT_L(0); PG8_BAR; PG8_MMA(1, 0, At, B0); PG8_MMA(1, 1, At, B1); PG8_BAR; PG8_SCHED;
;             PG8_STAGE(PG8_SA(0, 1), a2 + hstepA, voffA); PG8_LDB(B0, 1, 0); PG8_LDB(B1, 1, 1); PG8_SCHED; PG8_LDA(At, 1, 0);
;             PG8_WAIT_V(8); PG8_WAIT_L(0); PG8_BAR; PG8_MMA(0, 0, At, B0); PG8_MMA(0, 1, At, B1); PG8_BAR; PG8_SCHED;
	s_setprio 1
	v_mfma_f32_16x16x32_bf16 v[60:63], v[130:133], v[170:173], v[60:63]
	v_mfma_f32_16x16x32_bf16 v[56:59], v[142:145], v[170:173], v[56:59]
	v_mfma_f32_16x16x32_bf16 v[48:51], v[130:133], v[174:177], v[48:51]
	v_mfma_f32_16x16x32_bf16 v[40:43], v[142:145], v[174:177], v[40:43]
	v_mfma_f32_16x16x32_bf16 v[32:35], v[130:133], v[196:199], v[32:35]
	v_mfma_f32_16x16x32_bf16 v[24:27], v[142:145], v[196:199], v[24:27]
	v_mfma_f32_16x16x32_bf16 v[16:19], v[130:133], v[200:203], v[16:19]
	v_mfma_f32_16x16x32_bf16 v[8:11], v[142:145], v[200:203], v[8:11]
	v_mfma_f32_16x16x32_bf16 v[60:63], v[146:149], v[178:181], v[60:63]
	v_mfma_f32_16x16x32_bf16 v[56:59], v[150:153], v[178:181], v[56:59]
	v_mfma_f32_16x16x32_bf16 v[48:51], v[146:149], v[192:195], v[48:51]
	v_mfma_f32_16x16x32_bf16 v[40:43], v[150:153], v[192:195], v[40:43]
	v_mfma_f32_16x16x32_bf16 v[32:35], v[146:149], v[204:207], v[32:35]
	v_mfma_f32_16x16x32_bf16 v[24:27], v[150:153], v[204:207], v[24:27]
	v_mfma_f32_16x16x32_bf16 v[16:19], v[146:149], v[208:211], v[16:19]
	v_mfma_f32_16x16x32_bf16 v[8:11], v[150:153], v[208:211], v[8:11]
	v_mfma_f32_16x16x32_bf16 v[52:55], v[154:157], v[170:173], v[52:55]
	v_mfma_f32_16x16x32_bf16 v[44:47], v[158:161], v[170:173], v[44:47]
	v_mfma_f32_16x16x32_bf16 v[36:39], v[154:157], v[174:177], v[36:39]
	v_mfma_f32_16x16x32_bf16 v[28:31], v[158:161], v[174:177], v[28:31]
	v_mfma_f32_16x16x32_bf16 v[20:23], v[154:157], v[196:199], v[20:23]
	v_mfma_f32_16x16x32_bf16 v[12:15], v[158:161], v[196:199], v[12:15]
	v_mfma_f32_16x16x32_bf16 v[4:7], v[154:157], v[200:203], v[4:7]
	v_mfma_f32_16x16x32_bf16 v[0:3], v[158:161], v[200:203], v[0:3]
	v_mfma_f32_16x16x32_bf16 v[52:55], v[162:165], v[178:181], v[52:55]
	v_mfma_f32_16x16x32_bf16 v[44:47], v[166:169], v[178:181], v[44:47]
	v_mfma_f32_16x16x32_bf16 v[36:39], v[162:165], v[192:195], v[36:39]
	v_mfma_f32_16x16x32_bf16 v[28:31], v[166:169], v[192:195], v[28:31]
	v_mfma_f32_16x16x32_bf16 v[20:23], v[162:165], v[204:207], v[20:23]
	v_mfma_f32_16x16x32_bf16 v[12:15], v[166:169], v[204:207], v[12:15]
	v_mfma_f32_16x16x32_bf16 v[4:7], v[162:165], v[208:211], v[4:7]
	v_mfma_f32_16x16x32_bf16 v[0:3], v[166:169], v[208:211], v[0:3]
	s_setprio 0
	s_barrier
	s_add_u32 s26, s26, 0x80000
	s_addc_u32 s27, s27, 0
	s_mov_b32 m0, s1
	s_nop 0
	global_load_lds_dwordx4 v129, s[26:27]
	v_mov_b32_e32 v128, v139
	s_mov_b32 m0, s69
	s_nop 0
	global_load_lds_dwordx4 v135, s[26:27]
	v_add_u32_e32 v142, s34, v139
	v_xad_u32 v128, v128, 64, s34
	ds_read_b128 v[130:133], v142
	ds_read_b128 v[142:145], v142 offset:2048
	ds_read_b128 v[146:149], v128
	ds_read_b128 v[150:153], v128 offset:2048
	v_mov_b32_e32 v128, v139
	s_add_i32 s26, 0, 0x1c000
	v_add_u32_e32 v158, s26, v139
	v_xad_u32 v128, v128, 64, s26
	ds_read_b128 v[154:157], v158
	ds_read_b128 v[158:161], v158 offset:2048
	ds_read_b128 v[162:165], v128
	ds_read_b128 v[166:169], v128 offset:2048
	v_mov_b32_e32 v128, v138
	s_nop 0
	v_xad_u32 v128, v128, 64, 0
	ds_read_b128 v[170:173], v141 offset:32768
	ds_read_b128 v[174:177], v141 offset:34816
	ds_read_b128 v[178:181], v128 offset:32768
	ds_read_b128 v[192:195], v128 offset:34816
	ds_read_b128 v[196:199], v141 offset:36864
	ds_read_b128 v[200:203], v141 offset:38912
	ds_read_b128 v[204:207], v128 offset:36864
	ds_read_b128 v[208:211], v128 offset:38912
	s_waitcnt vmcnt(8)
	s_waitcnt lgkmcnt(0)
	s_barrier
	s_setprio 1
	v_mfma_f32_16x16x32_bf16 v[124:127], v[130:133], v[170:173], v[124:127]
	v_mfma_f32_16x16x32_bf16 v[120:123], v[142:145], v[170:173], v[120:123]
	v_mfma_f32_16x16x32_bf16 v[112:115], v[130:133], v[174:177], v[112:115]
	v_mfma_f32_16x16x32_bf16 v[104:107], v[142:145], v[174:177], v[104:107]
	v_mfma_f32_16x16x32_bf16 v[96:99], v[130:133], v[196:199], v[96:99]
	v_mfma_f32_16x16x32_bf16 v[88:91], v[142:145], v[196:199], v[88:91]
	v_mfma_f32_16x16x32_bf16 v[80:83], v[130:133], v[200:203], v[80:83]
	v_mfma_f32_16x16x32_bf16 v[72:75], v[142:145], v[200:203], v[72:75]
	v_mfma_f32_16x16x32_bf16 v[124:127], v[146:149], v[178:181], v[124:127]
	v_mfma_f32_16x16x32_bf16 v[120:123], v[150:153], v[178:181], v[120:123]
	v_mfma_f32_16x16x32_bf16 v[112:115], v[146:149], v[192:195], v[112:115]
	v_mfma_f32_16x16x32_bf16 v[104:107], v[150:153], v[192:195], v[104:107]
	v_mfma_f32_16x16x32_bf16 v[96:99], v[146:149], v[204:207], v[96:99]
	v_mfma_f32_16x16x32_bf16 v[88:91], v[150:153], v[204:207], v[88:91]
	v_mfma_f32_16x16x32_bf16 v[80:83], v[146:149], v[208:211], v[80:83]
	v_mfma_f32_16x16x32_bf16 v[72:75], v[150:153], v[208:211], v[72:75]
	v_mfma_f32_16x16x32_bf16 v[116:119], v[154:157], v[170:173], v[116:119]
	s_add_u32 s26, s24, 0x80
	s_addc_u32 s27, s25, 0
	v_mfma_f32_16x16x32_bf16 v[108:111], v[158:161], v[170:173], v[108:111]
	v_mfma_f32_16x16x32_bf16 v[100:103], v[154:157], v[174:177], v[100:103]
	v_mfma_f32_16x16x32_bf16 v[92:95], v[158:161], v[174:177], v[92:95]
	v_mfma_f32_16x16x32_bf16 v[84:87], v[154:157], v[196:199], v[84:87]
	v_mfma_f32_16x16x32_bf16 v[76:79], v[158:161], v[196:199], v[76:79]
	v_mfma_f32_16x16x32_bf16 v[68:71], v[154:157], v[200:203], v[68:71]
	v_mfma_f32_16x16x32_bf16 v[64:67], v[158:161], v[200:203], v[64:67]
	v_mfma_f32_16x16x32_bf16 v[116:119], v[162:165], v[178:181], v[116:119]
	v_mfma_f32_16x16x32_bf16 v[108:111], v[166:169], v[178:181], v[108:111]
	v_mfma_f32_16x16x32_bf16 v[100:103], v[162:165], v[192:195], v[100:103]
	v_mfma_f32_16x16x32_bf16 v[92:95], v[166:169], v[192:195], v[92:95]
	v_mfma_f32_16x16x32_bf16 v[84:87], v[162:165], v[204:207], v[84:87]
	v_mfma_f32_16x16x32_bf16 v[76:79], v[166:169], v[204:207], v[76:79]
	v_mfma_f32_16x16x32_bf16 v[68:71], v[162:165], v[208:211], v[68:71]
	v_mfma_f32_16x16x32_bf16 v[64:67], v[166:169], v[208:211], v[64:67]
	s_setprio 0
	s_barrier
; #define PG8_STAGE(bufoff, gbase, voff) do { _Pragma("unroll") for (int _i = 0; _i < 2; ++_i) \
;         dma16((const char*)(gbase), (voff)[_i], ldsb + (bufoff) + ldsw + _i * 8192); } while (0)
; #define PG8_LDA(dst, b, h) do { const int a1_ = opqv(aoff0) ^ 64; _Pragma("unroll") for (int m = 0; m < 4; ++m) { dst[m][0] = *(const LAS bf16x8*)(lds + PG8_SA(b, h) + aoff0 + m * 2048); dst[m][1] = *(const LAS bf16x8*)(lds + PG8_SA(b, h) + a1_ + m * 2048); } } while (0)
; #define PG8_MMA(ai, bj, At, Bt) do { __builtin_amdgcn_s_setprio(1); _Pragma("unroll") for (int m = 0; m < 4; ++m) _Pragma("unroll") for (int n = 0; n < 2; ++n) _Pragma("unroll") for (int k = 0; k < 2; ++k) \
;         acc[ai][bj][m][n] = __builtin_amdgcn_mfma_f32_16x16x32_bf16(Bt[n][k], At[m][k], acc[ai][bj][m][n], 0, 0, 0); __builtin_amdgcn_s_setprio(0); } while (0)
; #define PG8_WAIT_V(n) asm volatile("s_waitcnt vmcnt(" #n ")" ::: "memory")
; #define PG8_WAIT_L(n) asm volatile("s_waitcnt lgkmcnt(" #n ")" ::: "memory")
; #define PG8_BAR __builtin_amdgcn_s_barrier()
; #define PG8_SCHED __builtin_amdgcn_sched_barrier(0)
; template <class Epi>
; __device__ __forceinline__ void gemm_phase(LAS unsigned char* lds, const Gemm g, const StaticOrder& S, const Epi& E, int wave_) {
;     ...
;             PG8_STAGE(PG8_SB(1, 0), b3, voffB); PG8_STAGE(PG8_SB(1, 1), b3 + hstepB, voffB); PG8_STAGE(PG8_SA(1, 0), a3, voffA); PG8_LDA(At, 1, 1);
;             PG8_WAIT_V(8); PG8_WAIT_L(0); PG8_BAR; PG8_MMA(1, 0, At, B0); PG8_MMA(1, 1, At, B1); PG8_BAR; PG8_SCHED;
;         }
	s_add_u32 s24, s24, 0x80080
	s_addc_u32 s25, s25, 0
	v_mov_b32_e32 v128, v138
	s_nop 0
	s_nop 0
	v_xad_u32 v128, v128, 64, 0
	ds_read_b128 v[170:173], v141 offset:49152
	ds_read_b128 v[174:177], v141 offset:51200
	ds_read_b128 v[178:181], v128 offset:49152
	ds_read_b128 v[192:195], v128 offset:51200
	ds_read_b128 v[196:199], v141 offset:53248
	ds_read_b128 v[200:203], v141 offset:55296
	ds_read_b128 v[204:207], v128 offset:53248
	ds_read_b128 v[208:211], v128 offset:55296
	s_mov_b32 m0, s35
	s_nop 0
	global_load_lds_dwordx4 v134, s[26:27]
	s_mov_b32 m0, s33
	s_nop 0
	global_load_lds_dwordx4 v136, s[26:27]
	s_mov_b32 m0, s77
	s_nop 0
	global_load_lds_dwordx4 v134, s[24:25]
	s_mov_b32 m0, s3
	s_nop 0
	global_load_lds_dwordx4 v136, s[24:25]
	s_mov_b32 m0, s22
	s_nop 0
	global_load_lds_dwordx4 v129, s[18:19]
	s_mov_b32 m0, s2
	s_nop 0
	global_load_lds_dwordx4 v135, s[18:19]
	s_waitcnt vmcnt(8)
	s_waitcnt lgkmcnt(0)
	s_barrier
	s_setprio 1
	v_mfma_f32_16x16x32_bf16 v[60:63], v[130:133], v[170:173], v[60:63]
	v_mfma_f32_16x16x32_bf16 v[56:59], v[142:145], v[170:173], v[56:59]
	v_mfma_f32_16x16x32_bf16 v[48:51], v[130:133], v[174:177], v[48:51]
	v_mfma_f32_16x16x32_bf16 v[40:43], v[142:145], v[174:177], v[40:43]
	v_mfma_f32_16x16x32_bf16 v[32:35], v[130:133], v[196:199], v[32:35]
	v_mfma_f32_16x16x32_bf16 v[24:27], v[142:145], v[196:199], v[24:27]
	v_mfma_f32_16x16x32_bf16 v[16:19], v[130:133], v[200:203], v[16:19]
	v_mfma_f32_16x16x32_bf16 v[8:11], v[142:145], v[200:203], v[8:11]
	v_mfma_f32_16x16x32_bf16 v[60:63], v[146:149], v[178:181], v[60:63]
	v_mfma_f32_16x16x32_bf16 v[56:59], v[150:153], v[178:181], v[56:59]
	v_mfma_f32_16x16x32_bf16 v[48:51], v[146:149], v[192:195], v[48:51]
	v_mfma_f32_16x16x32_bf16 v[40:43], v[150:153], v[192:195], v[40:43]
	v_mfma_f32_16x16x32_bf16 v[32:35], v[146:149], v[204:207], v[32:35]
	v_mfma_f32_16x16x32_bf16 v[24:27], v[150:153], v[204:207], v[24:27]
	v_mfma_f32_16x16x32_bf16 v[16:19], v[146:149], v[208:211], v[16:19]
	v_mfma_f32_16x16x32_bf16 v[8:11], v[150:153], v[208:211], v[8:11]
	v_mfma_f32_16x16x32_bf16 v[52:55], v[154:157], v[170:173], v[52:55]
	v_mfma_f32_16x16x32_bf16 v[44:47], v[158:161], v[170:173], v[44:47]
	v_mfma_f32_16x16x32_bf16 v[36:39], v[154:157], v[174:177], v[36:39]
	v_mfma_f32_16x16x32_bf16 v[28:31], v[158:161], v[174:177], v[28:31]
	v_mfma_f32_16x16x32_bf16 v[20:23], v[154:157], v[196:199], v[20:23]
	v_mfma_f32_16x16x32_bf16 v[12:15], v[158:161], v[196:199], v[12:15]
	v_mfma_f32_16x16x32_bf16 v[4:7], v[154:157], v[200:203], v[4:7]
	v_mfma_f32_16x16x32_bf16 v[0:3], v[158:161], v[200:203], v[0:3]
	v_mfma_f32_16x16x32_bf16 v[52:55], v[162:165], v[178:181], v[52:55]
	v_mfma_f32_16x16x32_bf16 v[44:47], v[166:169], v[178:181], v[44:47]
	v_mfma_f32_16x16x32_bf16 v[36:39], v[162:165], v[192:195], v[36:39]
	v_mfma_f32_16x16x32_bf16 v[28:31], v[166:169], v[192:195], v[28:31]
	v_mfma_f32_16x16x32_bf16 v[20:23], v[162:165], v[204:207], v[20:23]
	v_mfma_f32_16x16x32_bf16 v[12:15], v[166:169], v[204:207], v[12:15]
	v_mfma_f32_16x16x32_bf16 v[4:7], v[162:165], v[208:211], v[4:7]
	v_mfma_f32_16x16x32_bf16 v[0:3], v[166:169], v[208:211], v[0:3]
	s_setprio 0
	s_barrier
	s_add_i32 s49, s49, 2
	s_add_u32 s47, s47, 0x100
	s_addc_u32 s48, s48, 0
	s_add_u32 s12, s12, 0x100
	s_addc_u32 s13, s13, 0
	s_cmp_gt_u32 s49, 29
	s_cbranch_scc0 .LBB0_191
	v_readlane_b32 s12, v253, 13
	v_readlane_b32 s13, v253, 14
	s_and_b64 vcc, exec, s[12:13]
	s_cbranch_vccz .LBB0_194
	s_barrier

; #define PG8_STAGE(bufoff, gbase, voff) do { _Pragma("unroll") for (int _i = 0; _i < 2; ++_i) \
;         dma16((const char*)(gbase), (voff)[_i], ldsb + (bufoff) + ldsw + _i * 8192); } while (0)
; #define PG8_LDA(dst, b, h) do { const int a1_ = opqv(aoff0) ^ 64; _Pragma("unroll") for (int m = 0; m < 4; ++m) { dst[m][0] = *(const LAS bf16x8*)(lds + PG8_SA(b, h) + aoff0 + m * 2048); dst[m][1] = *(const LAS bf16x8*)(lds + PG8_SA(b, h) + a1_ + m * 2048); } } while (0)
; #define PG8_LDB(dst, b, h) do { const int b1_ = opqv(boff0) ^ 64; _Pragma("unroll") for (int n = 0; n < 2; ++n) { dst[n][0] = *(const LAS bf16x8*)(lds + PG8_SB(b, h) + boff0 + n * 2048); dst[n][1] = *(const LAS bf16x8*)(lds + PG8_SB(b, h) + b1_ + n * 2048); } } while (0)
; #define PG8_MMA(ai, bj, At, Bt) do { __builtin_amdgcn_s_setprio(1); _Pragma("unroll") for (int m = 0; m < 4; ++m) _Pragma("unroll") for (int n = 0; n < 2; ++n) _Pragma("unroll") for (int k = 0; k < 2; ++k) \
;         acc[ai][bj][m][n] = __builtin_amdgcn_mfma_f32_16x16x32_bf16(Bt[n][k], At[m][k], acc[ai][bj][m][n], 0, 0, 0); __builtin_amdgcn_s_setprio(0); } while (0)
; #define PG8_WAIT_V(n) asm volatile("s_waitcnt vmcnt(" #n ")" ::: "memory")
; #define PG8_WAIT_L(n) asm volatile("s_waitcnt lgkmcnt(" #n ")" ::: "memory")
; #define PG8_BAR __builtin_amdgcn_s_barrier()
; #define PG8_SCHED __builtin_amdgcn_sched_barrier(0)
; template <class Epi>
; __device__ __forceinline__ void gemm_phase(LAS unsigned char* lds, const Gemm g, const StaticOrder& S, const Epi& E, int wave_) {
;     ...
;             const char* a2 = last ? nA : cA + (size_t)(t + 2) * kstep; const char* b2 = last ? nB : cB + (size_t)(t + 2) * kstep;
;             const char* a3 = a2 + kstep; const char* b3 = b2 + kstep;
;             PG8_STAGE(PG8_SA(1, 1), a1 + hstepA, voffA); PG8_LDB(B0, 0, 0); PG8_LDB(B1, 0, 1); PG8_SCHED; PG8_LDA(At, 0, 0);
;             PG8_WAIT_V(8); PG8_WAIT_L(0); PG8_BAR; PG8_MMA(0, 0, At, B0); PG8_MMA(0, 1, At, B1); PG8_BAR; PG8_SCHED;
;             PG8_STAGE(PG8_SB(0, 0), b2, voffB); PG8_STAGE(PG8_SB(0, 1), b2 + hstepB, voffB); PG8_STAGE(PG8_SA(0, 0), a2, voffA); PG8_LDA(At, 0, 1);
;             PG8_WAIT_V(8); PG8_WAIT_L(0); PG8_BAR; PG8_MMA(1, 0, At, B0); PG8_MMA(1, 1, At, B1); PG8_BAR; PG8_SCHED;
.LBB0_574:
	s_add_u32 s26, s12, 0xfff80080
	s_addc_u32 s27, s13, -1
	s_cmp_eq_u32 s57, 28
	s_cselect_b32 s36, s16, s26
	v_mov_b32_e32 v128, v144
	s_cselect_b32 s37, s11, s27
	s_cselect_b32 s30, s17, s52
	s_cselect_b32 s31, s9, s56
	s_add_u32 s26, s36, 0x80
	v_add_u32_e32 v137, s23, v144
	v_xad_u32 v136, v128, 64, s23
	s_addc_u32 s27, s37, 0
	ds_read_b128 v[128:131], v137
	ds_read_b128 v[146:149], v137 offset:2048
	ds_read_b128 v[150:153], v136
	ds_read_b128 v[154:157], v136 offset:2048
	v_mov_b32_e32 v136, v144
	s_add_i32 s58, 0, 0x14000
	v_add_u32_e32 v137, s58, v144
	v_xad_u32 v136, v136, 64, s58
	ds_read_b128 v[158:161], v137
	ds_read_b128 v[162:165], v137 offset:2048
	ds_read_b128 v[166:169], v136
	ds_read_b128 v[170:173], v136 offset:2048
	v_mov_b32_e32 v136, v143
	v_add_u32_e32 v137, 0, v143
	v_xad_u32 v136, v136, 64, 0
	ds_read_b128 v[174:177], v137
	ds_read_b128 v[178:181], v137 offset:2048
	ds_read_b128 v[192:195], v136
	ds_read_b128 v[196:199], v136 offset:2048
	ds_read_b128 v[200:203], v137 offset:4096
	ds_read_b128 v[204:207], v137 offset:6144
	ds_read_b128 v[208:211], v136 offset:4096
	ds_read_b128 v[212:215], v136 offset:6144
	s_mov_b32 m0, s14
	s_nop 0
	global_load_lds_dwordx4 v138, s[12:13]
	s_mov_b32 m0, s15
	s_nop 0
	global_load_lds_dwordx4 v140, s[12:13]
	s_waitcnt vmcnt(8)
	s_waitcnt lgkmcnt(0)
	s_barrier
	s_setprio 1
	v_mfma_f32_16x16x32_bf16 v[124:127], v[128:131], v[174:177], v[124:127]
	v_mfma_f32_16x16x32_bf16 v[120:123], v[146:149], v[174:177], v[120:123]
	v_mfma_f32_16x16x32_bf16 v[108:111], v[128:131], v[178:181], v[108:111]
	v_mfma_f32_16x16x32_bf16 v[104:107], v[146:149], v[178:181], v[104:107]
	v_mfma_f32_16x16x32_bf16 v[92:95], v[128:131], v[200:203], v[92:95]
	v_mfma_f32_16x16x32_bf16 v[88:91], v[146:149], v[200:203], v[88:91]
	v_mfma_f32_16x16x32_bf16 v[76:79], v[128:131], v[204:207], v[76:79]
	v_mfma_f32_16x16x32_bf16 v[72:75], v[146:149], v[204:207], v[72:75]
	v_mfma_f32_16x16x32_bf16 v[124:127], v[150:153], v[192:195], v[124:127]
	v_mfma_f32_16x16x32_bf16 v[120:123], v[154:157], v[192:195], v[120:123]
	v_mfma_f32_16x16x32_bf16 v[108:111], v[150:153], v[196:199], v[108:111]
	v_mfma_f32_16x16x32_bf16 v[104:107], v[154:157], v[196:199], v[104:107]
	v_mfma_f32_16x16x32_bf16 v[92:95], v[150:153], v[208:211], v[92:95]
	v_mfma_f32_16x16x32_bf16 v[88:91], v[154:157], v[208:211], v[88:91]
	v_mfma_f32_16x16x32_bf16 v[76:79], v[150:153], v[212:215], v[76:79]
	v_mfma_f32_16x16x32_bf16 v[72:75], v[154:157], v[212:215], v[72:75]
	v_mfma_f32_16x16x32_bf16 v[116:119], v[158:161], v[174:177], v[116:119]
	v_mfma_f32_16x16x32_bf16 v[112:115], v[162:165], v[174:177], v[112:115]
	v_mfma_f32_16x16x32_bf16 v[100:103], v[158:161], v[178:181], v[100:103]
	v_mfma_f32_16x16x32_bf16 v[96:99], v[162:165], v[178:181], v[96:99]
	v_mfma_f32_16x16x32_bf16 v[84:87], v[158:161], v[200:203], v[84:87]
	v_mfma_f32_16x16x32_bf16 v[80:83], v[162:165], v[200:203], v[80:83]
	v_mfma_f32_16x16x32_bf16 v[68:71], v[158:161], v[204:207], v[68:71]
	v_mfma_f32_16x16x32_bf16 v[64:67], v[162:165], v[204:207], v[64:67]
	v_mfma_f32_16x16x32_bf16 v[116:119], v[166:169], v[192:195], v[116:119]
	v_mfma_f32_16x16x32_bf16 v[112:115], v[170:173], v[192:195], v[112:115]
	v_mfma_f32_16x16x32_bf16 v[100:103], v[166:169], v[196:199], v[100:103]
	v_mfma_f32_16x16x32_bf16 v[96:99], v[170:173], v[196:199], v[96:99]
	v_mfma_f32_16x16x32_bf16 v[84:87], v[166:169], v[208:211], v[84:87]
	v_mfma_f32_16x16x32_bf16 v[80:83], v[170:173], v[208:211], v[80:83]
	v_mfma_f32_16x16x32_bf16 v[68:71], v[166:169], v[212:215], v[68:71]
	v_mfma_f32_16x16x32_bf16 v[64:67], v[170:173], v[212:215], v[64:67]
	s_setprio 0
	s_barrier
	v_mov_b32_e32 v136, v143
	s_add_u32 s58, s30, 0x80000
	s_addc_u32 s59, s31, 0
	s_nop 0
	s_nop 0
	s_nop 0
	v_xad_u32 v136, v136, 64, 0
	ds_read_b128 v[174:177], v137 offset:16384
	ds_read_b128 v[178:181], v137 offset:18432
	ds_read_b128 v[192:195], v136 offset:16384
	ds_read_b128 v[196:199], v136 offset:18432
	ds_read_b128 v[200:203], v137 offset:20480
	ds_read_b128 v[204:207], v137 offset:22528
	ds_read_b128 v[208:211], v136 offset:20480
	ds_read_b128 v[212:215], v136 offset:22528
	s_mov_b32 m0, s80
	s_nop 0
	global_load_lds_dwordx4 v139, s[30:31]
	s_mov_b32 m0, s81
	s_nop 0
	global_load_lds_dwordx4 v141, s[30:31]
	s_mov_b32 m0, s29
	s_nop 0
	global_load_lds_dwordx4 v139, s[58:59]
	s_mov_b32 m0, s88
	s_nop 0
	global_load_lds_dwordx4 v141, s[58:59]
	s_mov_b32 m0, s76
	s_nop 0
	global_load_lds_dwordx4 v138, s[36:37]
	s_mov_b32 m0, s89
	s_nop 0
	global_load_lds_dwordx4 v140, s[36:37]
	s_waitcnt vmcnt(8)
	s_waitcnt lgkmcnt(0)
	s_barrier
; #define PG8_STAGE(bufoff, gbase, voff) do { _Pragma("unroll") for (int _i = 0; _i < 2; ++_i) \
;         dma16((const char*)(gbase), (voff)[_i], ldsb + (bufoff) + ldsw + _i * 8192); } while (0)
; #define PG8_LDA(dst, b, h) do { const int a1_ = opqv(aoff0) ^ 64; _Pragma("unroll") for (int m = 0; m < 4; ++m) { dst[m][0] = *(const LAS bf16x8*)(lds + PG8_SA(b, h) + aoff0 + m * 2048); dst[m][1] = *(const LAS bf16x8*)(lds + PG8_SA(b, h) + a1_ + m * 2048); } } while (0)
; #define PG8_LDB(dst, b, h) do { const int b1_ = opqv(boff0) ^ 64; _Pragma("unroll") for (int n = 0; n < 2; ++n) { dst[n][0] = *(const LAS bf16x8*)(lds + PG8_SB(b, h) + boff0 + n * 2048); dst[n][1] = *(const LAS bf16x8*)(lds + PG8_SB(b, h) + b1_ + n * 2048); } } while (0)
; #define PG8_MMA(ai, bj, At, Bt) do { __builtin_amdgcn_s_setprio(1); _Pragma("unroll") for (int m = 0; m < 4; ++m) _Pragma("unroll") for (int n = 0; n < 2; ++n) _Pragma("unroll") for (int k = 0; k < 2; ++k) \
;         acc[ai][bj][m][n] = __builtin_amdgcn_mfma_f32_16x16x32_bf16(Bt[n][k], At[m][k], acc[ai][bj][m][n], 0, 0, 0); __builtin_amdgcn_s_setprio(0); } while (0)
; #define PG8_WAIT_V(n) asm volatile("s_waitcnt vmcnt(" #n ")" ::: "memory")
; #define PG8_WAIT_L(n) asm volatile("s_waitcnt lgkmcnt(" #n ")" ::: "memory")
; #define PG8_BAR __builtin_amdgcn_s_barrier()
; #define PG8_SCHED __builtin_amdgcn_sched_barrier(0)
; template <class Epi>
; __device__ __forceinline__ void gemm_phase(LAS unsigned char* lds, const Gemm g, const StaticOrder& S, const Epi& E, int wave_) {
;     ...
;             PG8_WAIT_V(8); PG8_WAIT_L(0); PG8_BAR; PG8_MMA(1, 0, At, B0); PG8_MMA(1, 1, At, B1); PG8_BAR; PG8_SCHED;
;             PG8_STAGE(PG8_SA(0, 1), a2 + hstepA, voffA); PG8_LDB(B0, 1, 0); PG8_LDB(B1, 1, 1); PG8_SCHED; PG8_LDA(At, 1, 0);
;             PG8_WAIT_V(8); PG8_WAIT_L(0); PG8_BAR; PG8_MMA(0, 0, At, B0); PG8_MMA(0, 1, At, B1); PG8_BAR; PG8_SCHED;
	s_setprio 1
	v_mfma_f32_16x16x32_bf16 v[60:63], v[128:131], v[174:177], v[60:63]
	v_mfma_f32_16x16x32_bf16 v[56:59], v[146:149], v[174:177], v[56:59]
	v_mfma_f32_16x16x32_bf16 v[44:47], v[128:131], v[178:181], v[44:47]
	v_mfma_f32_16x16x32_bf16 v[40:43], v[146:149], v[178:181], v[40:43]
	v_mfma_f32_16x16x32_bf16 v[28:31], v[128:131], v[200:203], v[28:31]
	v_mfma_f32_16x16x32_bf16 v[24:27], v[146:149], v[200:203], v[24:27]
	v_mfma_f32_16x16x32_bf16 v[12:15], v[128:131], v[204:207], v[12:15]
	v_mfma_f32_16x16x32_bf16 v[8:11], v[146:149], v[204:207], v[8:11]
	v_mfma_f32_16x16x32_bf16 v[60:63], v[150:153], v[192:195], v[60:63]
	v_mfma_f32_16x16x32_bf16 v[56:59], v[154:157], v[192:195], v[56:59]
	v_mfma_f32_16x16x32_bf16 v[44:47], v[150:153], v[196:199], v[44:47]
	v_mfma_f32_16x16x32_bf16 v[40:43], v[154:157], v[196:199], v[40:43]
	v_mfma_f32_16x16x32_bf16 v[28:31], v[150:153], v[208:211], v[28:31]
	v_mfma_f32_16x16x32_bf16 v[24:27], v[154:157], v[208:211], v[24:27]
	v_mfma_f32_16x16x32_bf16 v[12:15], v[150:153], v[212:215], v[12:15]
	v_mfma_f32_16x16x32_bf16 v[8:11], v[154:157], v[212:215], v[8:11]
	v_mfma_f32_16x16x32_bf16 v[52:55], v[158:161], v[174:177], v[52:55]
	v_mfma_f32_16x16x32_bf16 v[48:51], v[162:165], v[174:177], v[48:51]
	v_mfma_f32_16x16x32_bf16 v[36:39], v[158:161], v[178:181], v[36:39]
	v_mfma_f32_16x16x32_bf16 v[32:35], v[162:165], v[178:181], v[32:35]
	v_mfma_f32_16x16x32_bf16 v[20:23], v[158:161], v[200:203], v[20:23]
	v_mfma_f32_16x16x32_bf16 v[16:19], v[162:165], v[200:203], v[16:19]
	v_mfma_f32_16x16x32_bf16 v[4:7], v[158:161], v[204:207], v[4:7]
	v_mfma_f32_16x16x32_bf16 v[0:3], v[162:165], v[204:207], v[0:3]
	v_mfma_f32_16x16x32_bf16 v[52:55], v[166:169], v[192:195], v[52:55]
	v_mfma_f32_16x16x32_bf16 v[48:51], v[170:173], v[192:195], v[48:51]
	v_mfma_f32_16x16x32_bf16 v[36:39], v[166:169], v[196:199], v[36:39]
	v_mfma_f32_16x16x32_bf16 v[32:35], v[170:173], v[196:199], v[32:35]
	v_mfma_f32_16x16x32_bf16 v[20:23], v[166:169], v[208:211], v[20:23]
	v_mfma_f32_16x16x32_bf16 v[16:19], v[170:173], v[208:211], v[16:19]
	v_mfma_f32_16x16x32_bf16 v[4:7], v[166:169], v[212:215], v[4:7]
	v_mfma_f32_16x16x32_bf16 v[0:3], v[170:173], v[212:215], v[0:3]
	s_setprio 0
	s_barrier
	s_add_u32 s36, s36, 0x80000
	s_addc_u32 s37, s37, 0
	s_mov_b32 m0, s1
	s_nop 0
	global_load_lds_dwordx4 v138, s[36:37]
	v_mov_b32_e32 v128, v144
	s_mov_b32 m0, s69
	s_nop 0
	global_load_lds_dwordx4 v140, s[36:37]
	v_add_u32_e32 v146, s34, v144
	v_xad_u32 v136, v128, 64, s34
	ds_read_b128 v[128:131], v146
	ds_read_b128 v[146:149], v146 offset:2048
	ds_read_b128 v[150:153], v136
	ds_read_b128 v[154:157], v136 offset:2048
	v_mov_b32_e32 v136, v144
	s_add_i32 s36, 0, 0x1c000
	v_add_u32_e32 v162, s36, v144
	v_xad_u32 v136, v136, 64, s36
	ds_read_b128 v[158:161], v162
	ds_read_b128 v[162:165], v162 offset:2048
	ds_read_b128 v[166:169], v136
	ds_read_b128 v[170:173], v136 offset:2048
	v_mov_b32_e32 v136, v143
	s_nop 0
	v_xad_u32 v136, v136, 64, 0
	ds_read_b128 v[174:177], v137 offset:32768
	ds_read_b128 v[178:181], v137 offset:34816
	ds_read_b128 v[192:195], v136 offset:32768
	ds_read_b128 v[196:199], v136 offset:34816
	ds_read_b128 v[200:203], v137 offset:36864
	ds_read_b128 v[204:207], v137 offset:38912
	ds_read_b128 v[208:211], v136 offset:36864
	ds_read_b128 v[212:215], v136 offset:38912
	s_waitcnt vmcnt(8)
	s_waitcnt lgkmcnt(0)
	s_barrier
	s_setprio 1
	v_mfma_f32_16x16x32_bf16 v[124:127], v[128:131], v[174:177], v[124:127]
	v_mfma_f32_16x16x32_bf16 v[120:123], v[146:149], v[174:177], v[120:123]
	v_mfma_f32_16x16x32_bf16 v[108:111], v[128:131], v[178:181], v[108:111]
	v_mfma_f32_16x16x32_bf16 v[104:107], v[146:149], v[178:181], v[104:107]
	v_mfma_f32_16x16x32_bf16 v[92:95], v[128:131], v[200:203], v[92:95]
	v_mfma_f32_16x16x32_bf16 v[88:91], v[146:149], v[200:203], v[88:91]
	v_mfma_f32_16x16x32_bf16 v[76:79], v[128:131], v[204:207], v[76:79]
	v_mfma_f32_16x16x32_bf16 v[72:75], v[146:149], v[204:207], v[72:75]
	v_mfma_f32_16x16x32_bf16 v[124:127], v[150:153], v[192:195], v[124:127]
	v_mfma_f32_16x16x32_bf16 v[120:123], v[154:157], v[192:195], v[120:123]
	v_mfma_f32_16x16x32_bf16 v[108:111], v[150:153], v[196:199], v[108:111]
	v_mfma_f32_16x16x32_bf16 v[104:107], v[154:157], v[196:199], v[104:107]
	v_mfma_f32_16x16x32_bf16 v[92:95], v[150:153], v[208:211], v[92:95]
	v_mfma_f32_16x16x32_bf16 v[88:91], v[154:157], v[208:211], v[88:91]
	v_mfma_f32_16x16x32_bf16 v[76:79], v[150:153], v[212:215], v[76:79]
	v_mfma_f32_16x16x32_bf16 v[72:75], v[154:157], v[212:215], v[72:75]
	v_mfma_f32_16x16x32_bf16 v[116:119], v[158:161], v[174:177], v[116:119]
	s_add_u32 s36, s30, 0x80
	s_addc_u32 s37, s31, 0
	v_mfma_f32_16x16x32_bf16 v[112:115], v[162:165], v[174:177], v[112:115]
	v_mfma_f32_16x16x32_bf16 v[100:103], v[158:161], v[178:181], v[100:103]
	v_mfma_f32_16x16x32_bf16 v[96:99], v[162:165], v[178:181], v[96:99]
	v_mfma_f32_16x16x32_bf16 v[84:87], v[158:161], v[200:203], v[84:87]
	v_mfma_f32_16x16x32_bf16 v[80:83], v[162:165], v[200:203], v[80:83]
	v_mfma_f32_16x16x32_bf16 v[68:71], v[158:161], v[204:207], v[68:71]
	v_mfma_f32_16x16x32_bf16 v[64:67], v[162:165], v[204:207], v[64:67]
	v_mfma_f32_16x16x32_bf16 v[116:119], v[166:169], v[192:195], v[116:119]
	v_mfma_f32_16x16x32_bf16 v[112:115], v[170:173], v[192:195], v[112:115]
	v_mfma_f32_16x16x32_bf16 v[100:103], v[166:169], v[196:199], v[100:103]
	v_mfma_f32_16x16x32_bf16 v[96:99], v[170:173], v[196:199], v[96:99]
	v_mfma_f32_16x16x32_bf16 v[84:87], v[166:169], v[208:211], v[84:87]
	v_mfma_f32_16x16x32_bf16 v[80:83], v[170:173], v[208:211], v[80:83]
	v_mfma_f32_16x16x32_bf16 v[68:71], v[166:169], v[212:215], v[68:71]
	v_mfma_f32_16x16x32_bf16 v[64:67], v[170:173], v[212:215], v[64:67]
	s_setprio 0
	s_barrier
; #define PG8_STAGE(bufoff, gbase, voff) do { _Pragma("unroll") for (int _i = 0; _i < 2; ++_i) \
;         dma16((const char*)(gbase), (voff)[_i], ldsb + (bufoff) + ldsw + _i * 8192); } while (0)
; #define PG8_LDA(dst, b, h) do { const int a1_ = opqv(aoff0) ^ 64; _Pragma("unroll") for (int m = 0; m < 4; ++m) { dst[m][0] = *(const LAS bf16x8*)(lds + PG8_SA(b, h) + aoff0 + m * 2048); dst[m][1] = *(const LAS bf16x8*)(lds + PG8_SA(b, h) + a1_ + m * 2048); } } while (0)
; #define PG8_MMA(ai, bj, At, Bt) do { __builtin_amdgcn_s_setprio(1); _Pragma("unroll") for (int m = 0; m < 4; ++m) _Pragma("unroll") for (int n = 0; n < 2; ++n) _Pragma("unroll") for (int k = 0; k < 2; ++k) \
;         acc[ai][bj][m][n] = __builtin_amdgcn_mfma_f32_16x16x32_bf16(Bt[n][k], At[m][k], acc[ai][bj][m][n], 0, 0, 0); __builtin_amdgcn_s_setprio(0); } while (0)
; #define PG8_WAIT_V(n) asm volatile("s_waitcnt vmcnt(" #n ")" ::: "memory")
; #define PG8_WAIT_L(n) asm volatile("s_waitcnt lgkmcnt(" #n ")" ::: "memory")
; #define PG8_BAR __builtin_amdgcn_s_barrier()
; #define PG8_SCHED __builtin_amdgcn_sched_barrier(0)
; template <class Epi>
; __device__ __forceinline__ void gemm_phase(LAS unsigned char* lds, const Gemm g, const StaticOrder& S, const Epi& E, int wave_) {
;     ...
;             PG8_STAGE(PG8_SB(1, 0), b3, voffB); PG8_STAGE(PG8_SB(1, 1), b3 + hstepB, voffB); PG8_STAGE(PG8_SA(1, 0), a3, voffA); PG8_LDA(At, 1, 1);
;             PG8_WAIT_V(8); PG8_WAIT_L(0); PG8_BAR; PG8_MMA(1, 0, At, B0); PG8_MMA(1, 1, At, B1); PG8_BAR; PG8_SCHED;
;         }
	s_add_u32 s30, s30, 0x80080
	s_addc_u32 s31, s31, 0
	v_mov_b32_e32 v136, v143
	s_nop 0
	s_nop 0
	v_xad_u32 v136, v136, 64, 0
	ds_read_b128 v[174:177], v137 offset:49152
	ds_read_b128 v[178:181], v137 offset:51200
	ds_read_b128 v[192:195], v136 offset:49152
	ds_read_b128 v[196:199], v136 offset:51200
	ds_read_b128 v[200:203], v137 offset:53248
	ds_read_b128 v[204:207], v137 offset:55296
	ds_read_b128 v[208:211], v136 offset:53248
	ds_read_b128 v[212:215], v136 offset:55296
	s_mov_b32 m0, s35
	s_nop 0
	global_load_lds_dwordx4 v139, s[36:37]
	s_mov_b32 m0, s33
	s_nop 0
	global_load_lds_dwordx4 v141, s[36:37]
	s_mov_b32 m0, s77
	s_nop 0
	global_load_lds_dwordx4 v139, s[30:31]
	s_mov_b32 m0, s3
	s_nop 0
	global_load_lds_dwordx4 v141, s[30:31]
	s_mov_b32 m0, s22
	s_nop 0
	global_load_lds_dwordx4 v138, s[26:27]
	s_mov_b32 m0, s2
	s_nop 0
	global_load_lds_dwordx4 v140, s[26:27]
	s_waitcnt vmcnt(8)
	s_waitcnt lgkmcnt(0)
	s_barrier
	s_setprio 1
	v_mfma_f32_16x16x32_bf16 v[60:63], v[128:131], v[174:177], v[60:63]
	v_mfma_f32_16x16x32_bf16 v[56:59], v[146:149], v[174:177], v[56:59]
	v_mfma_f32_16x16x32_bf16 v[44:47], v[128:131], v[178:181], v[44:47]
	v_mfma_f32_16x16x32_bf16 v[40:43], v[146:149], v[178:181], v[40:43]
	v_mfma_f32_16x16x32_bf16 v[28:31], v[128:131], v[200:203], v[28:31]
	v_mfma_f32_16x16x32_bf16 v[24:27], v[146:149], v[200:203], v[24:27]
	v_mfma_f32_16x16x32_bf16 v[12:15], v[128:131], v[204:207], v[12:15]
	v_mfma_f32_16x16x32_bf16 v[8:11], v[146:149], v[204:207], v[8:11]
	v_mfma_f32_16x16x32_bf16 v[60:63], v[150:153], v[192:195], v[60:63]
	v_mfma_f32_16x16x32_bf16 v[56:59], v[154:157], v[192:195], v[56:59]
	v_mfma_f32_16x16x32_bf16 v[44:47], v[150:153], v[196:199], v[44:47]
	v_mfma_f32_16x16x32_bf16 v[40:43], v[154:157], v[196:199], v[40:43]
	v_mfma_f32_16x16x32_bf16 v[28:31], v[150:153], v[208:211], v[28:31]
	v_mfma_f32_16x16x32_bf16 v[24:27], v[154:157], v[208:211], v[24:27]
	v_mfma_f32_16x16x32_bf16 v[12:15], v[150:153], v[212:215], v[12:15]
	v_mfma_f32_16x16x32_bf16 v[8:11], v[154:157], v[212:215], v[8:11]
	v_mfma_f32_16x16x32_bf16 v[52:55], v[158:161], v[174:177], v[52:55]
	v_mfma_f32_16x16x32_bf16 v[48:51], v[162:165], v[174:177], v[48:51]
	v_mfma_f32_16x16x32_bf16 v[36:39], v[158:161], v[178:181], v[36:39]
	v_mfma_f32_16x16x32_bf16 v[32:35], v[162:165], v[178:181], v[32:35]
	v_mfma_f32_16x16x32_bf16 v[20:23], v[158:161], v[200:203], v[20:23]
	v_mfma_f32_16x16x32_bf16 v[16:19], v[162:165], v[200:203], v[16:19]
	v_mfma_f32_16x16x32_bf16 v[4:7], v[158:161], v[204:207], v[4:7]
	v_mfma_f32_16x16x32_bf16 v[0:3], v[162:165], v[204:207], v[0:3]
	v_mfma_f32_16x16x32_bf16 v[52:55], v[166:169], v[192:195], v[52:55]
	v_mfma_f32_16x16x32_bf16 v[48:51], v[170:173], v[192:195], v[48:51]
	v_mfma_f32_16x16x32_bf16 v[36:39], v[166:169], v[196:199], v[36:39]
	v_mfma_f32_16x16x32_bf16 v[32:35], v[170:173], v[196:199], v[32:35]
	v_mfma_f32_16x16x32_bf16 v[20:23], v[166:169], v[208:211], v[20:23]
	v_mfma_f32_16x16x32_bf16 v[16:19], v[170:173], v[208:211], v[16:19]
	v_mfma_f32_16x16x32_bf16 v[4:7], v[166:169], v[212:215], v[4:7]
	v_mfma_f32_16x16x32_bf16 v[0:3], v[170:173], v[212:215], v[0:3]
	s_setprio 0
	s_barrier
	s_add_i32 s57, s57, 2
	s_add_u32 s52, s52, 0x100
	s_addc_u32 s56, s56, 0
	s_add_u32 s12, s12, 0x100
	s_addc_u32 s13, s13, 0
	s_cmp_gt_u32 s57, 29
	s_cbranch_scc0 .LBB0_574
	v_readlane_b32 s12, v253, 13
	v_readlane_b32 s13, v253, 14
	s_and_b64 vcc, exec, s[12:13]
	s_cbranch_vccz .LBB0_577
	s_barrier

; #define PG8_STAGE(bufoff, gbase, voff) do { _Pragma("unroll") for (int _i = 0; _i < 2; ++_i) \
;         dma16((const char*)(gbase), (voff)[_i], ldsb + (bufoff) + ldsw + _i * 8192); } while (0)
; #define PG8_LDA(dst, b, h) do { const int a1_ = opqv(aoff0) ^ 64; _Pragma("unroll") for (int m = 0; m < 4; ++m) { dst[m][0] = *(const LAS bf16x8*)(lds + PG8_SA(b, h) + aoff0 + m * 2048); dst[m][1] = *(const LAS bf16x8*)(lds + PG8_SA(b, h) + a1_ + m * 2048); } } while (0)
; #define PG8_LDB(dst, b, h) do { const int b1_ = opqv(boff0) ^ 64; _Pragma("unroll") for (int n = 0; n < 2; ++n) { dst[n][0] = *(const LAS bf16x8*)(lds + PG8_SB(b, h) + boff0 + n * 2048); dst[n][1] = *(const LAS bf16x8*)(lds + PG8_SB(b, h) + b1_ + n * 2048); } } while (0)
; #define PG8_MMA(ai, bj, At, Bt) do { __builtin_amdgcn_s_setprio(1); _Pragma("unroll") for (int m = 0; m < 4; ++m) _Pragma("unroll") for (int n = 0; n < 2; ++n) _Pragma("unroll") for (int k = 0; k < 2; ++k) \
;         acc[ai][bj][m][n] = __builtin_amdgcn_mfma_f32_16x16x32_bf16(Bt[n][k], At[m][k], acc[ai][bj][m][n], 0, 0, 0); __builtin_amdgcn_s_setprio(0); } while (0)
; #define PG8_WAIT_V(n) asm volatile("s_waitcnt vmcnt(" #n ")" ::: "memory")
; #define PG8_WAIT_L(n) asm volatile("s_waitcnt lgkmcnt(" #n ")" ::: "memory")
; #define PG8_BAR __builtin_amdgcn_s_barrier()
; #define PG8_SCHED __builtin_amdgcn_sched_barrier(0)
; template <class Epi>
; __device__ __forceinline__ void gemm_phase(LAS unsigned char* lds, const Gemm g, const StaticOrder& S, const Epi& E, int wave_) {
;     ...
;             const char* a2 = last ? nA : cA + (size_t)(t + 2) * kstep; const char* b2 = last ? nB : cB + (size_t)(t + 2) * kstep;
;             const char* a3 = a2 + kstep; const char* b3 = b2 + kstep;
;             PG8_STAGE(PG8_SA(1, 1), a1 + hstepA, voffA); PG8_LDB(B0, 0, 0); PG8_LDB(B1, 0, 1); PG8_SCHED; PG8_LDA(At, 0, 0);
;             PG8_WAIT_V(8); PG8_WAIT_L(0); PG8_BAR; PG8_MMA(0, 0, At, B0); PG8_MMA(0, 1, At, B1); PG8_BAR; PG8_SCHED;
;             PG8_STAGE(PG8_SB(0, 0), b2, voffB); PG8_STAGE(PG8_SB(0, 1), b2 + hstepB, voffB); PG8_STAGE(PG8_SA(0, 0), a2, voffA); PG8_LDA(At, 0, 1);
;             PG8_WAIT_V(8); PG8_WAIT_L(0); PG8_BAR; PG8_MMA(1, 0, At, B0); PG8_MMA(1, 1, At, B1); PG8_BAR; PG8_SCHED;
.LBB0_744:
	s_add_u32 s30, s12, 0xfffc0080
	s_addc_u32 s31, s13, -1
	s_cmp_eq_u32 s57, 4
	s_cselect_b32 s42, s17, s30
	s_cselect_b32 s43, s16, s31
	s_cselect_b32 s36, s19, s52
	s_cselect_b32 s37, s11, s56
	s_add_u32 s30, s42, 0x80
	v_mov_b32_e32 v128, v180
	s_addc_u32 s31, s43, 0
	v_add_u32_e32 v132, s23, v180
	v_xad_u32 v144, v128, 64, s23
	v_mov_b32_e32 v148, v180
	s_add_i32 s58, 0, 0x14000
	ds_read_b128 v[128:131], v132
	ds_read_b128 v[132:135], v132 offset:2048
	ds_read_b128 v[140:143], v144
	ds_read_b128 v[144:147], v144 offset:2048
	v_add_u32_e32 v152, s58, v180
	v_xad_u32 v160, v148, 64, s58
	ds_read_b128 v[148:151], v152
	ds_read_b128 v[152:155], v152 offset:2048
	ds_read_b128 v[156:159], v160
	ds_read_b128 v[160:163], v160 offset:2048
	v_mov_b32_e32 v164, v179
	v_add_u32_e32 v182, 0, v179
	v_xad_u32 v172, v164, 64, 0
	ds_read_b128 v[164:167], v182
	ds_read_b128 v[168:171], v182 offset:2048
	ds_read_b128 v[192:195], v172
	ds_read_b128 v[196:199], v172 offset:2048
	ds_read_b128 v[200:203], v182 offset:4096
	ds_read_b128 v[204:207], v182 offset:6144
	ds_read_b128 v[208:211], v172 offset:4096
	ds_read_b128 v[212:215], v172 offset:6144
	s_mov_b32 m0, s14
	s_nop 0
	global_load_lds_dwordx4 v137, s[12:13]
	s_mov_b32 m0, s15
	s_nop 0
	global_load_lds_dwordx4 v176, s[12:13]
	s_waitcnt vmcnt(8)
	s_waitcnt lgkmcnt(0)
	s_barrier
	s_setprio 1
	v_mfma_f32_16x16x32_bf16 v[124:127], v[128:131], v[164:167], v[124:127]
	v_mfma_f32_16x16x32_bf16 v[120:123], v[132:135], v[164:167], v[120:123]
	v_mfma_f32_16x16x32_bf16 v[108:111], v[128:131], v[168:171], v[108:111]
	v_mfma_f32_16x16x32_bf16 v[104:107], v[132:135], v[168:171], v[104:107]
	v_mfma_f32_16x16x32_bf16 v[92:95], v[128:131], v[200:203], v[92:95]
	v_mfma_f32_16x16x32_bf16 v[88:91], v[132:135], v[200:203], v[88:91]
	v_mfma_f32_16x16x32_bf16 v[76:79], v[128:131], v[204:207], v[76:79]
	v_mfma_f32_16x16x32_bf16 v[72:75], v[132:135], v[204:207], v[72:75]
	v_mfma_f32_16x16x32_bf16 v[124:127], v[140:143], v[192:195], v[124:127]
	v_mfma_f32_16x16x32_bf16 v[120:123], v[144:147], v[192:195], v[120:123]
	v_mfma_f32_16x16x32_bf16 v[108:111], v[140:143], v[196:199], v[108:111]
	v_mfma_f32_16x16x32_bf16 v[104:107], v[144:147], v[196:199], v[104:107]
	v_mfma_f32_16x16x32_bf16 v[92:95], v[140:143], v[208:211], v[92:95]
	v_mfma_f32_16x16x32_bf16 v[88:91], v[144:147], v[208:211], v[88:91]
	v_mfma_f32_16x16x32_bf16 v[76:79], v[140:143], v[212:215], v[76:79]
	v_mfma_f32_16x16x32_bf16 v[72:75], v[144:147], v[212:215], v[72:75]
	v_mfma_f32_16x16x32_bf16 v[116:119], v[148:151], v[164:167], v[116:119]
	v_mfma_f32_16x16x32_bf16 v[112:115], v[152:155], v[164:167], v[112:115]
	v_mfma_f32_16x16x32_bf16 v[100:103], v[148:151], v[168:171], v[100:103]
	v_mfma_f32_16x16x32_bf16 v[96:99], v[152:155], v[168:171], v[96:99]
	v_mfma_f32_16x16x32_bf16 v[84:87], v[148:151], v[200:203], v[84:87]
	v_mfma_f32_16x16x32_bf16 v[80:83], v[152:155], v[200:203], v[80:83]
	v_mfma_f32_16x16x32_bf16 v[68:71], v[148:151], v[204:207], v[68:71]
	v_mfma_f32_16x16x32_bf16 v[64:67], v[152:155], v[204:207], v[64:67]
	v_mfma_f32_16x16x32_bf16 v[116:119], v[156:159], v[192:195], v[116:119]
	v_mfma_f32_16x16x32_bf16 v[112:115], v[160:163], v[192:195], v[112:115]
	v_mfma_f32_16x16x32_bf16 v[100:103], v[156:159], v[196:199], v[100:103]
	v_mfma_f32_16x16x32_bf16 v[96:99], v[160:163], v[196:199], v[96:99]
	v_mfma_f32_16x16x32_bf16 v[84:87], v[156:159], v[208:211], v[84:87]
	v_mfma_f32_16x16x32_bf16 v[80:83], v[160:163], v[208:211], v[80:83]
	v_mfma_f32_16x16x32_bf16 v[68:71], v[156:159], v[212:215], v[68:71]
	v_mfma_f32_16x16x32_bf16 v[64:67], v[160:163], v[212:215], v[64:67]
	s_setprio 0
	s_barrier
	v_mov_b32_e32 v164, v179
	s_add_u32 s58, s36, 0x20000
	s_addc_u32 s59, s37, 0
	s_nop 0
	s_nop 0
	s_nop 0
	v_xad_u32 v172, v164, 64, 0
	ds_read_b128 v[164:167], v182 offset:16384
	ds_read_b128 v[168:171], v182 offset:18432
	ds_read_b128 v[192:195], v172 offset:16384
	ds_read_b128 v[196:199], v172 offset:18432
	ds_read_b128 v[200:203], v182 offset:20480
	ds_read_b128 v[204:207], v182 offset:22528
	ds_read_b128 v[208:211], v172 offset:20480
	ds_read_b128 v[212:215], v172 offset:22528
	s_mov_b32 m0, s80
	s_nop 0
	global_load_lds_dwordx4 v175, s[36:37]
	s_mov_b32 m0, s81
	s_nop 0
	global_load_lds_dwordx4 v177, s[36:37]
	s_mov_b32 m0, s29
	s_nop 0
	global_load_lds_dwordx4 v175, s[58:59]
	s_mov_b32 m0, s88
	s_nop 0
	global_load_lds_dwordx4 v177, s[58:59]
	s_mov_b32 m0, s76
	s_nop 0
	global_load_lds_dwordx4 v137, s[42:43]
	s_mov_b32 m0, s89
	s_nop 0
	global_load_lds_dwordx4 v176, s[42:43]
	s_waitcnt vmcnt(8)
	s_waitcnt lgkmcnt(0)
	s_barrier
; #define PG8_STAGE(bufoff, gbase, voff) do { _Pragma("unroll") for (int _i = 0; _i < 2; ++_i) \
;         dma16((const char*)(gbase), (voff)[_i], ldsb + (bufoff) + ldsw + _i * 8192); } while (0)
; #define PG8_LDA(dst, b, h) do { const int a1_ = opqv(aoff0) ^ 64; _Pragma("unroll") for (int m = 0; m < 4; ++m) { dst[m][0] = *(const LAS bf16x8*)(lds + PG8_SA(b, h) + aoff0 + m * 2048); dst[m][1] = *(const LAS bf16x8*)(lds + PG8_SA(b, h) + a1_ + m * 2048); } } while (0)
; #define PG8_LDB(dst, b, h) do { const int b1_ = opqv(boff0) ^ 64; _Pragma("unroll") for (int n = 0; n < 2; ++n) { dst[n][0] = *(const LAS bf16x8*)(lds + PG8_SB(b, h) + boff0 + n * 2048); dst[n][1] = *(const LAS bf16x8*)(lds + PG8_SB(b, h) + b1_ + n * 2048); } } while (0)
; #define PG8_MMA(ai, bj, At, Bt) do { __builtin_amdgcn_s_setprio(1); _Pragma("unroll") for (int m = 0; m < 4; ++m) _Pragma("unroll") for (int n = 0; n < 2; ++n) _Pragma("unroll") for (int k = 0; k < 2; ++k) \
;         acc[ai][bj][m][n] = __builtin_amdgcn_mfma_f32_16x16x32_bf16(Bt[n][k], At[m][k], acc[ai][bj][m][n], 0, 0, 0); __builtin_amdgcn_s_setprio(0); } while (0)
; #define PG8_WAIT_V(n) asm volatile("s_waitcnt vmcnt(" #n ")" ::: "memory")
; #define PG8_WAIT_L(n) asm volatile("s_waitcnt lgkmcnt(" #n ")" ::: "memory")
; #define PG8_BAR __builtin_amdgcn_s_barrier()
; #define PG8_SCHED __builtin_amdgcn_sched_barrier(0)
; template <class Epi>
; __device__ __forceinline__ void gemm_phase(LAS unsigned char* lds, const Gemm g, const StaticOrder& S, const Epi& E, int wave_) {
;     ...
;             PG8_WAIT_V(8); PG8_WAIT_L(0); PG8_BAR; PG8_MMA(1, 0, At, B0); PG8_MMA(1, 1, At, B1); PG8_BAR; PG8_SCHED;
;             PG8_STAGE(PG8_SA(0, 1), a2 + hstepA, voffA); PG8_LDB(B0, 1, 0); PG8_LDB(B1, 1, 1); PG8_SCHED; PG8_LDA(At, 1, 0);
;             PG8_WAIT_V(8); PG8_WAIT_L(0); PG8_BAR; PG8_MMA(0, 0, At, B0); PG8_MMA(0, 1, At, B1); PG8_BAR; PG8_SCHED;
	s_setprio 1
	v_mfma_f32_16x16x32_bf16 v[60:63], v[128:131], v[164:167], v[60:63]
	v_mfma_f32_16x16x32_bf16 v[56:59], v[132:135], v[164:167], v[56:59]
	v_mfma_f32_16x16x32_bf16 v[44:47], v[128:131], v[168:171], v[44:47]
	v_mfma_f32_16x16x32_bf16 v[40:43], v[132:135], v[168:171], v[40:43]
	v_mfma_f32_16x16x32_bf16 v[28:31], v[128:131], v[200:203], v[28:31]
	v_mfma_f32_16x16x32_bf16 v[24:27], v[132:135], v[200:203], v[24:27]
	v_mfma_f32_16x16x32_bf16 v[12:15], v[128:131], v[204:207], v[12:15]
	v_mfma_f32_16x16x32_bf16 v[8:11], v[132:135], v[204:207], v[8:11]
	v_mfma_f32_16x16x32_bf16 v[60:63], v[140:143], v[192:195], v[60:63]
	v_mfma_f32_16x16x32_bf16 v[56:59], v[144:147], v[192:195], v[56:59]
	v_mfma_f32_16x16x32_bf16 v[44:47], v[140:143], v[196:199], v[44:47]
	v_mfma_f32_16x16x32_bf16 v[40:43], v[144:147], v[196:199], v[40:43]
	v_mfma_f32_16x16x32_bf16 v[28:31], v[140:143], v[208:211], v[28:31]
	v_mfma_f32_16x16x32_bf16 v[24:27], v[144:147], v[208:211], v[24:27]
	v_mfma_f32_16x16x32_bf16 v[12:15], v[140:143], v[212:215], v[12:15]
	v_mfma_f32_16x16x32_bf16 v[8:11], v[144:147], v[212:215], v[8:11]
	v_mfma_f32_16x16x32_bf16 v[52:55], v[148:151], v[164:167], v[52:55]
	v_mfma_f32_16x16x32_bf16 v[48:51], v[152:155], v[164:167], v[48:51]
	v_mfma_f32_16x16x32_bf16 v[36:39], v[148:151], v[168:171], v[36:39]
	v_mfma_f32_16x16x32_bf16 v[32:35], v[152:155], v[168:171], v[32:35]
	v_mfma_f32_16x16x32_bf16 v[20:23], v[148:151], v[200:203], v[20:23]
	v_mfma_f32_16x16x32_bf16 v[16:19], v[152:155], v[200:203], v[16:19]
	v_mfma_f32_16x16x32_bf16 v[4:7], v[148:151], v[204:207], v[4:7]
	v_mfma_f32_16x16x32_bf16 v[0:3], v[152:155], v[204:207], v[0:3]
	v_mfma_f32_16x16x32_bf16 v[52:55], v[156:159], v[192:195], v[52:55]
	v_mfma_f32_16x16x32_bf16 v[48:51], v[160:163], v[192:195], v[48:51]
	v_mfma_f32_16x16x32_bf16 v[36:39], v[156:159], v[196:199], v[36:39]
	v_mfma_f32_16x16x32_bf16 v[32:35], v[160:163], v[196:199], v[32:35]
	v_mfma_f32_16x16x32_bf16 v[20:23], v[156:159], v[208:211], v[20:23]
	v_mfma_f32_16x16x32_bf16 v[16:19], v[160:163], v[208:211], v[16:19]
	v_mfma_f32_16x16x32_bf16 v[4:7], v[156:159], v[212:215], v[4:7]
	v_mfma_f32_16x16x32_bf16 v[0:3], v[160:163], v[212:215], v[0:3]
	s_setprio 0
	s_barrier
	s_add_u32 s42, s42, 0x40000
	s_addc_u32 s43, s43, 0
	s_mov_b32 m0, s1
	s_nop 0
	global_load_lds_dwordx4 v137, s[42:43]
	v_mov_b32_e32 v128, v180
	s_mov_b32 m0, s69
	s_nop 0
	global_load_lds_dwordx4 v176, s[42:43]
	v_add_u32_e32 v132, s34, v180
	v_xad_u32 v144, v128, 64, s34
	v_mov_b32_e32 v148, v180
	s_add_i32 s42, 0, 0x1c000
	ds_read_b128 v[128:131], v132
	ds_read_b128 v[132:135], v132 offset:2048
	ds_read_b128 v[140:143], v144
	ds_read_b128 v[144:147], v144 offset:2048
	v_add_u32_e32 v152, s42, v180
	v_xad_u32 v160, v148, 64, s42
	ds_read_b128 v[148:151], v152
	ds_read_b128 v[152:155], v152 offset:2048
	ds_read_b128 v[156:159], v160
	ds_read_b128 v[160:163], v160 offset:2048
	v_mov_b32_e32 v164, v179
	s_nop 0
	v_xad_u32 v172, v164, 64, 0
	ds_read_b128 v[164:167], v182 offset:32768
	ds_read_b128 v[168:171], v182 offset:34816
	ds_read_b128 v[192:195], v172 offset:32768
	ds_read_b128 v[196:199], v172 offset:34816
	ds_read_b128 v[200:203], v182 offset:36864
	ds_read_b128 v[204:207], v182 offset:38912
	ds_read_b128 v[208:211], v172 offset:36864
	ds_read_b128 v[212:215], v172 offset:38912
	s_waitcnt vmcnt(8)
	s_waitcnt lgkmcnt(0)
	s_barrier
	s_setprio 1
	v_mfma_f32_16x16x32_bf16 v[124:127], v[128:131], v[164:167], v[124:127]
	v_mfma_f32_16x16x32_bf16 v[120:123], v[132:135], v[164:167], v[120:123]
	v_mfma_f32_16x16x32_bf16 v[108:111], v[128:131], v[168:171], v[108:111]
	v_mfma_f32_16x16x32_bf16 v[104:107], v[132:135], v[168:171], v[104:107]
	v_mfma_f32_16x16x32_bf16 v[92:95], v[128:131], v[200:203], v[92:95]
	v_mfma_f32_16x16x32_bf16 v[88:91], v[132:135], v[200:203], v[88:91]
	v_mfma_f32_16x16x32_bf16 v[76:79], v[128:131], v[204:207], v[76:79]
	v_mfma_f32_16x16x32_bf16 v[72:75], v[132:135], v[204:207], v[72:75]
	v_mfma_f32_16x16x32_bf16 v[124:127], v[140:143], v[192:195], v[124:127]
	v_mfma_f32_16x16x32_bf16 v[120:123], v[144:147], v[192:195], v[120:123]
	v_mfma_f32_16x16x32_bf16 v[108:111], v[140:143], v[196:199], v[108:111]
	v_mfma_f32_16x16x32_bf16 v[104:107], v[144:147], v[196:199], v[104:107]
	v_mfma_f32_16x16x32_bf16 v[92:95], v[140:143], v[208:211], v[92:95]
	v_mfma_f32_16x16x32_bf16 v[88:91], v[144:147], v[208:211], v[88:91]
	v_mfma_f32_16x16x32_bf16 v[76:79], v[140:143], v[212:215], v[76:79]
	v_mfma_f32_16x16x32_bf16 v[72:75], v[144:147], v[212:215], v[72:75]
	v_mfma_f32_16x16x32_bf16 v[116:119], v[148:151], v[164:167], v[116:119]
	s_add_u32 s42, s36, 0x80
	s_addc_u32 s43, s37, 0
	v_mfma_f32_16x16x32_bf16 v[112:115], v[152:155], v[164:167], v[112:115]
	v_mfma_f32_16x16x32_bf16 v[100:103], v[148:151], v[168:171], v[100:103]
	v_mfma_f32_16x16x32_bf16 v[96:99], v[152:155], v[168:171], v[96:99]
	v_mfma_f32_16x16x32_bf16 v[84:87], v[148:151], v[200:203], v[84:87]
	v_mfma_f32_16x16x32_bf16 v[80:83], v[152:155], v[200:203], v[80:83]
	v_mfma_f32_16x16x32_bf16 v[68:71], v[148:151], v[204:207], v[68:71]
	v_mfma_f32_16x16x32_bf16 v[64:67], v[152:155], v[204:207], v[64:67]
	v_mfma_f32_16x16x32_bf16 v[116:119], v[156:159], v[192:195], v[116:119]
	v_mfma_f32_16x16x32_bf16 v[112:115], v[160:163], v[192:195], v[112:115]
	v_mfma_f32_16x16x32_bf16 v[100:103], v[156:159], v[196:199], v[100:103]
	v_mfma_f32_16x16x32_bf16 v[96:99], v[160:163], v[196:199], v[96:99]
	v_mfma_f32_16x16x32_bf16 v[84:87], v[156:159], v[208:211], v[84:87]
	v_mfma_f32_16x16x32_bf16 v[80:83], v[160:163], v[208:211], v[80:83]
	v_mfma_f32_16x16x32_bf16 v[68:71], v[156:159], v[212:215], v[68:71]
	v_mfma_f32_16x16x32_bf16 v[64:67], v[160:163], v[212:215], v[64:67]
	s_setprio 0
	s_barrier
; #define PG8_STAGE(bufoff, gbase, voff) do { _Pragma("unroll") for (int _i = 0; _i < 2; ++_i) \
;         dma16((const char*)(gbase), (voff)[_i], ldsb + (bufoff) + ldsw + _i * 8192); } while (0)
; #define PG8_LDA(dst, b, h) do { const int a1_ = opqv(aoff0) ^ 64; _Pragma("unroll") for (int m = 0; m < 4; ++m) { dst[m][0] = *(const LAS bf16x8*)(lds + PG8_SA(b, h) + aoff0 + m * 2048); dst[m][1] = *(const LAS bf16x8*)(lds + PG8_SA(b, h) + a1_ + m * 2048); } } while (0)
; #define PG8_MMA(ai, bj, At, Bt) do { __builtin_amdgcn_s_setprio(1); _Pragma("unroll") for (int m = 0; m < 4; ++m) _Pragma("unroll") for (int n = 0; n < 2; ++n) _Pragma("unroll") for (int k = 0; k < 2; ++k) \
;         acc[ai][bj][m][n] = __builtin_amdgcn_mfma_f32_16x16x32_bf16(Bt[n][k], At[m][k], acc[ai][bj][m][n], 0, 0, 0); __builtin_amdgcn_s_setprio(0); } while (0)
; #define PG8_WAIT_V(n) asm volatile("s_waitcnt vmcnt(" #n ")" ::: "memory")
; #define PG8_WAIT_L(n) asm volatile("s_waitcnt lgkmcnt(" #n ")" ::: "memory")
; #define PG8_BAR __builtin_amdgcn_s_barrier()
; #define PG8_SCHED __builtin_amdgcn_sched_barrier(0)
; template <class Epi>
; __device__ __forceinline__ void gemm_phase(LAS unsigned char* lds, const Gemm g, const StaticOrder& S, const Epi& E, int wave_) {
;     ...
;             PG8_STAGE(PG8_SB(1, 0), b3, voffB); PG8_STAGE(PG8_SB(1, 1), b3 + hstepB, voffB); PG8_STAGE(PG8_SA(1, 0), a3, voffA); PG8_LDA(At, 1, 1);
;             PG8_WAIT_V(8); PG8_WAIT_L(0); PG8_BAR; PG8_MMA(1, 0, At, B0); PG8_MMA(1, 1, At, B1); PG8_BAR; PG8_SCHED;
;         }
;         if (wr == 0) PG8_BAR;
	s_add_u32 s36, s36, 0x20080
	s_addc_u32 s37, s37, 0
	v_mov_b32_e32 v164, v179
	s_nop 0
	s_nop 0
	v_xad_u32 v172, v164, 64, 0
	ds_read_b128 v[164:167], v182 offset:49152
	ds_read_b128 v[168:171], v182 offset:51200
	ds_read_b128 v[192:195], v172 offset:49152
	ds_read_b128 v[196:199], v172 offset:51200
	ds_read_b128 v[200:203], v182 offset:53248
	ds_read_b128 v[204:207], v182 offset:55296
	ds_read_b128 v[208:211], v172 offset:53248
	ds_read_b128 v[212:215], v172 offset:55296
	s_mov_b32 m0, s35
	s_nop 0
	global_load_lds_dwordx4 v175, s[42:43]
	s_mov_b32 m0, s33
	s_nop 0
	global_load_lds_dwordx4 v177, s[42:43]
	s_mov_b32 m0, s77
	s_nop 0
	global_load_lds_dwordx4 v175, s[36:37]
	s_mov_b32 m0, s3
	s_nop 0
	global_load_lds_dwordx4 v177, s[36:37]
	s_mov_b32 m0, s22
	s_nop 0
	global_load_lds_dwordx4 v137, s[30:31]
	s_mov_b32 m0, s2
	s_nop 0
	global_load_lds_dwordx4 v176, s[30:31]
	s_waitcnt vmcnt(8)
	s_waitcnt lgkmcnt(0)
	s_barrier
	s_setprio 1
	v_mfma_f32_16x16x32_bf16 v[60:63], v[128:131], v[164:167], v[60:63]
	v_mfma_f32_16x16x32_bf16 v[56:59], v[132:135], v[164:167], v[56:59]
	v_mfma_f32_16x16x32_bf16 v[44:47], v[128:131], v[168:171], v[44:47]
	v_mfma_f32_16x16x32_bf16 v[40:43], v[132:135], v[168:171], v[40:43]
	v_mfma_f32_16x16x32_bf16 v[28:31], v[128:131], v[200:203], v[28:31]
	v_mfma_f32_16x16x32_bf16 v[24:27], v[132:135], v[200:203], v[24:27]
	v_mfma_f32_16x16x32_bf16 v[12:15], v[128:131], v[204:207], v[12:15]
	v_mfma_f32_16x16x32_bf16 v[8:11], v[132:135], v[204:207], v[8:11]
	v_mfma_f32_16x16x32_bf16 v[60:63], v[140:143], v[192:195], v[60:63]
	v_mfma_f32_16x16x32_bf16 v[56:59], v[144:147], v[192:195], v[56:59]
	v_mfma_f32_16x16x32_bf16 v[44:47], v[140:143], v[196:199], v[44:47]
	v_mfma_f32_16x16x32_bf16 v[40:43], v[144:147], v[196:199], v[40:43]
	v_mfma_f32_16x16x32_bf16 v[28:31], v[140:143], v[208:211], v[28:31]
	v_mfma_f32_16x16x32_bf16 v[24:27], v[144:147], v[208:211], v[24:27]
	v_mfma_f32_16x16x32_bf16 v[12:15], v[140:143], v[212:215], v[12:15]
	v_mfma_f32_16x16x32_bf16 v[8:11], v[144:147], v[212:215], v[8:11]
	v_mfma_f32_16x16x32_bf16 v[52:55], v[148:151], v[164:167], v[52:55]
	v_mfma_f32_16x16x32_bf16 v[48:51], v[152:155], v[164:167], v[48:51]
	v_mfma_f32_16x16x32_bf16 v[36:39], v[148:151], v[168:171], v[36:39]
	v_mfma_f32_16x16x32_bf16 v[32:35], v[152:155], v[168:171], v[32:35]
	v_mfma_f32_16x16x32_bf16 v[20:23], v[148:151], v[200:203], v[20:23]
	v_mfma_f32_16x16x32_bf16 v[16:19], v[152:155], v[200:203], v[16:19]
	v_mfma_f32_16x16x32_bf16 v[4:7], v[148:151], v[204:207], v[4:7]
	v_mfma_f32_16x16x32_bf16 v[0:3], v[152:155], v[204:207], v[0:3]
	v_mfma_f32_16x16x32_bf16 v[52:55], v[156:159], v[192:195], v[52:55]
	v_mfma_f32_16x16x32_bf16 v[48:51], v[160:163], v[192:195], v[48:51]
	v_mfma_f32_16x16x32_bf16 v[36:39], v[156:159], v[196:199], v[36:39]
	v_mfma_f32_16x16x32_bf16 v[32:35], v[160:163], v[196:199], v[32:35]
	v_mfma_f32_16x16x32_bf16 v[20:23], v[156:159], v[208:211], v[20:23]
	v_mfma_f32_16x16x32_bf16 v[16:19], v[160:163], v[208:211], v[16:19]
	v_mfma_f32_16x16x32_bf16 v[4:7], v[156:159], v[212:215], v[4:7]
	v_mfma_f32_16x16x32_bf16 v[0:3], v[160:163], v[212:215], v[0:3]
	s_setprio 0
	s_barrier
	s_add_i32 s57, s57, 2
	s_add_u32 s52, s52, 0x100
	s_addc_u32 s56, s56, 0
	s_add_u32 s12, s12, 0x100
	s_addc_u32 s13, s13, 0
	s_cmp_gt_u32 s57, 5
	s_cbranch_scc0 .LBB0_744
	v_readlane_b32 s12, v253, 13
	v_readlane_b32 s13, v253, 14
	s_and_b64 vcc, exec, s[12:13]
	s_cbranch_vccz .LBB0_747
	s_barrier

; #define PG8_STAGE(bufoff, gbase, voff) do { _Pragma("unroll") for (int _i = 0; _i < 2; ++_i) \
;         dma16((const char*)(gbase), (voff)[_i], ldsb + (bufoff) + ldsw + _i * 8192); } while (0)
; #define PG8_LDA(dst, b, h) do { const int a1_ = opqv(aoff0) ^ 64; _Pragma("unroll") for (int m = 0; m < 4; ++m) { dst[m][0] = *(const LAS bf16x8*)(lds + PG8_SA(b, h) + aoff0 + m * 2048); dst[m][1] = *(const LAS bf16x8*)(lds + PG8_SA(b, h) + a1_ + m * 2048); } } while (0)
; #define PG8_LDB(dst, b, h) do { const int b1_ = opqv(boff0) ^ 64; _Pragma("unroll") for (int n = 0; n < 2; ++n) { dst[n][0] = *(const LAS bf16x8*)(lds + PG8_SB(b, h) + boff0 + n * 2048); dst[n][1] = *(const LAS bf16x8*)(lds + PG8_SB(b, h) + b1_ + n * 2048); } } while (0)
; #define PG8_MMA(ai, bj, At, Bt) do { __builtin_amdgcn_s_setprio(1); _Pragma("unroll") for (int m = 0; m < 4; ++m) _Pragma("unroll") for (int n = 0; n < 2; ++n) _Pragma("unroll") for (int k = 0; k < 2; ++k) \
;         acc[ai][bj][m][n] = __builtin_amdgcn_mfma_f32_16x16x32_bf16(Bt[n][k], At[m][k], acc[ai][bj][m][n], 0, 0, 0); __builtin_amdgcn_s_setprio(0); } while (0)
; #define PG8_WAIT_V(n) asm volatile("s_waitcnt vmcnt(" #n ")" ::: "memory")
; #define PG8_WAIT_L(n) asm volatile("s_waitcnt lgkmcnt(" #n ")" ::: "memory")
; #define PG8_BAR __builtin_amdgcn_s_barrier()
; #define PG8_SCHED __builtin_amdgcn_sched_barrier(0)
; template <class Epi>
; __device__ __forceinline__ void gemm_phase(LAS unsigned char* lds, const Gemm g, const StaticOrder& S, const Epi& E, int wave_) {
;     ...
;         for (int t = 0; t < nt; t += 2) {
;             const bool last = (t == nt - 2);
;             const char* a1 = cA + (size_t)(t + 1) * kstep;
;             const char* a2 = last ? nA : cA + (size_t)(t + 2) * kstep; const char* b2 = last ? nB : cB + (size_t)(t + 2) * kstep;
;             const char* a3 = a2 + kstep; const char* b3 = b2 + kstep;
;             PG8_STAGE(PG8_SA(1, 1), a1 + hstepA, voffA); PG8_LDB(B0, 0, 0); PG8_LDB(B1, 0, 1); PG8_SCHED; PG8_LDA(At, 0, 0);
;             PG8_WAIT_V(8); PG8_WAIT_L(0); PG8_BAR; PG8_MMA(0, 0, At, B0); PG8_MMA(0, 1, At, B1); PG8_BAR; PG8_SCHED;
;             PG8_STAGE(PG8_SB(0, 0), b2, voffB); PG8_STAGE(PG8_SB(0, 1), b2 + hstepB, voffB); PG8_STAGE(PG8_SA(0, 0), a2, voffA); PG8_LDA(At, 0, 1);
.LBB0_796:
	s_add_u32 s30, s12, 0xfffc0080
	s_addc_u32 s31, s13, -1
	s_cmp_eq_u32 s55, 4
	s_cselect_b32 s42, s17, s30
	s_cselect_b32 s43, s16, s31
	s_cselect_b32 s36, s19, s52
	s_cselect_b32 s37, s11, s54
	s_add_u32 s30, s42, 0x80
	v_mov_b32_e32 v130, v161
	s_addc_u32 s31, s43, 0
	v_add_u32_e32 v134, s23, v161
	v_xad_u32 v142, v130, 64, s23
	v_mov_b32_e32 v146, v161
	s_add_i32 s56, 0, 0x14000
	ds_read_b128 v[130:133], v134
	ds_read_b128 v[134:137], v134 offset:2048
	ds_read_b128 v[138:141], v142
	ds_read_b128 v[142:145], v142 offset:2048
	v_add_u32_e32 v150, s56, v161
	v_xad_u32 v154, v146, 64, s56
	ds_read_b128 v[146:149], v150
	ds_read_b128 v[150:153], v150 offset:2048
	ds_read_b128 v[162:165], v154
	ds_read_b128 v[166:169], v154 offset:2048
	v_mov_b32_e32 v154, v160
	v_add_u32_e32 v155, 0, v160
	v_xad_u32 v154, v154, 64, 0
	ds_read_b128 v[176:179], v155
	ds_read_b128 v[180:183], v155 offset:2048
	ds_read_b128 v[192:195], v154
	ds_read_b128 v[196:199], v154 offset:2048
	ds_read_b128 v[200:203], v155 offset:4096
	ds_read_b128 v[204:207], v155 offset:6144
	ds_read_b128 v[208:211], v154 offset:4096
	ds_read_b128 v[212:215], v154 offset:6144
	s_mov_b32 m0, s14
	s_nop 0
	global_load_lds_dwordx4 v129, s[12:13]
	s_mov_b32 m0, s15
	s_nop 0
	global_load_lds_dwordx4 v157, s[12:13]
	s_waitcnt vmcnt(8)
	s_waitcnt lgkmcnt(0)
	s_barrier
	s_setprio 1
	v_mfma_f32_16x16x32_bf16 v[124:127], v[130:133], v[176:179], v[124:127]
	v_mfma_f32_16x16x32_bf16 v[120:123], v[134:137], v[176:179], v[120:123]
	v_mfma_f32_16x16x32_bf16 v[108:111], v[130:133], v[180:183], v[108:111]
	v_mfma_f32_16x16x32_bf16 v[104:107], v[134:137], v[180:183], v[104:107]
	v_mfma_f32_16x16x32_bf16 v[92:95], v[130:133], v[200:203], v[92:95]
	v_mfma_f32_16x16x32_bf16 v[88:91], v[134:137], v[200:203], v[88:91]
	v_mfma_f32_16x16x32_bf16 v[76:79], v[130:133], v[204:207], v[76:79]
	v_mfma_f32_16x16x32_bf16 v[72:75], v[134:137], v[204:207], v[72:75]
	v_mfma_f32_16x16x32_bf16 v[124:127], v[138:141], v[192:195], v[124:127]
	v_mfma_f32_16x16x32_bf16 v[120:123], v[142:145], v[192:195], v[120:123]
	v_mfma_f32_16x16x32_bf16 v[108:111], v[138:141], v[196:199], v[108:111]
	v_mfma_f32_16x16x32_bf16 v[104:107], v[142:145], v[196:199], v[104:107]
	v_mfma_f32_16x16x32_bf16 v[92:95], v[138:141], v[208:211], v[92:95]
	v_mfma_f32_16x16x32_bf16 v[88:91], v[142:145], v[208:211], v[88:91]
	v_mfma_f32_16x16x32_bf16 v[76:79], v[138:141], v[212:215], v[76:79]
	v_mfma_f32_16x16x32_bf16 v[72:75], v[142:145], v[212:215], v[72:75]
	v_mfma_f32_16x16x32_bf16 v[116:119], v[146:149], v[176:179], v[116:119]
	v_mfma_f32_16x16x32_bf16 v[112:115], v[150:153], v[176:179], v[112:115]
	v_mfma_f32_16x16x32_bf16 v[100:103], v[146:149], v[180:183], v[100:103]
	v_mfma_f32_16x16x32_bf16 v[96:99], v[150:153], v[180:183], v[96:99]
	v_mfma_f32_16x16x32_bf16 v[84:87], v[146:149], v[200:203], v[84:87]
	v_mfma_f32_16x16x32_bf16 v[80:83], v[150:153], v[200:203], v[80:83]
	v_mfma_f32_16x16x32_bf16 v[68:71], v[146:149], v[204:207], v[68:71]
	v_mfma_f32_16x16x32_bf16 v[64:67], v[150:153], v[204:207], v[64:67]
	v_mfma_f32_16x16x32_bf16 v[116:119], v[162:165], v[192:195], v[116:119]
	v_mfma_f32_16x16x32_bf16 v[112:115], v[166:169], v[192:195], v[112:115]
	v_mfma_f32_16x16x32_bf16 v[100:103], v[162:165], v[196:199], v[100:103]
	v_mfma_f32_16x16x32_bf16 v[96:99], v[166:169], v[196:199], v[96:99]
	v_mfma_f32_16x16x32_bf16 v[84:87], v[162:165], v[208:211], v[84:87]
	v_mfma_f32_16x16x32_bf16 v[80:83], v[166:169], v[208:211], v[80:83]
	v_mfma_f32_16x16x32_bf16 v[68:71], v[162:165], v[212:215], v[68:71]
	v_mfma_f32_16x16x32_bf16 v[64:67], v[166:169], v[212:215], v[64:67]
	s_setprio 0
	s_barrier
	v_mov_b32_e32 v154, v160
	s_add_u32 s56, s36, 0x20000
	s_addc_u32 s57, s37, 0
	s_nop 0
	s_nop 0
	s_nop 0
	v_xad_u32 v154, v154, 64, 0
	ds_read_b128 v[176:179], v155 offset:16384
	ds_read_b128 v[180:183], v155 offset:18432
	ds_read_b128 v[192:195], v154 offset:16384
	ds_read_b128 v[196:199], v154 offset:18432
	ds_read_b128 v[200:203], v155 offset:20480
	ds_read_b128 v[204:207], v155 offset:22528
	ds_read_b128 v[208:211], v154 offset:20480
	ds_read_b128 v[212:215], v154 offset:22528
	s_mov_b32 m0, s80
	s_nop 0
	global_load_lds_dwordx4 v156, s[36:37]
	s_mov_b32 m0, s81
	s_nop 0
	global_load_lds_dwordx4 v158, s[36:37]
	s_mov_b32 m0, s29
	s_nop 0
	global_load_lds_dwordx4 v156, s[56:57]
	s_mov_b32 m0, s88
	s_nop 0
	global_load_lds_dwordx4 v158, s[56:57]
	s_mov_b32 m0, s76
	s_nop 0
	global_load_lds_dwordx4 v129, s[42:43]
	s_mov_b32 m0, s89
	s_nop 0
	global_load_lds_dwordx4 v157, s[42:43]
	s_waitcnt vmcnt(8)
	s_waitcnt lgkmcnt(0)
	s_barrier
; #define PG8_STAGE(bufoff, gbase, voff) do { _Pragma("unroll") for (int _i = 0; _i < 2; ++_i) \
;         dma16((const char*)(gbase), (voff)[_i], ldsb + (bufoff) + ldsw + _i * 8192); } while (0)
; #define PG8_LDA(dst, b, h) do { const int a1_ = opqv(aoff0) ^ 64; _Pragma("unroll") for (int m = 0; m < 4; ++m) { dst[m][0] = *(const LAS bf16x8*)(lds + PG8_SA(b, h) + aoff0 + m * 2048); dst[m][1] = *(const LAS bf16x8*)(lds + PG8_SA(b, h) + a1_ + m * 2048); } } while (0)
; #define PG8_LDB(dst, b, h) do { const int b1_ = opqv(boff0) ^ 64; _Pragma("unroll") for (int n = 0; n < 2; ++n) { dst[n][0] = *(const LAS bf16x8*)(lds + PG8_SB(b, h) + boff0 + n * 2048); dst[n][1] = *(const LAS bf16x8*)(lds + PG8_SB(b, h) + b1_ + n * 2048); } } while (0)
; #define PG8_MMA(ai, bj, At, Bt) do { __builtin_amdgcn_s_setprio(1); _Pragma("unroll") for (int m = 0; m < 4; ++m) _Pragma("unroll") for (int n = 0; n < 2; ++n) _Pragma("unroll") for (int k = 0; k < 2; ++k) \
;         acc[ai][bj][m][n] = __builtin_amdgcn_mfma_f32_16x16x32_bf16(Bt[n][k], At[m][k], acc[ai][bj][m][n], 0, 0, 0); __builtin_amdgcn_s_setprio(0); } while (0)
; #define PG8_WAIT_V(n) asm volatile("s_waitcnt vmcnt(" #n ")" ::: "memory")
; #define PG8_WAIT_L(n) asm volatile("s_waitcnt lgkmcnt(" #n ")" ::: "memory")
; #define PG8_BAR __builtin_amdgcn_s_barrier()
; #define PG8_SCHED __builtin_amdgcn_sched_barrier(0)
; template <class Epi>
; __device__ __forceinline__ void gemm_phase(LAS unsigned char* lds, const Gemm g, const StaticOrder& S, const Epi& E, int wave_) {
;     ...
;             PG8_WAIT_V(8); PG8_WAIT_L(0); PG8_BAR; PG8_MMA(1, 0, At, B0); PG8_MMA(1, 1, At, B1); PG8_BAR; PG8_SCHED;
;             PG8_STAGE(PG8_SA(0, 1), a2 + hstepA, voffA); PG8_LDB(B0, 1, 0); PG8_LDB(B1, 1, 1); PG8_SCHED; PG8_LDA(At, 1, 0);
;             PG8_WAIT_V(8); PG8_WAIT_L(0); PG8_BAR; PG8_MMA(0, 0, At, B0); PG8_MMA(0, 1, At, B1); PG8_BAR; PG8_SCHED;
	s_setprio 1
	v_mfma_f32_16x16x32_bf16 v[60:63], v[130:133], v[176:179], v[60:63]
	v_mfma_f32_16x16x32_bf16 v[56:59], v[134:137], v[176:179], v[56:59]
	v_mfma_f32_16x16x32_bf16 v[44:47], v[130:133], v[180:183], v[44:47]
	v_mfma_f32_16x16x32_bf16 v[40:43], v[134:137], v[180:183], v[40:43]
	v_mfma_f32_16x16x32_bf16 v[28:31], v[130:133], v[200:203], v[28:31]
	v_mfma_f32_16x16x32_bf16 v[24:27], v[134:137], v[200:203], v[24:27]
	v_mfma_f32_16x16x32_bf16 v[12:15], v[130:133], v[204:207], v[12:15]
	v_mfma_f32_16x16x32_bf16 v[8:11], v[134:137], v[204:207], v[8:11]
	v_mfma_f32_16x16x32_bf16 v[60:63], v[138:141], v[192:195], v[60:63]
	v_mfma_f32_16x16x32_bf16 v[56:59], v[142:145], v[192:195], v[56:59]
	v_mfma_f32_16x16x32_bf16 v[44:47], v[138:141], v[196:199], v[44:47]
	v_mfma_f32_16x16x32_bf16 v[40:43], v[142:145], v[196:199], v[40:43]
	v_mfma_f32_16x16x32_bf16 v[28:31], v[138:141], v[208:211], v[28:31]
	v_mfma_f32_16x16x32_bf16 v[24:27], v[142:145], v[208:211], v[24:27]
	v_mfma_f32_16x16x32_bf16 v[12:15], v[138:141], v[212:215], v[12:15]
	v_mfma_f32_16x16x32_bf16 v[8:11], v[142:145], v[212:215], v[8:11]
	v_mfma_f32_16x16x32_bf16 v[52:55], v[146:149], v[176:179], v[52:55]
	v_mfma_f32_16x16x32_bf16 v[48:51], v[150:153], v[176:179], v[48:51]
	v_mfma_f32_16x16x32_bf16 v[36:39], v[146:149], v[180:183], v[36:39]
	v_mfma_f32_16x16x32_bf16 v[32:35], v[150:153], v[180:183], v[32:35]
	v_mfma_f32_16x16x32_bf16 v[20:23], v[146:149], v[200:203], v[20:23]
	v_mfma_f32_16x16x32_bf16 v[16:19], v[150:153], v[200:203], v[16:19]
	v_mfma_f32_16x16x32_bf16 v[4:7], v[146:149], v[204:207], v[4:7]
	v_mfma_f32_16x16x32_bf16 v[0:3], v[150:153], v[204:207], v[0:3]
	v_mfma_f32_16x16x32_bf16 v[52:55], v[162:165], v[192:195], v[52:55]
	v_mfma_f32_16x16x32_bf16 v[48:51], v[166:169], v[192:195], v[48:51]
	v_mfma_f32_16x16x32_bf16 v[36:39], v[162:165], v[196:199], v[36:39]
	v_mfma_f32_16x16x32_bf16 v[32:35], v[166:169], v[196:199], v[32:35]
	v_mfma_f32_16x16x32_bf16 v[20:23], v[162:165], v[208:211], v[20:23]
	v_mfma_f32_16x16x32_bf16 v[16:19], v[166:169], v[208:211], v[16:19]
	v_mfma_f32_16x16x32_bf16 v[4:7], v[162:165], v[212:215], v[4:7]
	v_mfma_f32_16x16x32_bf16 v[0:3], v[166:169], v[212:215], v[0:3]
	s_setprio 0
	s_barrier
	s_add_u32 s42, s42, 0x40000
	s_addc_u32 s43, s43, 0
	s_mov_b32 m0, s1
	s_nop 0
	global_load_lds_dwordx4 v129, s[42:43]
	v_mov_b32_e32 v130, v161
	s_mov_b32 m0, s69
	s_nop 0
	global_load_lds_dwordx4 v157, s[42:43]
	v_add_u32_e32 v134, s34, v161
	v_xad_u32 v142, v130, 64, s34
	v_mov_b32_e32 v146, v161
	s_add_i32 s42, 0, 0x1c000
	ds_read_b128 v[130:133], v134
	ds_read_b128 v[134:137], v134 offset:2048
	ds_read_b128 v[138:141], v142
	ds_read_b128 v[142:145], v142 offset:2048
	v_add_u32_e32 v150, s42, v161
	v_xad_u32 v154, v146, 64, s42
	ds_read_b128 v[146:149], v150
	ds_read_b128 v[150:153], v150 offset:2048
	ds_read_b128 v[162:165], v154
	ds_read_b128 v[166:169], v154 offset:2048
	v_mov_b32_e32 v154, v160
	s_nop 0
	v_xad_u32 v154, v154, 64, 0
	ds_read_b128 v[176:179], v155 offset:32768
	ds_read_b128 v[180:183], v155 offset:34816
	ds_read_b128 v[192:195], v154 offset:32768
	ds_read_b128 v[196:199], v154 offset:34816
	ds_read_b128 v[200:203], v155 offset:36864
	ds_read_b128 v[204:207], v155 offset:38912
	ds_read_b128 v[208:211], v154 offset:36864
	ds_read_b128 v[212:215], v154 offset:38912
	s_waitcnt vmcnt(8)
	s_waitcnt lgkmcnt(0)
	s_barrier
	s_setprio 1
	v_mfma_f32_16x16x32_bf16 v[124:127], v[130:133], v[176:179], v[124:127]
	v_mfma_f32_16x16x32_bf16 v[120:123], v[134:137], v[176:179], v[120:123]
	v_mfma_f32_16x16x32_bf16 v[108:111], v[130:133], v[180:183], v[108:111]
	v_mfma_f32_16x16x32_bf16 v[104:107], v[134:137], v[180:183], v[104:107]
	v_mfma_f32_16x16x32_bf16 v[92:95], v[130:133], v[200:203], v[92:95]
	v_mfma_f32_16x16x32_bf16 v[88:91], v[134:137], v[200:203], v[88:91]
	v_mfma_f32_16x16x32_bf16 v[76:79], v[130:133], v[204:207], v[76:79]
	v_mfma_f32_16x16x32_bf16 v[72:75], v[134:137], v[204:207], v[72:75]
	v_mfma_f32_16x16x32_bf16 v[124:127], v[138:141], v[192:195], v[124:127]
	v_mfma_f32_16x16x32_bf16 v[120:123], v[142:145], v[192:195], v[120:123]
	v_mfma_f32_16x16x32_bf16 v[108:111], v[138:141], v[196:199], v[108:111]
	v_mfma_f32_16x16x32_bf16 v[104:107], v[142:145], v[196:199], v[104:107]
	v_mfma_f32_16x16x32_bf16 v[92:95], v[138:141], v[208:211], v[92:95]
	v_mfma_f32_16x16x32_bf16 v[88:91], v[142:145], v[208:211], v[88:91]
	v_mfma_f32_16x16x32_bf16 v[76:79], v[138:141], v[212:215], v[76:79]
	v_mfma_f32_16x16x32_bf16 v[72:75], v[142:145], v[212:215], v[72:75]
	v_mfma_f32_16x16x32_bf16 v[116:119], v[146:149], v[176:179], v[116:119]
	s_add_u32 s42, s36, 0x80
	s_addc_u32 s43, s37, 0
	v_mfma_f32_16x16x32_bf16 v[112:115], v[150:153], v[176:179], v[112:115]
	v_mfma_f32_16x16x32_bf16 v[100:103], v[146:149], v[180:183], v[100:103]
	v_mfma_f32_16x16x32_bf16 v[96:99], v[150:153], v[180:183], v[96:99]
	v_mfma_f32_16x16x32_bf16 v[84:87], v[146:149], v[200:203], v[84:87]
	v_mfma_f32_16x16x32_bf16 v[80:83], v[150:153], v[200:203], v[80:83]
	v_mfma_f32_16x16x32_bf16 v[68:71], v[146:149], v[204:207], v[68:71]
	v_mfma_f32_16x16x32_bf16 v[64:67], v[150:153], v[204:207], v[64:67]
	v_mfma_f32_16x16x32_bf16 v[116:119], v[162:165], v[192:195], v[116:119]
	v_mfma_f32_16x16x32_bf16 v[112:115], v[166:169], v[192:195], v[112:115]
	v_mfma_f32_16x16x32_bf16 v[100:103], v[162:165], v[196:199], v[100:103]
	v_mfma_f32_16x16x32_bf16 v[96:99], v[166:169], v[196:199], v[96:99]
	v_mfma_f32_16x16x32_bf16 v[84:87], v[162:165], v[208:211], v[84:87]
	v_mfma_f32_16x16x32_bf16 v[80:83], v[166:169], v[208:211], v[80:83]
	v_mfma_f32_16x16x32_bf16 v[68:71], v[162:165], v[212:215], v[68:71]
	v_mfma_f32_16x16x32_bf16 v[64:67], v[166:169], v[212:215], v[64:67]
	s_setprio 0
	s_barrier
; #define PG8_STAGE(bufoff, gbase, voff) do { _Pragma("unroll") for (int _i = 0; _i < 2; ++_i) \
;         dma16((const char*)(gbase), (voff)[_i], ldsb + (bufoff) + ldsw + _i * 8192); } while (0)
; #define PG8_LDA(dst, b, h) do { const int a1_ = opqv(aoff0) ^ 64; _Pragma("unroll") for (int m = 0; m < 4; ++m) { dst[m][0] = *(const LAS bf16x8*)(lds + PG8_SA(b, h) + aoff0 + m * 2048); dst[m][1] = *(const LAS bf16x8*)(lds + PG8_SA(b, h) + a1_ + m * 2048); } } while (0)
; #define PG8_MMA(ai, bj, At, Bt) do { __builtin_amdgcn_s_setprio(1); _Pragma("unroll") for (int m = 0; m < 4; ++m) _Pragma("unroll") for (int n = 0; n < 2; ++n) _Pragma("unroll") for (int k = 0; k < 2; ++k) \
;         acc[ai][bj][m][n] = __builtin_amdgcn_mfma_f32_16x16x32_bf16(Bt[n][k], At[m][k], acc[ai][bj][m][n], 0, 0, 0); __builtin_amdgcn_s_setprio(0); } while (0)
; #define PG8_WAIT_V(n) asm volatile("s_waitcnt vmcnt(" #n ")" ::: "memory")
; #define PG8_WAIT_L(n) asm volatile("s_waitcnt lgkmcnt(" #n ")" ::: "memory")
; #define PG8_BAR __builtin_amdgcn_s_barrier()
; #define PG8_SCHED __builtin_amdgcn_sched_barrier(0)
; template <class Epi>
; __device__ __forceinline__ void gemm_phase(LAS unsigned char* lds, const Gemm g, const StaticOrder& S, const Epi& E, int wave_) {
;     ...
;             PG8_STAGE(PG8_SB(1, 0), b3, voffB); PG8_STAGE(PG8_SB(1, 1), b3 + hstepB, voffB); PG8_STAGE(PG8_SA(1, 0), a3, voffA); PG8_LDA(At, 1, 1);
;             PG8_WAIT_V(8); PG8_WAIT_L(0); PG8_BAR; PG8_MMA(1, 0, At, B0); PG8_MMA(1, 1, At, B1); PG8_BAR; PG8_SCHED;
;         }
;         if (wr == 0) PG8_BAR;
	s_add_u32 s36, s36, 0x20080
	s_addc_u32 s37, s37, 0
	v_mov_b32_e32 v154, v160
	s_nop 0
	s_nop 0
	v_xad_u32 v154, v154, 64, 0
	ds_read_b128 v[176:179], v155 offset:49152
	ds_read_b128 v[180:183], v155 offset:51200
	ds_read_b128 v[192:195], v154 offset:49152
	ds_read_b128 v[196:199], v154 offset:51200
	ds_read_b128 v[200:203], v155 offset:53248
	ds_read_b128 v[204:207], v155 offset:55296
	ds_read_b128 v[208:211], v154 offset:53248
	ds_read_b128 v[212:215], v154 offset:55296
	s_mov_b32 m0, s35
	s_nop 0
	global_load_lds_dwordx4 v156, s[42:43]
	s_mov_b32 m0, s33
	s_nop 0
	global_load_lds_dwordx4 v158, s[42:43]
	s_mov_b32 m0, s77
	s_nop 0
	global_load_lds_dwordx4 v156, s[36:37]
	s_mov_b32 m0, s3
	s_nop 0
	global_load_lds_dwordx4 v158, s[36:37]
	s_mov_b32 m0, s22
	s_nop 0
	global_load_lds_dwordx4 v129, s[30:31]
	s_mov_b32 m0, s2
	s_nop 0
	global_load_lds_dwordx4 v157, s[30:31]
	s_waitcnt vmcnt(8)
	s_waitcnt lgkmcnt(0)
	s_barrier
	s_setprio 1
	v_mfma_f32_16x16x32_bf16 v[60:63], v[130:133], v[176:179], v[60:63]
	v_mfma_f32_16x16x32_bf16 v[56:59], v[134:137], v[176:179], v[56:59]
	v_mfma_f32_16x16x32_bf16 v[44:47], v[130:133], v[180:183], v[44:47]
	v_mfma_f32_16x16x32_bf16 v[40:43], v[134:137], v[180:183], v[40:43]
	v_mfma_f32_16x16x32_bf16 v[28:31], v[130:133], v[200:203], v[28:31]
	v_mfma_f32_16x16x32_bf16 v[24:27], v[134:137], v[200:203], v[24:27]
	v_mfma_f32_16x16x32_bf16 v[12:15], v[130:133], v[204:207], v[12:15]
	v_mfma_f32_16x16x32_bf16 v[8:11], v[134:137], v[204:207], v[8:11]
	v_mfma_f32_16x16x32_bf16 v[60:63], v[138:141], v[192:195], v[60:63]
	v_mfma_f32_16x16x32_bf16 v[56:59], v[142:145], v[192:195], v[56:59]
	v_mfma_f32_16x16x32_bf16 v[44:47], v[138:141], v[196:199], v[44:47]
	v_mfma_f32_16x16x32_bf16 v[40:43], v[142:145], v[196:199], v[40:43]
	v_mfma_f32_16x16x32_bf16 v[28:31], v[138:141], v[208:211], v[28:31]
	v_mfma_f32_16x16x32_bf16 v[24:27], v[142:145], v[208:211], v[24:27]
	v_mfma_f32_16x16x32_bf16 v[12:15], v[138:141], v[212:215], v[12:15]
	v_mfma_f32_16x16x32_bf16 v[8:11], v[142:145], v[212:215], v[8:11]
	v_mfma_f32_16x16x32_bf16 v[52:55], v[146:149], v[176:179], v[52:55]
	v_mfma_f32_16x16x32_bf16 v[48:51], v[150:153], v[176:179], v[48:51]
	v_mfma_f32_16x16x32_bf16 v[36:39], v[146:149], v[180:183], v[36:39]
	v_mfma_f32_16x16x32_bf16 v[32:35], v[150:153], v[180:183], v[32:35]
	v_mfma_f32_16x16x32_bf16 v[20:23], v[146:149], v[200:203], v[20:23]
	v_mfma_f32_16x16x32_bf16 v[16:19], v[150:153], v[200:203], v[16:19]
	v_mfma_f32_16x16x32_bf16 v[4:7], v[146:149], v[204:207], v[4:7]
	v_mfma_f32_16x16x32_bf16 v[0:3], v[150:153], v[204:207], v[0:3]
	v_mfma_f32_16x16x32_bf16 v[52:55], v[162:165], v[192:195], v[52:55]
	v_mfma_f32_16x16x32_bf16 v[48:51], v[166:169], v[192:195], v[48:51]
	v_mfma_f32_16x16x32_bf16 v[36:39], v[162:165], v[196:199], v[36:39]
	v_mfma_f32_16x16x32_bf16 v[32:35], v[166:169], v[196:199], v[32:35]
	v_mfma_f32_16x16x32_bf16 v[20:23], v[162:165], v[208:211], v[20:23]
	v_mfma_f32_16x16x32_bf16 v[16:19], v[166:169], v[208:211], v[16:19]
	v_mfma_f32_16x16x32_bf16 v[4:7], v[162:165], v[212:215], v[4:7]
	v_mfma_f32_16x16x32_bf16 v[0:3], v[166:169], v[212:215], v[0:3]
	s_setprio 0
	s_barrier
	s_add_i32 s55, s55, 2
	s_add_u32 s52, s52, 0x100
	s_addc_u32 s54, s54, 0
	s_add_u32 s12, s12, 0x100
	s_addc_u32 s13, s13, 0
	s_cmp_gt_u32 s55, 5
	s_cbranch_scc0 .LBB0_796
	v_readlane_b32 s12, v253, 13
	v_readlane_b32 s13, v253, 14
	s_and_b64 vcc, exec, s[12:13]
	s_cbranch_vccz .LBB0_799
	s_barrier

; #define PG8_STAGE(bufoff, gbase, voff) do { _Pragma("unroll") for (int _i = 0; _i < 2; ++_i) \
;         dma16((const char*)(gbase), (voff)[_i], ldsb + (bufoff) + ldsw + _i * 8192); } while (0)
; #define PG8_LDA(dst, b, h) do { const int a1_ = opqv(aoff0) ^ 64; _Pragma("unroll") for (int m = 0; m < 4; ++m) { dst[m][0] = *(const LAS bf16x8*)(lds + PG8_SA(b, h) + aoff0 + m * 2048); dst[m][1] = *(const LAS bf16x8*)(lds + PG8_SA(b, h) + a1_ + m * 2048); } } while (0)
; #define PG8_LDB(dst, b, h) do { const int b1_ = opqv(boff0) ^ 64; _Pragma("unroll") for (int n = 0; n < 2; ++n) { dst[n][0] = *(const LAS bf16x8*)(lds + PG8_SB(b, h) + boff0 + n * 2048); dst[n][1] = *(const LAS bf16x8*)(lds + PG8_SB(b, h) + b1_ + n * 2048); } } while (0)
; #define PG8_MMA(ai, bj, At, Bt) do { __builtin_amdgcn_s_setprio(1); _Pragma("unroll") for (int m = 0; m < 4; ++m) _Pragma("unroll") for (int n = 0; n < 2; ++n) _Pragma("unroll") for (int k = 0; k < 2; ++k) \
;         acc[ai][bj][m][n] = __builtin_amdgcn_mfma_f32_16x16x32_bf16(Bt[n][k], At[m][k], acc[ai][bj][m][n], 0, 0, 0); __builtin_amdgcn_s_setprio(0); } while (0)
; #define PG8_WAIT_V(n) asm volatile("s_waitcnt vmcnt(" #n ")" ::: "memory")
; #define PG8_WAIT_L(n) asm volatile("s_waitcnt lgkmcnt(" #n ")" ::: "memory")
; #define PG8_BAR __builtin_amdgcn_s_barrier()
; #define PG8_SCHED __builtin_amdgcn_sched_barrier(0)
; template <class Epi>
; __device__ __forceinline__ void gemm_phase(LAS unsigned char* lds, const Gemm g, const StaticOrder& S, const Epi& E, int wave_) {
;     ...
;         for (int t = 0; t < nt; t += 2) {
;             const bool last = (t == nt - 2);
;             const char* a1 = cA + (size_t)(t + 1) * kstep;
;             const char* a2 = last ? nA : cA + (size_t)(t + 2) * kstep; const char* b2 = last ? nB : cB + (size_t)(t + 2) * kstep;
;             const char* a3 = a2 + kstep; const char* b3 = b2 + kstep;
;             PG8_STAGE(PG8_SA(1, 1), a1 + hstepA, voffA); PG8_LDB(B0, 0, 0); PG8_LDB(B1, 0, 1); PG8_SCHED; PG8_LDA(At, 0, 0);
;             PG8_WAIT_V(8); PG8_WAIT_L(0); PG8_BAR; PG8_MMA(0, 0, At, B0); PG8_MMA(0, 1, At, B1); PG8_BAR; PG8_SCHED;
;             PG8_STAGE(PG8_SB(0, 0), b2, voffB); PG8_STAGE(PG8_SB(0, 1), b2 + hstepB, voffB); PG8_STAGE(PG8_SA(0, 0), a2, voffA); PG8_LDA(At, 0, 1);
.LBB0_1104:
	s_add_u32 s30, s12, 0xfff80080
	s_addc_u32 s31, s13, -1
	s_cmp_eq_u32 s57, 28
	s_cselect_b32 s40, s17, s30
	s_cselect_b32 s41, s16, s31
	s_cselect_b32 s36, s19, s55
	s_cselect_b32 s37, s11, s56
	s_add_u32 s30, s40, 0x80
	v_mov_b32_e32 v128, v172
	s_addc_u32 s31, s41, 0
	v_add_u32_e32 v132, s23, v172
	v_xad_u32 v140, v128, 64, s23
	v_mov_b32_e32 v144, v172
	s_add_i32 s60, 0, 0x14000
	ds_read_b128 v[128:131], v132
	ds_read_b128 v[132:135], v132 offset:2048
	ds_read_b128 v[136:139], v140
	ds_read_b128 v[140:143], v140 offset:2048
	v_add_u32_e32 v148, s60, v172
	v_xad_u32 v156, v144, 64, s60
	ds_read_b128 v[144:147], v148
	ds_read_b128 v[148:151], v148 offset:2048
	ds_read_b128 v[152:155], v156
	ds_read_b128 v[156:159], v156 offset:2048
	v_mov_b32_e32 v160, v171
	v_add_u32_e32 v183, 0, v171
	v_xad_u32 v182, v160, 64, 0
	ds_read_b128 v[160:163], v183
	ds_read_b128 v[174:177], v183 offset:2048
	ds_read_b128 v[178:181], v182
	ds_read_b128 v[192:195], v182 offset:2048
	ds_read_b128 v[196:199], v183 offset:4096
	ds_read_b128 v[200:203], v183 offset:6144
	ds_read_b128 v[204:207], v182 offset:4096
	ds_read_b128 v[208:211], v182 offset:6144
	s_mov_b32 m0, s14
	s_nop 0
	global_load_lds_dwordx4 v166, s[12:13]
	s_mov_b32 m0, s15
	s_nop 0
	global_load_lds_dwordx4 v168, s[12:13]
	s_waitcnt vmcnt(8)
	s_waitcnt lgkmcnt(0)
	s_barrier
	s_setprio 1
	v_mfma_f32_16x16x32_bf16 v[124:127], v[128:131], v[160:163], v[124:127]
	v_mfma_f32_16x16x32_bf16 v[120:123], v[132:135], v[160:163], v[120:123]
	v_mfma_f32_16x16x32_bf16 v[108:111], v[128:131], v[174:177], v[108:111]
	v_mfma_f32_16x16x32_bf16 v[104:107], v[132:135], v[174:177], v[104:107]
	v_mfma_f32_16x16x32_bf16 v[92:95], v[128:131], v[196:199], v[92:95]
	v_mfma_f32_16x16x32_bf16 v[88:91], v[132:135], v[196:199], v[88:91]
	v_mfma_f32_16x16x32_bf16 v[76:79], v[128:131], v[200:203], v[76:79]
	v_mfma_f32_16x16x32_bf16 v[72:75], v[132:135], v[200:203], v[72:75]
	v_mfma_f32_16x16x32_bf16 v[124:127], v[136:139], v[178:181], v[124:127]
	v_mfma_f32_16x16x32_bf16 v[120:123], v[140:143], v[178:181], v[120:123]
	v_mfma_f32_16x16x32_bf16 v[108:111], v[136:139], v[192:195], v[108:111]
	v_mfma_f32_16x16x32_bf16 v[104:107], v[140:143], v[192:195], v[104:107]
	v_mfma_f32_16x16x32_bf16 v[92:95], v[136:139], v[204:207], v[92:95]
	v_mfma_f32_16x16x32_bf16 v[88:91], v[140:143], v[204:207], v[88:91]
	v_mfma_f32_16x16x32_bf16 v[76:79], v[136:139], v[208:211], v[76:79]
	v_mfma_f32_16x16x32_bf16 v[72:75], v[140:143], v[208:211], v[72:75]
	v_mfma_f32_16x16x32_bf16 v[116:119], v[144:147], v[160:163], v[116:119]
	v_mfma_f32_16x16x32_bf16 v[112:115], v[148:151], v[160:163], v[112:115]
	v_mfma_f32_16x16x32_bf16 v[100:103], v[144:147], v[174:177], v[100:103]
	v_mfma_f32_16x16x32_bf16 v[96:99], v[148:151], v[174:177], v[96:99]
	v_mfma_f32_16x16x32_bf16 v[84:87], v[144:147], v[196:199], v[84:87]
	v_mfma_f32_16x16x32_bf16 v[80:83], v[148:151], v[196:199], v[80:83]
	v_mfma_f32_16x16x32_bf16 v[68:71], v[144:147], v[200:203], v[68:71]
	v_mfma_f32_16x16x32_bf16 v[64:67], v[148:151], v[200:203], v[64:67]
	v_mfma_f32_16x16x32_bf16 v[116:119], v[152:155], v[178:181], v[116:119]
	v_mfma_f32_16x16x32_bf16 v[112:115], v[156:159], v[178:181], v[112:115]
	v_mfma_f32_16x16x32_bf16 v[100:103], v[152:155], v[192:195], v[100:103]
	v_mfma_f32_16x16x32_bf16 v[96:99], v[156:159], v[192:195], v[96:99]
	v_mfma_f32_16x16x32_bf16 v[84:87], v[152:155], v[204:207], v[84:87]
	v_mfma_f32_16x16x32_bf16 v[80:83], v[156:159], v[204:207], v[80:83]
	v_mfma_f32_16x16x32_bf16 v[68:71], v[152:155], v[208:211], v[68:71]
	v_mfma_f32_16x16x32_bf16 v[64:67], v[156:159], v[208:211], v[64:67]
	s_setprio 0
	s_barrier
	v_mov_b32_e32 v160, v171
	s_add_u32 s60, s36, 0x80000
	s_addc_u32 s61, s37, 0
	s_nop 0
	s_nop 0
	s_nop 0
	v_xad_u32 v182, v160, 64, 0
	ds_read_b128 v[160:163], v183 offset:16384
	ds_read_b128 v[174:177], v183 offset:18432
	ds_read_b128 v[178:181], v182 offset:16384
	ds_read_b128 v[192:195], v182 offset:18432
	ds_read_b128 v[196:199], v183 offset:20480
	ds_read_b128 v[200:203], v183 offset:22528
	ds_read_b128 v[204:207], v182 offset:20480
	ds_read_b128 v[208:211], v182 offset:22528
	s_mov_b32 m0, s80
	s_nop 0
	global_load_lds_dwordx4 v167, s[36:37]
	s_mov_b32 m0, s81
	s_nop 0
	global_load_lds_dwordx4 v169, s[36:37]
	s_mov_b32 m0, s29
	s_nop 0
	global_load_lds_dwordx4 v167, s[60:61]
	s_mov_b32 m0, s88
	s_nop 0
	global_load_lds_dwordx4 v169, s[60:61]
	s_mov_b32 m0, s76
	s_nop 0
	global_load_lds_dwordx4 v166, s[40:41]
	s_mov_b32 m0, s89
	s_nop 0
	global_load_lds_dwordx4 v168, s[40:41]
	s_waitcnt vmcnt(8)
	s_waitcnt lgkmcnt(0)
	s_barrier
; #define PG8_STAGE(bufoff, gbase, voff) do { _Pragma("unroll") for (int _i = 0; _i < 2; ++_i) \
;         dma16((const char*)(gbase), (voff)[_i], ldsb + (bufoff) + ldsw + _i * 8192); } while (0)
; #define PG8_LDA(dst, b, h) do { const int a1_ = opqv(aoff0) ^ 64; _Pragma("unroll") for (int m = 0; m < 4; ++m) { dst[m][0] = *(const LAS bf16x8*)(lds + PG8_SA(b, h) + aoff0 + m * 2048); dst[m][1] = *(const LAS bf16x8*)(lds + PG8_SA(b, h) + a1_ + m * 2048); } } while (0)
; #define PG8_LDB(dst, b, h) do { const int b1_ = opqv(boff0) ^ 64; _Pragma("unroll") for (int n = 0; n < 2; ++n) { dst[n][0] = *(const LAS bf16x8*)(lds + PG8_SB(b, h) + boff0 + n * 2048); dst[n][1] = *(const LAS bf16x8*)(lds + PG8_SB(b, h) + b1_ + n * 2048); } } while (0)
; #define PG8_MMA(ai, bj, At, Bt) do { __builtin_amdgcn_s_setprio(1); _Pragma("unroll") for (int m = 0; m < 4; ++m) _Pragma("unroll") for (int n = 0; n < 2; ++n) _Pragma("unroll") for (int k = 0; k < 2; ++k) \
;         acc[ai][bj][m][n] = __builtin_amdgcn_mfma_f32_16x16x32_bf16(Bt[n][k], At[m][k], acc[ai][bj][m][n], 0, 0, 0); __builtin_amdgcn_s_setprio(0); } while (0)
; #define PG8_WAIT_V(n) asm volatile("s_waitcnt vmcnt(" #n ")" ::: "memory")
; #define PG8_WAIT_L(n) asm volatile("s_waitcnt lgkmcnt(" #n ")" ::: "memory")
; #define PG8_BAR __builtin_amdgcn_s_barrier()
; #define PG8_SCHED __builtin_amdgcn_sched_barrier(0)
; template <class Epi>
; __device__ __forceinline__ void gemm_phase(LAS unsigned char* lds, const Gemm g, const StaticOrder& S, const Epi& E, int wave_) {
;     ...
;             PG8_WAIT_V(8); PG8_WAIT_L(0); PG8_BAR; PG8_MMA(1, 0, At, B0); PG8_MMA(1, 1, At, B1); PG8_BAR; PG8_SCHED;
;             PG8_STAGE(PG8_SA(0, 1), a2 + hstepA, voffA); PG8_LDB(B0, 1, 0); PG8_LDB(B1, 1, 1); PG8_SCHED; PG8_LDA(At, 1, 0);
;             PG8_WAIT_V(8); PG8_WAIT_L(0); PG8_BAR; PG8_MMA(0, 0, At, B0); PG8_MMA(0, 1, At, B1); PG8_BAR; PG8_SCHED;
	s_setprio 1
	v_mfma_f32_16x16x32_bf16 v[60:63], v[128:131], v[160:163], v[60:63]
	v_mfma_f32_16x16x32_bf16 v[56:59], v[132:135], v[160:163], v[56:59]
	v_mfma_f32_16x16x32_bf16 v[44:47], v[128:131], v[174:177], v[44:47]
	v_mfma_f32_16x16x32_bf16 v[40:43], v[132:135], v[174:177], v[40:43]
	v_mfma_f32_16x16x32_bf16 v[28:31], v[128:131], v[196:199], v[28:31]
	v_mfma_f32_16x16x32_bf16 v[24:27], v[132:135], v[196:199], v[24:27]
	v_mfma_f32_16x16x32_bf16 v[12:15], v[128:131], v[200:203], v[12:15]
	v_mfma_f32_16x16x32_bf16 v[8:11], v[132:135], v[200:203], v[8:11]
	v_mfma_f32_16x16x32_bf16 v[60:63], v[136:139], v[178:181], v[60:63]
	v_mfma_f32_16x16x32_bf16 v[56:59], v[140:143], v[178:181], v[56:59]
	v_mfma_f32_16x16x32_bf16 v[44:47], v[136:139], v[192:195], v[44:47]
	v_mfma_f32_16x16x32_bf16 v[40:43], v[140:143], v[192:195], v[40:43]
	v_mfma_f32_16x16x32_bf16 v[28:31], v[136:139], v[204:207], v[28:31]
	v_mfma_f32_16x16x32_bf16 v[24:27], v[140:143], v[204:207], v[24:27]
	v_mfma_f32_16x16x32_bf16 v[12:15], v[136:139], v[208:211], v[12:15]
	v_mfma_f32_16x16x32_bf16 v[8:11], v[140:143], v[208:211], v[8:11]
	v_mfma_f32_16x16x32_bf16 v[52:55], v[144:147], v[160:163], v[52:55]
	v_mfma_f32_16x16x32_bf16 v[48:51], v[148:151], v[160:163], v[48:51]
	v_mfma_f32_16x16x32_bf16 v[36:39], v[144:147], v[174:177], v[36:39]
	v_mfma_f32_16x16x32_bf16 v[32:35], v[148:151], v[174:177], v[32:35]
	v_mfma_f32_16x16x32_bf16 v[20:23], v[144:147], v[196:199], v[20:23]
	v_mfma_f32_16x16x32_bf16 v[16:19], v[148:151], v[196:199], v[16:19]
	v_mfma_f32_16x16x32_bf16 v[4:7], v[144:147], v[200:203], v[4:7]
	v_mfma_f32_16x16x32_bf16 v[0:3], v[148:151], v[200:203], v[0:3]
	v_mfma_f32_16x16x32_bf16 v[52:55], v[152:155], v[178:181], v[52:55]
	v_mfma_f32_16x16x32_bf16 v[48:51], v[156:159], v[178:181], v[48:51]
	v_mfma_f32_16x16x32_bf16 v[36:39], v[152:155], v[192:195], v[36:39]
	v_mfma_f32_16x16x32_bf16 v[32:35], v[156:159], v[192:195], v[32:35]
	v_mfma_f32_16x16x32_bf16 v[20:23], v[152:155], v[204:207], v[20:23]
	v_mfma_f32_16x16x32_bf16 v[16:19], v[156:159], v[204:207], v[16:19]
	v_mfma_f32_16x16x32_bf16 v[4:7], v[152:155], v[208:211], v[4:7]
	v_mfma_f32_16x16x32_bf16 v[0:3], v[156:159], v[208:211], v[0:3]
	s_setprio 0
	s_barrier
	s_add_u32 s40, s40, 0x80000
	s_addc_u32 s41, s41, 0
	s_mov_b32 m0, s1
	s_nop 0
	global_load_lds_dwordx4 v166, s[40:41]
	v_mov_b32_e32 v128, v172
	s_mov_b32 m0, s69
	s_nop 0
	global_load_lds_dwordx4 v168, s[40:41]
	v_add_u32_e32 v132, s34, v172
	v_xad_u32 v140, v128, 64, s34
	v_mov_b32_e32 v144, v172
	s_add_i32 s40, 0, 0x1c000
	ds_read_b128 v[128:131], v132
	ds_read_b128 v[132:135], v132 offset:2048
	ds_read_b128 v[136:139], v140
	ds_read_b128 v[140:143], v140 offset:2048
	v_add_u32_e32 v148, s40, v172
	v_xad_u32 v156, v144, 64, s40
	ds_read_b128 v[144:147], v148
	ds_read_b128 v[148:151], v148 offset:2048
	ds_read_b128 v[152:155], v156
	ds_read_b128 v[156:159], v156 offset:2048
	v_mov_b32_e32 v160, v171
	s_nop 0
	v_xad_u32 v182, v160, 64, 0
	ds_read_b128 v[160:163], v183 offset:32768
	ds_read_b128 v[174:177], v183 offset:34816
	ds_read_b128 v[178:181], v182 offset:32768
	ds_read_b128 v[192:195], v182 offset:34816
	ds_read_b128 v[196:199], v183 offset:36864
	ds_read_b128 v[200:203], v183 offset:38912
	ds_read_b128 v[204:207], v182 offset:36864
	ds_read_b128 v[208:211], v182 offset:38912
	s_waitcnt vmcnt(8)
	s_waitcnt lgkmcnt(0)
	s_barrier
	s_setprio 1
	v_mfma_f32_16x16x32_bf16 v[124:127], v[128:131], v[160:163], v[124:127]
	v_mfma_f32_16x16x32_bf16 v[120:123], v[132:135], v[160:163], v[120:123]
	v_mfma_f32_16x16x32_bf16 v[108:111], v[128:131], v[174:177], v[108:111]
	v_mfma_f32_16x16x32_bf16 v[104:107], v[132:135], v[174:177], v[104:107]
	v_mfma_f32_16x16x32_bf16 v[92:95], v[128:131], v[196:199], v[92:95]
	v_mfma_f32_16x16x32_bf16 v[88:91], v[132:135], v[196:199], v[88:91]
	v_mfma_f32_16x16x32_bf16 v[76:79], v[128:131], v[200:203], v[76:79]
	v_mfma_f32_16x16x32_bf16 v[72:75], v[132:135], v[200:203], v[72:75]
	v_mfma_f32_16x16x32_bf16 v[124:127], v[136:139], v[178:181], v[124:127]
	v_mfma_f32_16x16x32_bf16 v[120:123], v[140:143], v[178:181], v[120:123]
	v_mfma_f32_16x16x32_bf16 v[108:111], v[136:139], v[192:195], v[108:111]
	v_mfma_f32_16x16x32_bf16 v[104:107], v[140:143], v[192:195], v[104:107]
	v_mfma_f32_16x16x32_bf16 v[92:95], v[136:139], v[204:207], v[92:95]
	v_mfma_f32_16x16x32_bf16 v[88:91], v[140:143], v[204:207], v[88:91]
	v_mfma_f32_16x16x32_bf16 v[76:79], v[136:139], v[208:211], v[76:79]
	v_mfma_f32_16x16x32_bf16 v[72:75], v[140:143], v[208:211], v[72:75]
	v_mfma_f32_16x16x32_bf16 v[116:119], v[144:147], v[160:163], v[116:119]
	s_add_u32 s40, s36, 0x80
	s_addc_u32 s41, s37, 0
	v_mfma_f32_16x16x32_bf16 v[112:115], v[148:151], v[160:163], v[112:115]
	v_mfma_f32_16x16x32_bf16 v[100:103], v[144:147], v[174:177], v[100:103]
	v_mfma_f32_16x16x32_bf16 v[96:99], v[148:151], v[174:177], v[96:99]
	v_mfma_f32_16x16x32_bf16 v[84:87], v[144:147], v[196:199], v[84:87]
	v_mfma_f32_16x16x32_bf16 v[80:83], v[148:151], v[196:199], v[80:83]
	v_mfma_f32_16x16x32_bf16 v[68:71], v[144:147], v[200:203], v[68:71]
	v_mfma_f32_16x16x32_bf16 v[64:67], v[148:151], v[200:203], v[64:67]
	v_mfma_f32_16x16x32_bf16 v[116:119], v[152:155], v[178:181], v[116:119]
	v_mfma_f32_16x16x32_bf16 v[112:115], v[156:159], v[178:181], v[112:115]
	v_mfma_f32_16x16x32_bf16 v[100:103], v[152:155], v[192:195], v[100:103]
	v_mfma_f32_16x16x32_bf16 v[96:99], v[156:159], v[192:195], v[96:99]
	v_mfma_f32_16x16x32_bf16 v[84:87], v[152:155], v[204:207], v[84:87]
	v_mfma_f32_16x16x32_bf16 v[80:83], v[156:159], v[204:207], v[80:83]
	v_mfma_f32_16x16x32_bf16 v[68:71], v[152:155], v[208:211], v[68:71]
	v_mfma_f32_16x16x32_bf16 v[64:67], v[156:159], v[208:211], v[64:67]
	s_setprio 0
	s_barrier
; #define PG8_STAGE(bufoff, gbase, voff) do { _Pragma("unroll") for (int _i = 0; _i < 2; ++_i) \
;         dma16((const char*)(gbase), (voff)[_i], ldsb + (bufoff) + ldsw + _i * 8192); } while (0)
; #define PG8_LDA(dst, b, h) do { const int a1_ = opqv(aoff0) ^ 64; _Pragma("unroll") for (int m = 0; m < 4; ++m) { dst[m][0] = *(const LAS bf16x8*)(lds + PG8_SA(b, h) + aoff0 + m * 2048); dst[m][1] = *(const LAS bf16x8*)(lds + PG8_SA(b, h) + a1_ + m * 2048); } } while (0)
; #define PG8_MMA(ai, bj, At, Bt) do { __builtin_amdgcn_s_setprio(1); _Pragma("unroll") for (int m = 0; m < 4; ++m) _Pragma("unroll") for (int n = 0; n < 2; ++n) _Pragma("unroll") for (int k = 0; k < 2; ++k) \
;         acc[ai][bj][m][n] = __builtin_amdgcn_mfma_f32_16x16x32_bf16(Bt[n][k], At[m][k], acc[ai][bj][m][n], 0, 0, 0); __builtin_amdgcn_s_setprio(0); } while (0)
; #define PG8_WAIT_V(n) asm volatile("s_waitcnt vmcnt(" #n ")" ::: "memory")
; #define PG8_WAIT_L(n) asm volatile("s_waitcnt lgkmcnt(" #n ")" ::: "memory")
; #define PG8_BAR __builtin_amdgcn_s_barrier()
; #define PG8_SCHED __builtin_amdgcn_sched_barrier(0)
; template <class Epi>
; __device__ __forceinline__ void gemm_phase(LAS unsigned char* lds, const Gemm g, const StaticOrder& S, const Epi& E, int wave_) {
;     ...
;             PG8_STAGE(PG8_SB(1, 0), b3, voffB); PG8_STAGE(PG8_SB(1, 1), b3 + hstepB, voffB); PG8_STAGE(PG8_SA(1, 0), a3, voffA); PG8_LDA(At, 1, 1);
;             PG8_WAIT_V(8); PG8_WAIT_L(0); PG8_BAR; PG8_MMA(1, 0, At, B0); PG8_MMA(1, 1, At, B1); PG8_BAR; PG8_SCHED;
;         }
;         if (wr == 0) PG8_BAR;
	s_add_u32 s36, s36, 0x80080
	s_addc_u32 s37, s37, 0
	v_mov_b32_e32 v160, v171
	s_nop 0
	s_nop 0
	v_xad_u32 v182, v160, 64, 0
	ds_read_b128 v[160:163], v183 offset:49152
	ds_read_b128 v[174:177], v183 offset:51200
	ds_read_b128 v[178:181], v182 offset:49152
	ds_read_b128 v[192:195], v182 offset:51200
	ds_read_b128 v[196:199], v183 offset:53248
	ds_read_b128 v[200:203], v183 offset:55296
	ds_read_b128 v[204:207], v182 offset:53248
	ds_read_b128 v[208:211], v182 offset:55296
	s_mov_b32 m0, s35
	s_nop 0
	global_load_lds_dwordx4 v167, s[40:41]
	s_mov_b32 m0, s33
	s_nop 0
	global_load_lds_dwordx4 v169, s[40:41]
	s_mov_b32 m0, s77
	s_nop 0
	global_load_lds_dwordx4 v167, s[36:37]
	s_mov_b32 m0, s3
	s_nop 0
	global_load_lds_dwordx4 v169, s[36:37]
	s_mov_b32 m0, s22
	s_nop 0
	global_load_lds_dwordx4 v166, s[30:31]
	s_mov_b32 m0, s2
	s_nop 0
	global_load_lds_dwordx4 v168, s[30:31]
	s_waitcnt vmcnt(8)
	s_waitcnt lgkmcnt(0)
	s_barrier
	s_setprio 1
	v_mfma_f32_16x16x32_bf16 v[60:63], v[128:131], v[160:163], v[60:63]
	v_mfma_f32_16x16x32_bf16 v[56:59], v[132:135], v[160:163], v[56:59]
	v_mfma_f32_16x16x32_bf16 v[44:47], v[128:131], v[174:177], v[44:47]
	v_mfma_f32_16x16x32_bf16 v[40:43], v[132:135], v[174:177], v[40:43]
	v_mfma_f32_16x16x32_bf16 v[28:31], v[128:131], v[196:199], v[28:31]
	v_mfma_f32_16x16x32_bf16 v[24:27], v[132:135], v[196:199], v[24:27]
	v_mfma_f32_16x16x32_bf16 v[12:15], v[128:131], v[200:203], v[12:15]
	v_mfma_f32_16x16x32_bf16 v[8:11], v[132:135], v[200:203], v[8:11]
	v_mfma_f32_16x16x32_bf16 v[60:63], v[136:139], v[178:181], v[60:63]
	v_mfma_f32_16x16x32_bf16 v[56:59], v[140:143], v[178:181], v[56:59]
	v_mfma_f32_16x16x32_bf16 v[44:47], v[136:139], v[192:195], v[44:47]
	v_mfma_f32_16x16x32_bf16 v[40:43], v[140:143], v[192:195], v[40:43]
	v_mfma_f32_16x16x32_bf16 v[28:31], v[136:139], v[204:207], v[28:31]
	v_mfma_f32_16x16x32_bf16 v[24:27], v[140:143], v[204:207], v[24:27]
	v_mfma_f32_16x16x32_bf16 v[12:15], v[136:139], v[208:211], v[12:15]
	v_mfma_f32_16x16x32_bf16 v[8:11], v[140:143], v[208:211], v[8:11]
	v_mfma_f32_16x16x32_bf16 v[52:55], v[144:147], v[160:163], v[52:55]
	v_mfma_f32_16x16x32_bf16 v[48:51], v[148:151], v[160:163], v[48:51]
	v_mfma_f32_16x16x32_bf16 v[36:39], v[144:147], v[174:177], v[36:39]
	v_mfma_f32_16x16x32_bf16 v[32:35], v[148:151], v[174:177], v[32:35]
	v_mfma_f32_16x16x32_bf16 v[20:23], v[144:147], v[196:199], v[20:23]
	v_mfma_f32_16x16x32_bf16 v[16:19], v[148:151], v[196:199], v[16:19]
	v_mfma_f32_16x16x32_bf16 v[4:7], v[144:147], v[200:203], v[4:7]
	v_mfma_f32_16x16x32_bf16 v[0:3], v[148:151], v[200:203], v[0:3]
	v_mfma_f32_16x16x32_bf16 v[52:55], v[152:155], v[178:181], v[52:55]
	v_mfma_f32_16x16x32_bf16 v[48:51], v[156:159], v[178:181], v[48:51]
	v_mfma_f32_16x16x32_bf16 v[36:39], v[152:155], v[192:195], v[36:39]
	v_mfma_f32_16x16x32_bf16 v[32:35], v[156:159], v[192:195], v[32:35]
	v_mfma_f32_16x16x32_bf16 v[20:23], v[152:155], v[204:207], v[20:23]
	v_mfma_f32_16x16x32_bf16 v[16:19], v[156:159], v[204:207], v[16:19]
	v_mfma_f32_16x16x32_bf16 v[4:7], v[152:155], v[208:211], v[4:7]
	v_mfma_f32_16x16x32_bf16 v[0:3], v[156:159], v[208:211], v[0:3]
	s_setprio 0
	s_barrier
	s_add_i32 s57, s57, 2
	s_add_u32 s55, s55, 0x100
	s_addc_u32 s56, s56, 0
	s_add_u32 s12, s12, 0x100
	s_addc_u32 s13, s13, 0
	s_cmp_gt_u32 s57, 29
	s_cbranch_scc0 .LBB0_1104
	v_readlane_b32 s12, v253, 13
	v_readlane_b32 s13, v253, 14
	s_and_b64 vcc, exec, s[12:13]
	s_cbranch_vccz .LBB0_1107
	s_barrier

; #define PG8_STAGE(bufoff, gbase, voff) do { _Pragma("unroll") for (int _i = 0; _i < 2; ++_i) \
;         dma16((const char*)(gbase), (voff)[_i], ldsb + (bufoff) + ldsw + _i * 8192); } while (0)
; #define PG8_LDA(dst, b, h) do { const int a1_ = opqv(aoff0) ^ 64; _Pragma("unroll") for (int m = 0; m < 4; ++m) { dst[m][0] = *(const LAS bf16x8*)(lds + PG8_SA(b, h) + aoff0 + m * 2048); dst[m][1] = *(const LAS bf16x8*)(lds + PG8_SA(b, h) + a1_ + m * 2048); } } while (0)
; #define PG8_LDB(dst, b, h) do { const int b1_ = opqv(boff0) ^ 64; _Pragma("unroll") for (int n = 0; n < 2; ++n) { dst[n][0] = *(const LAS bf16x8*)(lds + PG8_SB(b, h) + boff0 + n * 2048); dst[n][1] = *(const LAS bf16x8*)(lds + PG8_SB(b, h) + b1_ + n * 2048); } } while (0)
; #define PG8_MMA(ai, bj, At, Bt) do { __builtin_amdgcn_s_setprio(1); _Pragma("unroll") for (int m = 0; m < 4; ++m) _Pragma("unroll") for (int n = 0; n < 2; ++n) _Pragma("unroll") for (int k = 0; k < 2; ++k) \
;         acc[ai][bj][m][n] = __builtin_amdgcn_mfma_f32_16x16x32_bf16(Bt[n][k], At[m][k], acc[ai][bj][m][n], 0, 0, 0); __builtin_amdgcn_s_setprio(0); } while (0)
; #define PG8_WAIT_V(n) asm volatile("s_waitcnt vmcnt(" #n ")" ::: "memory")
; #define PG8_WAIT_L(n) asm volatile("s_waitcnt lgkmcnt(" #n ")" ::: "memory")
; #define PG8_BAR __builtin_amdgcn_s_barrier()
; #define PG8_SCHED __builtin_amdgcn_sched_barrier(0)
; template <class Epi>
; __device__ __forceinline__ void gemm_phase(LAS unsigned char* lds, const Gemm g, const StaticOrder& S, const Epi& E, int wave_) {
;     ...
;         for (int t = 0; t < nt; t += 2) {
;             const bool last = (t == nt - 2);
;             const char* a1 = cA + (size_t)(t + 1) * kstep;
;             const char* a2 = last ? nA : cA + (size_t)(t + 2) * kstep; const char* b2 = last ? nB : cB + (size_t)(t + 2) * kstep;
;             const char* a3 = a2 + kstep; const char* b3 = b2 + kstep;
;             PG8_STAGE(PG8_SA(1, 1), a1 + hstepA, voffA); PG8_LDB(B0, 0, 0); PG8_LDB(B1, 0, 1); PG8_SCHED; PG8_LDA(At, 0, 0);
;             PG8_WAIT_V(8); PG8_WAIT_L(0); PG8_BAR; PG8_MMA(0, 0, At, B0); PG8_MMA(0, 1, At, B1); PG8_BAR; PG8_SCHED;
;             PG8_STAGE(PG8_SB(0, 0), b2, voffB); PG8_STAGE(PG8_SB(0, 1), b2 + hstepB, voffB); PG8_STAGE(PG8_SA(0, 0), a2, voffA); PG8_LDA(At, 0, 1);
.LBB0_1322:
	s_add_u32 s36, s12, 0xfff80080
	s_addc_u32 s37, s13, -1
	s_cmp_eq_u32 s57, 28
	s_cselect_b32 s44, s17, s36
	s_cselect_b32 s45, s16, s37
	s_cselect_b32 s40, s25, s55
	s_cselect_b32 s41, s19, s56
	s_add_u32 s36, s44, 0x80
	v_mov_b32_e32 v128, v178
	s_addc_u32 s37, s45, 0
	v_add_u32_e32 v132, s23, v178
	v_xad_u32 v140, v128, 64, s23
	v_mov_b32_e32 v144, v178
	s_add_i32 s60, 0, 0x14000
	ds_read_b128 v[128:131], v132
	ds_read_b128 v[132:135], v132 offset:2048
	ds_read_b128 v[136:139], v140
	ds_read_b128 v[140:143], v140 offset:2048
	v_add_u32_e32 v148, s60, v178
	v_xad_u32 v156, v144, 64, s60
	ds_read_b128 v[144:147], v148
	ds_read_b128 v[148:151], v148 offset:2048
	ds_read_b128 v[152:155], v156
	ds_read_b128 v[156:159], v156 offset:2048
	v_mov_b32_e32 v160, v177
	v_add_u32_e32 v169, 0, v177
	v_xad_u32 v168, v160, 64, 0
	ds_read_b128 v[160:163], v169
	ds_read_b128 v[164:167], v169 offset:2048
	ds_read_b128 v[180:183], v168
	ds_read_b128 v[192:195], v168 offset:2048
	ds_read_b128 v[196:199], v169 offset:4096
	ds_read_b128 v[200:203], v169 offset:6144
	ds_read_b128 v[204:207], v168 offset:4096
	ds_read_b128 v[208:211], v168 offset:6144
	s_mov_b32 m0, s14
	s_nop 0
	global_load_lds_dwordx4 v172, s[12:13]
	s_mov_b32 m0, s15
	s_nop 0
	global_load_lds_dwordx4 v174, s[12:13]
	s_waitcnt vmcnt(8)
	s_waitcnt lgkmcnt(0)
	s_barrier
	s_setprio 1
	v_mfma_f32_16x16x32_bf16 v[124:127], v[128:131], v[160:163], v[124:127]
	v_mfma_f32_16x16x32_bf16 v[120:123], v[132:135], v[160:163], v[120:123]
	v_mfma_f32_16x16x32_bf16 v[108:111], v[128:131], v[164:167], v[108:111]
	v_mfma_f32_16x16x32_bf16 v[104:107], v[132:135], v[164:167], v[104:107]
	v_mfma_f32_16x16x32_bf16 v[92:95], v[128:131], v[196:199], v[92:95]
	v_mfma_f32_16x16x32_bf16 v[88:91], v[132:135], v[196:199], v[88:91]
	v_mfma_f32_16x16x32_bf16 v[76:79], v[128:131], v[200:203], v[76:79]
	v_mfma_f32_16x16x32_bf16 v[72:75], v[132:135], v[200:203], v[72:75]
	v_mfma_f32_16x16x32_bf16 v[124:127], v[136:139], v[180:183], v[124:127]
	v_mfma_f32_16x16x32_bf16 v[120:123], v[140:143], v[180:183], v[120:123]
	v_mfma_f32_16x16x32_bf16 v[108:111], v[136:139], v[192:195], v[108:111]
	v_mfma_f32_16x16x32_bf16 v[104:107], v[140:143], v[192:195], v[104:107]
	v_mfma_f32_16x16x32_bf16 v[92:95], v[136:139], v[204:207], v[92:95]
	v_mfma_f32_16x16x32_bf16 v[88:91], v[140:143], v[204:207], v[88:91]
	v_mfma_f32_16x16x32_bf16 v[76:79], v[136:139], v[208:211], v[76:79]
	v_mfma_f32_16x16x32_bf16 v[72:75], v[140:143], v[208:211], v[72:75]
	v_mfma_f32_16x16x32_bf16 v[116:119], v[144:147], v[160:163], v[116:119]
	v_mfma_f32_16x16x32_bf16 v[112:115], v[148:151], v[160:163], v[112:115]
	v_mfma_f32_16x16x32_bf16 v[100:103], v[144:147], v[164:167], v[100:103]
	v_mfma_f32_16x16x32_bf16 v[96:99], v[148:151], v[164:167], v[96:99]
	v_mfma_f32_16x16x32_bf16 v[84:87], v[144:147], v[196:199], v[84:87]
	v_mfma_f32_16x16x32_bf16 v[80:83], v[148:151], v[196:199], v[80:83]
	v_mfma_f32_16x16x32_bf16 v[68:71], v[144:147], v[200:203], v[68:71]
	v_mfma_f32_16x16x32_bf16 v[64:67], v[148:151], v[200:203], v[64:67]
	v_mfma_f32_16x16x32_bf16 v[116:119], v[152:155], v[180:183], v[116:119]
	v_mfma_f32_16x16x32_bf16 v[112:115], v[156:159], v[180:183], v[112:115]
	v_mfma_f32_16x16x32_bf16 v[100:103], v[152:155], v[192:195], v[100:103]
	v_mfma_f32_16x16x32_bf16 v[96:99], v[156:159], v[192:195], v[96:99]
	v_mfma_f32_16x16x32_bf16 v[84:87], v[152:155], v[204:207], v[84:87]
	v_mfma_f32_16x16x32_bf16 v[80:83], v[156:159], v[204:207], v[80:83]
	v_mfma_f32_16x16x32_bf16 v[68:71], v[152:155], v[208:211], v[68:71]
	v_mfma_f32_16x16x32_bf16 v[64:67], v[156:159], v[208:211], v[64:67]
	s_setprio 0
	s_barrier
	v_mov_b32_e32 v160, v177
	s_add_u32 s60, s40, 0x80000
	s_addc_u32 s61, s41, 0
	s_nop 0
	s_nop 0
	s_nop 0
	v_xad_u32 v168, v160, 64, 0
	ds_read_b128 v[160:163], v169 offset:16384
	ds_read_b128 v[164:167], v169 offset:18432
	ds_read_b128 v[180:183], v168 offset:16384
	ds_read_b128 v[192:195], v168 offset:18432
	ds_read_b128 v[196:199], v169 offset:20480
	ds_read_b128 v[200:203], v169 offset:22528
	ds_read_b128 v[204:207], v168 offset:20480
	ds_read_b128 v[208:211], v168 offset:22528
	s_mov_b32 m0, s80
	s_nop 0
	global_load_lds_dwordx4 v173, s[40:41]
	s_mov_b32 m0, s81
	s_nop 0
	global_load_lds_dwordx4 v175, s[40:41]
	s_mov_b32 m0, s29
	s_nop 0
	global_load_lds_dwordx4 v173, s[60:61]
	s_mov_b32 m0, s88
	s_nop 0
	global_load_lds_dwordx4 v175, s[60:61]
	s_mov_b32 m0, s76
	s_nop 0
	global_load_lds_dwordx4 v172, s[44:45]
	s_mov_b32 m0, s89
	s_nop 0
	global_load_lds_dwordx4 v174, s[44:45]
	s_waitcnt vmcnt(8)
	s_waitcnt lgkmcnt(0)
	s_barrier
; #define PG8_STAGE(bufoff, gbase, voff) do { _Pragma("unroll") for (int _i = 0; _i < 2; ++_i) \
;         dma16((const char*)(gbase), (voff)[_i], ldsb + (bufoff) + ldsw + _i * 8192); } while (0)
; #define PG8_LDA(dst, b, h) do { const int a1_ = opqv(aoff0) ^ 64; _Pragma("unroll") for (int m = 0; m < 4; ++m) { dst[m][0] = *(const LAS bf16x8*)(lds + PG8_SA(b, h) + aoff0 + m * 2048); dst[m][1] = *(const LAS bf16x8*)(lds + PG8_SA(b, h) + a1_ + m * 2048); } } while (0)
; #define PG8_LDB(dst, b, h) do { const int b1_ = opqv(boff0) ^ 64; _Pragma("unroll") for (int n = 0; n < 2; ++n) { dst[n][0] = *(const LAS bf16x8*)(lds + PG8_SB(b, h) + boff0 + n * 2048); dst[n][1] = *(const LAS bf16x8*)(lds + PG8_SB(b, h) + b1_ + n * 2048); } } while (0)
; #define PG8_MMA(ai, bj, At, Bt) do { __builtin_amdgcn_s_setprio(1); _Pragma("unroll") for (int m = 0; m < 4; ++m) _Pragma("unroll") for (int n = 0; n < 2; ++n) _Pragma("unroll") for (int k = 0; k < 2; ++k) \
;         acc[ai][bj][m][n] = __builtin_amdgcn_mfma_f32_16x16x32_bf16(Bt[n][k], At[m][k], acc[ai][bj][m][n], 0, 0, 0); __builtin_amdgcn_s_setprio(0); } while (0)
; #define PG8_WAIT_V(n) asm volatile("s_waitcnt vmcnt(" #n ")" ::: "memory")
; #define PG8_WAIT_L(n) asm volatile("s_waitcnt lgkmcnt(" #n ")" ::: "memory")
; #define PG8_BAR __builtin_amdgcn_s_barrier()
; #define PG8_SCHED __builtin_amdgcn_sched_barrier(0)
; template <class Epi>
; __device__ __forceinline__ void gemm_phase(LAS unsigned char* lds, const Gemm g, const StaticOrder& S, const Epi& E, int wave_) {
;     ...
;             PG8_WAIT_V(8); PG8_WAIT_L(0); PG8_BAR; PG8_MMA(1, 0, At, B0); PG8_MMA(1, 1, At, B1); PG8_BAR; PG8_SCHED;
;             PG8_STAGE(PG8_SA(0, 1), a2 + hstepA, voffA); PG8_LDB(B0, 1, 0); PG8_LDB(B1, 1, 1); PG8_SCHED; PG8_LDA(At, 1, 0);
;             PG8_WAIT_V(8); PG8_WAIT_L(0); PG8_BAR; PG8_MMA(0, 0, At, B0); PG8_MMA(0, 1, At, B1); PG8_BAR; PG8_SCHED;
	s_setprio 1
	v_mfma_f32_16x16x32_bf16 v[60:63], v[128:131], v[160:163], v[60:63]
	v_mfma_f32_16x16x32_bf16 v[56:59], v[132:135], v[160:163], v[56:59]
	v_mfma_f32_16x16x32_bf16 v[44:47], v[128:131], v[164:167], v[44:47]
	v_mfma_f32_16x16x32_bf16 v[40:43], v[132:135], v[164:167], v[40:43]
	v_mfma_f32_16x16x32_bf16 v[28:31], v[128:131], v[196:199], v[28:31]
	v_mfma_f32_16x16x32_bf16 v[24:27], v[132:135], v[196:199], v[24:27]
	v_mfma_f32_16x16x32_bf16 v[12:15], v[128:131], v[200:203], v[12:15]
	v_mfma_f32_16x16x32_bf16 v[8:11], v[132:135], v[200:203], v[8:11]
	v_mfma_f32_16x16x32_bf16 v[60:63], v[136:139], v[180:183], v[60:63]
	v_mfma_f32_16x16x32_bf16 v[56:59], v[140:143], v[180:183], v[56:59]
	v_mfma_f32_16x16x32_bf16 v[44:47], v[136:139], v[192:195], v[44:47]
	v_mfma_f32_16x16x32_bf16 v[40:43], v[140:143], v[192:195], v[40:43]
	v_mfma_f32_16x16x32_bf16 v[28:31], v[136:139], v[204:207], v[28:31]
	v_mfma_f32_16x16x32_bf16 v[24:27], v[140:143], v[204:207], v[24:27]
	v_mfma_f32_16x16x32_bf16 v[12:15], v[136:139], v[208:211], v[12:15]
	v_mfma_f32_16x16x32_bf16 v[8:11], v[140:143], v[208:211], v[8:11]
	v_mfma_f32_16x16x32_bf16 v[52:55], v[144:147], v[160:163], v[52:55]
	v_mfma_f32_16x16x32_bf16 v[48:51], v[148:151], v[160:163], v[48:51]
	v_mfma_f32_16x16x32_bf16 v[36:39], v[144:147], v[164:167], v[36:39]
	v_mfma_f32_16x16x32_bf16 v[32:35], v[148:151], v[164:167], v[32:35]
	v_mfma_f32_16x16x32_bf16 v[20:23], v[144:147], v[196:199], v[20:23]
	v_mfma_f32_16x16x32_bf16 v[16:19], v[148:151], v[196:199], v[16:19]
	v_mfma_f32_16x16x32_bf16 v[4:7], v[144:147], v[200:203], v[4:7]
	v_mfma_f32_16x16x32_bf16 v[0:3], v[148:151], v[200:203], v[0:3]
	v_mfma_f32_16x16x32_bf16 v[52:55], v[152:155], v[180:183], v[52:55]
	v_mfma_f32_16x16x32_bf16 v[48:51], v[156:159], v[180:183], v[48:51]
	v_mfma_f32_16x16x32_bf16 v[36:39], v[152:155], v[192:195], v[36:39]
	v_mfma_f32_16x16x32_bf16 v[32:35], v[156:159], v[192:195], v[32:35]
	v_mfma_f32_16x16x32_bf16 v[20:23], v[152:155], v[204:207], v[20:23]
	v_mfma_f32_16x16x32_bf16 v[16:19], v[156:159], v[204:207], v[16:19]
	v_mfma_f32_16x16x32_bf16 v[4:7], v[152:155], v[208:211], v[4:7]
	v_mfma_f32_16x16x32_bf16 v[0:3], v[156:159], v[208:211], v[0:3]
	s_setprio 0
	s_barrier
	s_add_u32 s44, s44, 0x80000
	s_addc_u32 s45, s45, 0
	s_mov_b32 m0, s1
	s_nop 0
	global_load_lds_dwordx4 v172, s[44:45]
	v_mov_b32_e32 v128, v178
	s_mov_b32 m0, s69
	s_nop 0
	global_load_lds_dwordx4 v174, s[44:45]
	v_add_u32_e32 v132, s34, v178
	v_xad_u32 v140, v128, 64, s34
	v_mov_b32_e32 v144, v178
	s_add_i32 s44, 0, 0x1c000
	ds_read_b128 v[128:131], v132
	ds_read_b128 v[132:135], v132 offset:2048
	ds_read_b128 v[136:139], v140
	ds_read_b128 v[140:143], v140 offset:2048
	v_add_u32_e32 v148, s44, v178
	v_xad_u32 v156, v144, 64, s44
	ds_read_b128 v[144:147], v148
	ds_read_b128 v[148:151], v148 offset:2048
	ds_read_b128 v[152:155], v156
	ds_read_b128 v[156:159], v156 offset:2048
	v_mov_b32_e32 v160, v177
	s_nop 0
	v_xad_u32 v168, v160, 64, 0
	ds_read_b128 v[160:163], v169 offset:32768
	ds_read_b128 v[164:167], v169 offset:34816
	ds_read_b128 v[180:183], v168 offset:32768
	ds_read_b128 v[192:195], v168 offset:34816
	ds_read_b128 v[196:199], v169 offset:36864
	ds_read_b128 v[200:203], v169 offset:38912
	ds_read_b128 v[204:207], v168 offset:36864
	ds_read_b128 v[208:211], v168 offset:38912
	s_waitcnt vmcnt(8)
	s_waitcnt lgkmcnt(0)
	s_barrier
	s_setprio 1
	v_mfma_f32_16x16x32_bf16 v[124:127], v[128:131], v[160:163], v[124:127]
	v_mfma_f32_16x16x32_bf16 v[120:123], v[132:135], v[160:163], v[120:123]
	v_mfma_f32_16x16x32_bf16 v[108:111], v[128:131], v[164:167], v[108:111]
	v_mfma_f32_16x16x32_bf16 v[104:107], v[132:135], v[164:167], v[104:107]
	v_mfma_f32_16x16x32_bf16 v[92:95], v[128:131], v[196:199], v[92:95]
	v_mfma_f32_16x16x32_bf16 v[88:91], v[132:135], v[196:199], v[88:91]
	v_mfma_f32_16x16x32_bf16 v[76:79], v[128:131], v[200:203], v[76:79]
	v_mfma_f32_16x16x32_bf16 v[72:75], v[132:135], v[200:203], v[72:75]
	v_mfma_f32_16x16x32_bf16 v[124:127], v[136:139], v[180:183], v[124:127]
	v_mfma_f32_16x16x32_bf16 v[120:123], v[140:143], v[180:183], v[120:123]
	v_mfma_f32_16x16x32_bf16 v[108:111], v[136:139], v[192:195], v[108:111]
	v_mfma_f32_16x16x32_bf16 v[104:107], v[140:143], v[192:195], v[104:107]
	v_mfma_f32_16x16x32_bf16 v[92:95], v[136:139], v[204:207], v[92:95]
	v_mfma_f32_16x16x32_bf16 v[88:91], v[140:143], v[204:207], v[88:91]
	v_mfma_f32_16x16x32_bf16 v[76:79], v[136:139], v[208:211], v[76:79]
	v_mfma_f32_16x16x32_bf16 v[72:75], v[140:143], v[208:211], v[72:75]
	v_mfma_f32_16x16x32_bf16 v[116:119], v[144:147], v[160:163], v[116:119]
	s_add_u32 s44, s40, 0x80
	s_addc_u32 s45, s41, 0
	v_mfma_f32_16x16x32_bf16 v[112:115], v[148:151], v[160:163], v[112:115]
	v_mfma_f32_16x16x32_bf16 v[100:103], v[144:147], v[164:167], v[100:103]
	v_mfma_f32_16x16x32_bf16 v[96:99], v[148:151], v[164:167], v[96:99]
	v_mfma_f32_16x16x32_bf16 v[84:87], v[144:147], v[196:199], v[84:87]
	v_mfma_f32_16x16x32_bf16 v[80:83], v[148:151], v[196:199], v[80:83]
	v_mfma_f32_16x16x32_bf16 v[68:71], v[144:147], v[200:203], v[68:71]
	v_mfma_f32_16x16x32_bf16 v[64:67], v[148:151], v[200:203], v[64:67]
	v_mfma_f32_16x16x32_bf16 v[116:119], v[152:155], v[180:183], v[116:119]
	v_mfma_f32_16x16x32_bf16 v[112:115], v[156:159], v[180:183], v[112:115]
	v_mfma_f32_16x16x32_bf16 v[100:103], v[152:155], v[192:195], v[100:103]
	v_mfma_f32_16x16x32_bf16 v[96:99], v[156:159], v[192:195], v[96:99]
	v_mfma_f32_16x16x32_bf16 v[84:87], v[152:155], v[204:207], v[84:87]
	v_mfma_f32_16x16x32_bf16 v[80:83], v[156:159], v[204:207], v[80:83]
	v_mfma_f32_16x16x32_bf16 v[68:71], v[152:155], v[208:211], v[68:71]
	v_mfma_f32_16x16x32_bf16 v[64:67], v[156:159], v[208:211], v[64:67]
	s_setprio 0
	s_barrier
; #define PG8_STAGE(bufoff, gbase, voff) do { _Pragma("unroll") for (int _i = 0; _i < 2; ++_i) \
;         dma16((const char*)(gbase), (voff)[_i], ldsb + (bufoff) + ldsw + _i * 8192); } while (0)
; #define PG8_LDA(dst, b, h) do { const int a1_ = opqv(aoff0) ^ 64; _Pragma("unroll") for (int m = 0; m < 4; ++m) { dst[m][0] = *(const LAS bf16x8*)(lds + PG8_SA(b, h) + aoff0 + m * 2048); dst[m][1] = *(const LAS bf16x8*)(lds + PG8_SA(b, h) + a1_ + m * 2048); } } while (0)
; #define PG8_MMA(ai, bj, At, Bt) do { __builtin_amdgcn_s_setprio(1); _Pragma("unroll") for (int m = 0; m < 4; ++m) _Pragma("unroll") for (int n = 0; n < 2; ++n) _Pragma("unroll") for (int k = 0; k < 2; ++k) \
;         acc[ai][bj][m][n] = __builtin_amdgcn_mfma_f32_16x16x32_bf16(Bt[n][k], At[m][k], acc[ai][bj][m][n], 0, 0, 0); __builtin_amdgcn_s_setprio(0); } while (0)
; #define PG8_WAIT_V(n) asm volatile("s_waitcnt vmcnt(" #n ")" ::: "memory")
; #define PG8_WAIT_L(n) asm volatile("s_waitcnt lgkmcnt(" #n ")" ::: "memory")
; #define PG8_BAR __builtin_amdgcn_s_barrier()
; #define PG8_SCHED __builtin_amdgcn_sched_barrier(0)
; template <class Epi>
; __device__ __forceinline__ void gemm_phase(LAS unsigned char* lds, const Gemm g, const StaticOrder& S, const Epi& E, int wave_) {
;     ...
;             PG8_STAGE(PG8_SB(1, 0), b3, voffB); PG8_STAGE(PG8_SB(1, 1), b3 + hstepB, voffB); PG8_STAGE(PG8_SA(1, 0), a3, voffA); PG8_LDA(At, 1, 1);
;             PG8_WAIT_V(8); PG8_WAIT_L(0); PG8_BAR; PG8_MMA(1, 0, At, B0); PG8_MMA(1, 1, At, B1); PG8_BAR; PG8_SCHED;
;         }
;         if (wr == 0) PG8_BAR;
	s_add_u32 s40, s40, 0x80080
	s_addc_u32 s41, s41, 0
	v_mov_b32_e32 v160, v177
	s_nop 0
	s_nop 0
	v_xad_u32 v168, v160, 64, 0
	ds_read_b128 v[160:163], v169 offset:49152
	ds_read_b128 v[164:167], v169 offset:51200
	ds_read_b128 v[180:183], v168 offset:49152
	ds_read_b128 v[192:195], v168 offset:51200
	ds_read_b128 v[196:199], v169 offset:53248
	ds_read_b128 v[200:203], v169 offset:55296
	ds_read_b128 v[204:207], v168 offset:53248
	ds_read_b128 v[208:211], v168 offset:55296
	s_mov_b32 m0, s35
	s_nop 0
	global_load_lds_dwordx4 v173, s[44:45]
	s_mov_b32 m0, s33
	s_nop 0
	global_load_lds_dwordx4 v175, s[44:45]
	s_mov_b32 m0, s77
	s_nop 0
	global_load_lds_dwordx4 v173, s[40:41]
	s_mov_b32 m0, s3
	s_nop 0
	global_load_lds_dwordx4 v175, s[40:41]
	s_mov_b32 m0, s22
	s_nop 0
	global_load_lds_dwordx4 v172, s[36:37]
	s_mov_b32 m0, s2
	s_nop 0
	global_load_lds_dwordx4 v174, s[36:37]
	s_waitcnt vmcnt(8)
	s_waitcnt lgkmcnt(0)
	s_barrier
	s_setprio 1
	v_mfma_f32_16x16x32_bf16 v[60:63], v[128:131], v[160:163], v[60:63]
	v_mfma_f32_16x16x32_bf16 v[56:59], v[132:135], v[160:163], v[56:59]
	v_mfma_f32_16x16x32_bf16 v[44:47], v[128:131], v[164:167], v[44:47]
	v_mfma_f32_16x16x32_bf16 v[40:43], v[132:135], v[164:167], v[40:43]
	v_mfma_f32_16x16x32_bf16 v[28:31], v[128:131], v[196:199], v[28:31]
	v_mfma_f32_16x16x32_bf16 v[24:27], v[132:135], v[196:199], v[24:27]
	v_mfma_f32_16x16x32_bf16 v[12:15], v[128:131], v[200:203], v[12:15]
	v_mfma_f32_16x16x32_bf16 v[8:11], v[132:135], v[200:203], v[8:11]
	v_mfma_f32_16x16x32_bf16 v[60:63], v[136:139], v[180:183], v[60:63]
	v_mfma_f32_16x16x32_bf16 v[56:59], v[140:143], v[180:183], v[56:59]
	v_mfma_f32_16x16x32_bf16 v[44:47], v[136:139], v[192:195], v[44:47]
	v_mfma_f32_16x16x32_bf16 v[40:43], v[140:143], v[192:195], v[40:43]
	v_mfma_f32_16x16x32_bf16 v[28:31], v[136:139], v[204:207], v[28:31]
	v_mfma_f32_16x16x32_bf16 v[24:27], v[140:143], v[204:207], v[24:27]
	v_mfma_f32_16x16x32_bf16 v[12:15], v[136:139], v[208:211], v[12:15]
	v_mfma_f32_16x16x32_bf16 v[8:11], v[140:143], v[208:211], v[8:11]
	v_mfma_f32_16x16x32_bf16 v[52:55], v[144:147], v[160:163], v[52:55]
	v_mfma_f32_16x16x32_bf16 v[48:51], v[148:151], v[160:163], v[48:51]
	v_mfma_f32_16x16x32_bf16 v[36:39], v[144:147], v[164:167], v[36:39]
	v_mfma_f32_16x16x32_bf16 v[32:35], v[148:151], v[164:167], v[32:35]
	v_mfma_f32_16x16x32_bf16 v[20:23], v[144:147], v[196:199], v[20:23]
	v_mfma_f32_16x16x32_bf16 v[16:19], v[148:151], v[196:199], v[16:19]
	v_mfma_f32_16x16x32_bf16 v[4:7], v[144:147], v[200:203], v[4:7]
	v_mfma_f32_16x16x32_bf16 v[0:3], v[148:151], v[200:203], v[0:3]
	v_mfma_f32_16x16x32_bf16 v[52:55], v[152:155], v[180:183], v[52:55]
	v_mfma_f32_16x16x32_bf16 v[48:51], v[156:159], v[180:183], v[48:51]
	v_mfma_f32_16x16x32_bf16 v[36:39], v[152:155], v[192:195], v[36:39]
	v_mfma_f32_16x16x32_bf16 v[32:35], v[156:159], v[192:195], v[32:35]
	v_mfma_f32_16x16x32_bf16 v[20:23], v[152:155], v[204:207], v[20:23]
	v_mfma_f32_16x16x32_bf16 v[16:19], v[156:159], v[204:207], v[16:19]
	v_mfma_f32_16x16x32_bf16 v[4:7], v[152:155], v[208:211], v[4:7]
	v_mfma_f32_16x16x32_bf16 v[0:3], v[156:159], v[208:211], v[0:3]
	s_setprio 0
	s_barrier
	s_add_i32 s57, s57, 2
	s_add_u32 s55, s55, 0x100
	s_addc_u32 s56, s56, 0
	s_add_u32 s12, s12, 0x100
	s_addc_u32 s13, s13, 0
	s_cmp_gt_u32 s57, 29
	s_cbranch_scc0 .LBB0_1322
	v_readlane_b32 s12, v253, 13
	v_readlane_b32 s13, v253, 14
	s_and_b64 vcc, exec, s[12:13]
	s_cbranch_vccz .LBB0_1325
	s_barrier

; #define PG8_STAGE(bufoff, gbase, voff) do { _Pragma("unroll") for (int _i = 0; _i < 2; ++_i) \
;         dma16((const char*)(gbase), (voff)[_i], ldsb + (bufoff) + ldsw + _i * 8192); } while (0)
; #define PG8_LDA(dst, b, h) do { const int a1_ = opqv(aoff0) ^ 64; _Pragma("unroll") for (int m = 0; m < 4; ++m) { dst[m][0] = *(const LAS bf16x8*)(lds + PG8_SA(b, h) + aoff0 + m * 2048); dst[m][1] = *(const LAS bf16x8*)(lds + PG8_SA(b, h) + a1_ + m * 2048); } } while (0)
; #define PG8_LDB(dst, b, h) do { const int b1_ = opqv(boff0) ^ 64; _Pragma("unroll") for (int n = 0; n < 2; ++n) { dst[n][0] = *(const LAS bf16x8*)(lds + PG8_SB(b, h) + boff0 + n * 2048); dst[n][1] = *(const LAS bf16x8*)(lds + PG8_SB(b, h) + b1_ + n * 2048); } } while (0)
; #define PG8_MMA(ai, bj, At, Bt) do { __builtin_amdgcn_s_setprio(1); _Pragma("unroll") for (int m = 0; m < 4; ++m) _Pragma("unroll") for (int n = 0; n < 2; ++n) _Pragma("unroll") for (int k = 0; k < 2; ++k) \
;         acc[ai][bj][m][n] = __builtin_amdgcn_mfma_f32_16x16x32_bf16(Bt[n][k], At[m][k], acc[ai][bj][m][n], 0, 0, 0); __builtin_amdgcn_s_setprio(0); } while (0)
; #define PG8_WAIT_V(n) asm volatile("s_waitcnt vmcnt(" #n ")" ::: "memory")
; #define PG8_WAIT_L(n) asm volatile("s_waitcnt lgkmcnt(" #n ")" ::: "memory")
; #define PG8_BAR __builtin_amdgcn_s_barrier()
; #define PG8_SCHED __builtin_amdgcn_sched_barrier(0)
; template <class Epi>
; __device__ __forceinline__ void gemm_phase(LAS unsigned char* lds, const Gemm g, const StaticOrder& S, const Epi& E, int wave_) {
;     ...
;         for (int t = 0; t < nt; t += 2) {
;             const bool last = (t == nt - 2);
;             const char* a1 = cA + (size_t)(t + 1) * kstep;
;             const char* a2 = last ? nA : cA + (size_t)(t + 2) * kstep; const char* b2 = last ? nB : cB + (size_t)(t + 2) * kstep;
;             const char* a3 = a2 + kstep; const char* b3 = b2 + kstep;
;             PG8_STAGE(PG8_SA(1, 1), a1 + hstepA, voffA); PG8_LDB(B0, 0, 0); PG8_LDB(B1, 0, 1); PG8_SCHED; PG8_LDA(At, 0, 0);
;             PG8_WAIT_V(8); PG8_WAIT_L(0); PG8_BAR; PG8_MMA(0, 0, At, B0); PG8_MMA(0, 1, At, B1); PG8_BAR; PG8_SCHED;
;             PG8_STAGE(PG8_SB(0, 0), b2, voffB); PG8_STAGE(PG8_SB(0, 1), b2 + hstepB, voffB); PG8_STAGE(PG8_SA(0, 0), a2, voffA); PG8_LDA(At, 0, 1);
.LBB0_1342:
	s_add_u32 s46, s26, s30
	s_addc_u32 s47, s27, s31
	s_add_u32 s44, s46, 0x100
	s_addc_u32 s45, s47, 0
	s_and_b64 s[40:41], s[36:37], exec
	s_cselect_b32 s45, s9, s45
	s_cselect_b32 s44, s61, s44
	s_add_u32 s30, s24, s30
	s_addc_u32 s31, s25, s31
	s_add_u32 s40, s30, 0x100
	s_addc_u32 s41, s31, 0
	s_add_u32 s30, s44, 0x80
	s_addc_u32 s31, s45, 0
	s_add_u32 s56, s46, 0x10080
	s_addc_u32 s57, s47, 0
	s_mov_b32 m0, s14
	s_nop 0
	global_load_lds_dwordx4 v130, s[56:57]
	v_mov_b32_e32 v128, v136
	s_mov_b32 m0, s15
	s_nop 0
	global_load_lds_dwordx4 v132, s[56:57]
	s_and_b64 s[36:37], s[36:37], exec
	v_xad_u32 v128, v128, 64, s23
	v_add_u32_e32 v129, s23, v136
	s_cselect_b32 s49, s7, s41
	s_cselect_b32 s48, s62, s40
	s_add_i32 s37, 0, 0x14000
	ds_read_b128 v[138:141], v129
	ds_read_b128 v[142:145], v129 offset:2048
	ds_read_b128 v[146:149], v128
	ds_read_b128 v[150:153], v128 offset:2048
	v_mov_b32_e32 v128, v136
	v_add_u32_e32 v129, s37, v136
	s_add_u32 s46, s48, 0x10000
	v_xad_u32 v128, v128, 64, s37
	ds_read_b128 v[154:157], v129
	ds_read_b128 v[158:161], v129 offset:2048
	ds_read_b128 v[162:165], v128
	ds_read_b128 v[166:169], v128 offset:2048
	s_addc_u32 s47, s49, 0
	s_add_u32 s40, s44, 0x10000
	s_addc_u32 s41, s45, 0
	s_add_i32 s63, 0, 0x1c000
	s_add_u32 s36, s48, 0x80
	s_addc_u32 s37, s49, 0
	s_add_u32 s56, s48, 0x10080
	s_addc_u32 s57, s49, 0
	v_mov_b32_e32 v128, v135
	v_add_u32_e32 v129, 0, v135
	v_xad_u32 v128, v128, 64, 0
	ds_read_b128 v[172:175], v129
	ds_read_b128 v[176:179], v129 offset:2048
	ds_read_b128 v[180:183], v128
	ds_read_b128 v[192:195], v128 offset:2048
	ds_read_b128 v[196:199], v129 offset:4096
	ds_read_b128 v[200:203], v129 offset:6144
	ds_read_b128 v[204:207], v128 offset:4096
	ds_read_b128 v[208:211], v128 offset:6144
	s_waitcnt vmcnt(8)
	s_waitcnt lgkmcnt(0)
	s_barrier
	s_setprio 1
	v_mfma_f32_16x16x32_bf16 v[124:127], v[138:141], v[172:175], v[124:127]
	v_mfma_f32_16x16x32_bf16 v[120:123], v[142:145], v[172:175], v[120:123]
	v_mfma_f32_16x16x32_bf16 v[116:119], v[138:141], v[176:179], v[116:119]
	v_mfma_f32_16x16x32_bf16 v[108:111], v[142:145], v[176:179], v[108:111]
	v_mfma_f32_16x16x32_bf16 v[100:103], v[138:141], v[196:199], v[100:103]
	v_mfma_f32_16x16x32_bf16 v[92:95], v[142:145], v[196:199], v[92:95]
	v_mfma_f32_16x16x32_bf16 v[84:87], v[138:141], v[200:203], v[84:87]
	v_mfma_f32_16x16x32_bf16 v[76:79], v[142:145], v[200:203], v[76:79]
	v_mfma_f32_16x16x32_bf16 v[124:127], v[146:149], v[180:183], v[124:127]
	v_mfma_f32_16x16x32_bf16 v[120:123], v[150:153], v[180:183], v[120:123]
	v_mfma_f32_16x16x32_bf16 v[116:119], v[146:149], v[192:195], v[116:119]
	v_mfma_f32_16x16x32_bf16 v[108:111], v[150:153], v[192:195], v[108:111]
	v_mfma_f32_16x16x32_bf16 v[100:103], v[146:149], v[204:207], v[100:103]
	v_mfma_f32_16x16x32_bf16 v[92:95], v[150:153], v[204:207], v[92:95]
	v_mfma_f32_16x16x32_bf16 v[84:87], v[146:149], v[208:211], v[84:87]
	v_mfma_f32_16x16x32_bf16 v[76:79], v[150:153], v[208:211], v[76:79]
	v_mfma_f32_16x16x32_bf16 v[112:115], v[154:157], v[172:175], v[112:115]
	v_mfma_f32_16x16x32_bf16 v[104:107], v[158:161], v[172:175], v[104:107]
	v_mfma_f32_16x16x32_bf16 v[96:99], v[154:157], v[176:179], v[96:99]
	v_mfma_f32_16x16x32_bf16 v[88:91], v[158:161], v[176:179], v[88:91]
	v_mfma_f32_16x16x32_bf16 v[80:83], v[154:157], v[196:199], v[80:83]
	v_mfma_f32_16x16x32_bf16 v[72:75], v[158:161], v[196:199], v[72:75]
	v_mfma_f32_16x16x32_bf16 v[68:71], v[154:157], v[200:203], v[68:71]
	v_mfma_f32_16x16x32_bf16 v[64:67], v[158:161], v[200:203], v[64:67]
	v_mfma_f32_16x16x32_bf16 v[112:115], v[162:165], v[180:183], v[112:115]
	v_mfma_f32_16x16x32_bf16 v[104:107], v[166:169], v[180:183], v[104:107]
	v_mfma_f32_16x16x32_bf16 v[96:99], v[162:165], v[192:195], v[96:99]
	v_mfma_f32_16x16x32_bf16 v[88:91], v[166:169], v[192:195], v[88:91]
	v_mfma_f32_16x16x32_bf16 v[80:83], v[162:165], v[204:207], v[80:83]
	v_mfma_f32_16x16x32_bf16 v[72:75], v[166:169], v[204:207], v[72:75]
	v_mfma_f32_16x16x32_bf16 v[68:71], v[162:165], v[208:211], v[68:71]
	v_mfma_f32_16x16x32_bf16 v[64:67], v[166:169], v[208:211], v[64:67]
	s_setprio 0
	s_barrier
	v_mov_b32_e32 v128, v135
	s_nop 0
	s_nop 0
	s_nop 0
	v_xad_u32 v128, v128, 64, 0
	ds_read_b128 v[172:175], v129 offset:16384
	ds_read_b128 v[176:179], v129 offset:18432
	ds_read_b128 v[180:183], v128 offset:16384
	ds_read_b128 v[192:195], v128 offset:18432
	ds_read_b128 v[196:199], v129 offset:20480
	ds_read_b128 v[200:203], v129 offset:22528
	ds_read_b128 v[204:207], v128 offset:20480
	ds_read_b128 v[208:211], v128 offset:22528
	s_mov_b32 m0, s80
	s_nop 0
	global_load_lds_dwordx4 v131, s[48:49]
	s_mov_b32 m0, s81
	s_nop 0
	global_load_lds_dwordx4 v133, s[48:49]
	s_mov_b32 m0, s29
	s_nop 0
	global_load_lds_dwordx4 v131, s[46:47]
	s_mov_b32 m0, s88
	s_nop 0
	global_load_lds_dwordx4 v133, s[46:47]
	s_mov_b32 m0, s76
	s_nop 0
	global_load_lds_dwordx4 v130, s[44:45]
	s_mov_b32 m0, s89
	s_nop 0
	global_load_lds_dwordx4 v132, s[44:45]
	s_waitcnt vmcnt(8)
	s_waitcnt lgkmcnt(0)
	s_barrier
; #define PG8_STAGE(bufoff, gbase, voff) do { _Pragma("unroll") for (int _i = 0; _i < 2; ++_i) \
;         dma16((const char*)(gbase), (voff)[_i], ldsb + (bufoff) + ldsw + _i * 8192); } while (0)
; #define PG8_LDA(dst, b, h) do { const int a1_ = opqv(aoff0) ^ 64; _Pragma("unroll") for (int m = 0; m < 4; ++m) { dst[m][0] = *(const LAS bf16x8*)(lds + PG8_SA(b, h) + aoff0 + m * 2048); dst[m][1] = *(const LAS bf16x8*)(lds + PG8_SA(b, h) + a1_ + m * 2048); } } while (0)
; #define PG8_LDB(dst, b, h) do { const int b1_ = opqv(boff0) ^ 64; _Pragma("unroll") for (int n = 0; n < 2; ++n) { dst[n][0] = *(const LAS bf16x8*)(lds + PG8_SB(b, h) + boff0 + n * 2048); dst[n][1] = *(const LAS bf16x8*)(lds + PG8_SB(b, h) + b1_ + n * 2048); } } while (0)
; #define PG8_MMA(ai, bj, At, Bt) do { __builtin_amdgcn_s_setprio(1); _Pragma("unroll") for (int m = 0; m < 4; ++m) _Pragma("unroll") for (int n = 0; n < 2; ++n) _Pragma("unroll") for (int k = 0; k < 2; ++k) \
;         acc[ai][bj][m][n] = __builtin_amdgcn_mfma_f32_16x16x32_bf16(Bt[n][k], At[m][k], acc[ai][bj][m][n], 0, 0, 0); __builtin_amdgcn_s_setprio(0); } while (0)
; #define PG8_WAIT_V(n) asm volatile("s_waitcnt vmcnt(" #n ")" ::: "memory")
; #define PG8_WAIT_L(n) asm volatile("s_waitcnt lgkmcnt(" #n ")" ::: "memory")
; #define PG8_BAR __builtin_amdgcn_s_barrier()
; #define PG8_SCHED __builtin_amdgcn_sched_barrier(0)
; template <class Epi>
; __device__ __forceinline__ void gemm_phase(LAS unsigned char* lds, const Gemm g, const StaticOrder& S, const Epi& E, int wave_) {
;     ...
;             PG8_WAIT_V(8); PG8_WAIT_L(0); PG8_BAR; PG8_MMA(1, 0, At, B0); PG8_MMA(1, 1, At, B1); PG8_BAR; PG8_SCHED;
;             PG8_STAGE(PG8_SA(0, 1), a2 + hstepA, voffA); PG8_LDB(B0, 1, 0); PG8_LDB(B1, 1, 1); PG8_SCHED; PG8_LDA(At, 1, 0);
;             PG8_WAIT_V(8); PG8_WAIT_L(0); PG8_BAR; PG8_MMA(0, 0, At, B0); PG8_MMA(0, 1, At, B1); PG8_BAR; PG8_SCHED;
	s_setprio 1
	v_mfma_f32_16x16x32_bf16 v[60:63], v[138:141], v[172:175], v[60:63]
	v_mfma_f32_16x16x32_bf16 v[56:59], v[142:145], v[172:175], v[56:59]
	v_mfma_f32_16x16x32_bf16 v[52:55], v[138:141], v[176:179], v[52:55]
	v_mfma_f32_16x16x32_bf16 v[44:47], v[142:145], v[176:179], v[44:47]
	v_mfma_f32_16x16x32_bf16 v[36:39], v[138:141], v[196:199], v[36:39]
	v_mfma_f32_16x16x32_bf16 v[28:31], v[142:145], v[196:199], v[28:31]
	v_mfma_f32_16x16x32_bf16 v[20:23], v[138:141], v[200:203], v[20:23]
	v_mfma_f32_16x16x32_bf16 v[12:15], v[142:145], v[200:203], v[12:15]
	v_mfma_f32_16x16x32_bf16 v[60:63], v[146:149], v[180:183], v[60:63]
	v_mfma_f32_16x16x32_bf16 v[56:59], v[150:153], v[180:183], v[56:59]
	v_mfma_f32_16x16x32_bf16 v[52:55], v[146:149], v[192:195], v[52:55]
	v_mfma_f32_16x16x32_bf16 v[44:47], v[150:153], v[192:195], v[44:47]
	v_mfma_f32_16x16x32_bf16 v[36:39], v[146:149], v[204:207], v[36:39]
	v_mfma_f32_16x16x32_bf16 v[28:31], v[150:153], v[204:207], v[28:31]
	v_mfma_f32_16x16x32_bf16 v[20:23], v[146:149], v[208:211], v[20:23]
	v_mfma_f32_16x16x32_bf16 v[12:15], v[150:153], v[208:211], v[12:15]
	v_mfma_f32_16x16x32_bf16 v[48:51], v[154:157], v[172:175], v[48:51]
	v_mfma_f32_16x16x32_bf16 v[40:43], v[158:161], v[172:175], v[40:43]
	v_mfma_f32_16x16x32_bf16 v[32:35], v[154:157], v[176:179], v[32:35]
	v_mfma_f32_16x16x32_bf16 v[24:27], v[158:161], v[176:179], v[24:27]
	v_mfma_f32_16x16x32_bf16 v[16:19], v[154:157], v[196:199], v[16:19]
	v_mfma_f32_16x16x32_bf16 v[8:11], v[158:161], v[196:199], v[8:11]
	v_mfma_f32_16x16x32_bf16 v[4:7], v[154:157], v[200:203], v[4:7]
	v_mfma_f32_16x16x32_bf16 v[0:3], v[158:161], v[200:203], v[0:3]
	v_mfma_f32_16x16x32_bf16 v[48:51], v[162:165], v[180:183], v[48:51]
	v_mfma_f32_16x16x32_bf16 v[40:43], v[166:169], v[180:183], v[40:43]
	v_mfma_f32_16x16x32_bf16 v[32:35], v[162:165], v[192:195], v[32:35]
	v_mfma_f32_16x16x32_bf16 v[24:27], v[166:169], v[192:195], v[24:27]
	v_mfma_f32_16x16x32_bf16 v[16:19], v[162:165], v[204:207], v[16:19]
	v_mfma_f32_16x16x32_bf16 v[8:11], v[166:169], v[204:207], v[8:11]
	v_mfma_f32_16x16x32_bf16 v[4:7], v[162:165], v[208:211], v[4:7]
	v_mfma_f32_16x16x32_bf16 v[0:3], v[166:169], v[208:211], v[0:3]
	s_setprio 0
	s_barrier
	v_mov_b32_e32 v128, v136
	v_add_u32_e32 v142, s34, v136
	v_xad_u32 v128, v128, 64, s34
	ds_read_b128 v[138:141], v142
	ds_read_b128 v[142:145], v142 offset:2048
	ds_read_b128 v[146:149], v128
	ds_read_b128 v[150:153], v128 offset:2048
	v_mov_b32_e32 v128, v136
	v_add_u32_e32 v158, s63, v136
	v_xad_u32 v128, v128, 64, s63
	ds_read_b128 v[154:157], v158
	ds_read_b128 v[158:161], v158 offset:2048
	ds_read_b128 v[162:165], v128
	ds_read_b128 v[166:169], v128 offset:2048
	v_mov_b32_e32 v128, v135
	s_nop 0
	v_xad_u32 v128, v128, 64, 0
	ds_read_b128 v[172:175], v129 offset:32768
	ds_read_b128 v[176:179], v129 offset:34816
	ds_read_b128 v[180:183], v128 offset:32768
	ds_read_b128 v[192:195], v128 offset:34816
	ds_read_b128 v[196:199], v129 offset:36864
	ds_read_b128 v[200:203], v129 offset:38912
	ds_read_b128 v[204:207], v128 offset:36864
	ds_read_b128 v[208:211], v128 offset:38912
	s_mov_b32 m0, s1
	s_nop 0
	global_load_lds_dwordx4 v130, s[40:41]
	s_mov_b32 m0, s69
	s_nop 0
	global_load_lds_dwordx4 v132, s[40:41]
	s_waitcnt vmcnt(8)
	s_waitcnt lgkmcnt(0)
	s_barrier
	s_setprio 1
	v_mfma_f32_16x16x32_bf16 v[124:127], v[138:141], v[172:175], v[124:127]
	v_mfma_f32_16x16x32_bf16 v[120:123], v[142:145], v[172:175], v[120:123]
	v_mfma_f32_16x16x32_bf16 v[116:119], v[138:141], v[176:179], v[116:119]
	v_mfma_f32_16x16x32_bf16 v[108:111], v[142:145], v[176:179], v[108:111]
	v_mfma_f32_16x16x32_bf16 v[100:103], v[138:141], v[196:199], v[100:103]
	v_mfma_f32_16x16x32_bf16 v[92:95], v[142:145], v[196:199], v[92:95]
	v_mfma_f32_16x16x32_bf16 v[84:87], v[138:141], v[200:203], v[84:87]
	v_mfma_f32_16x16x32_bf16 v[76:79], v[142:145], v[200:203], v[76:79]
	v_mfma_f32_16x16x32_bf16 v[124:127], v[146:149], v[180:183], v[124:127]
	v_mfma_f32_16x16x32_bf16 v[120:123], v[150:153], v[180:183], v[120:123]
	v_mfma_f32_16x16x32_bf16 v[116:119], v[146:149], v[192:195], v[116:119]
	v_mfma_f32_16x16x32_bf16 v[108:111], v[150:153], v[192:195], v[108:111]
	v_mfma_f32_16x16x32_bf16 v[100:103], v[146:149], v[204:207], v[100:103]
	v_mfma_f32_16x16x32_bf16 v[92:95], v[150:153], v[204:207], v[92:95]
	v_mfma_f32_16x16x32_bf16 v[84:87], v[146:149], v[208:211], v[84:87]
	v_mfma_f32_16x16x32_bf16 v[76:79], v[150:153], v[208:211], v[76:79]
	v_mfma_f32_16x16x32_bf16 v[112:115], v[154:157], v[172:175], v[112:115]
	v_mfma_f32_16x16x32_bf16 v[104:107], v[158:161], v[172:175], v[104:107]
	v_mfma_f32_16x16x32_bf16 v[96:99], v[154:157], v[176:179], v[96:99]
	v_mfma_f32_16x16x32_bf16 v[88:91], v[158:161], v[176:179], v[88:91]
	v_mfma_f32_16x16x32_bf16 v[80:83], v[154:157], v[196:199], v[80:83]
	v_mfma_f32_16x16x32_bf16 v[72:75], v[158:161], v[196:199], v[72:75]
	v_mfma_f32_16x16x32_bf16 v[68:71], v[154:157], v[200:203], v[68:71]
	v_mfma_f32_16x16x32_bf16 v[64:67], v[158:161], v[200:203], v[64:67]
	v_mfma_f32_16x16x32_bf16 v[112:115], v[162:165], v[180:183], v[112:115]
	v_mfma_f32_16x16x32_bf16 v[104:107], v[166:169], v[180:183], v[104:107]
	v_mfma_f32_16x16x32_bf16 v[96:99], v[162:165], v[192:195], v[96:99]
	v_mfma_f32_16x16x32_bf16 v[88:91], v[166:169], v[192:195], v[88:91]
	v_mfma_f32_16x16x32_bf16 v[80:83], v[162:165], v[204:207], v[80:83]
	v_mfma_f32_16x16x32_bf16 v[72:75], v[166:169], v[204:207], v[72:75]
	v_mfma_f32_16x16x32_bf16 v[68:71], v[162:165], v[208:211], v[68:71]
	v_mfma_f32_16x16x32_bf16 v[64:67], v[166:169], v[208:211], v[64:67]
	s_setprio 0
	s_barrier
; #define PG8_STAGE(bufoff, gbase, voff) do { _Pragma("unroll") for (int _i = 0; _i < 2; ++_i) \
;         dma16((const char*)(gbase), (voff)[_i], ldsb + (bufoff) + ldsw + _i * 8192); } while (0)
; #define PG8_LDA(dst, b, h) do { const int a1_ = opqv(aoff0) ^ 64; _Pragma("unroll") for (int m = 0; m < 4; ++m) { dst[m][0] = *(const LAS bf16x8*)(lds + PG8_SA(b, h) + aoff0 + m * 2048); dst[m][1] = *(const LAS bf16x8*)(lds + PG8_SA(b, h) + a1_ + m * 2048); } } while (0)
; #define PG8_MMA(ai, bj, At, Bt) do { __builtin_amdgcn_s_setprio(1); _Pragma("unroll") for (int m = 0; m < 4; ++m) _Pragma("unroll") for (int n = 0; n < 2; ++n) _Pragma("unroll") for (int k = 0; k < 2; ++k) \
;         acc[ai][bj][m][n] = __builtin_amdgcn_mfma_f32_16x16x32_bf16(Bt[n][k], At[m][k], acc[ai][bj][m][n], 0, 0, 0); __builtin_amdgcn_s_setprio(0); } while (0)
; #define PG8_WAIT_V(n) asm volatile("s_waitcnt vmcnt(" #n ")" ::: "memory")
; #define PG8_WAIT_L(n) asm volatile("s_waitcnt lgkmcnt(" #n ")" ::: "memory")
; #define PG8_BAR __builtin_amdgcn_s_barrier()
; #define PG8_SCHED __builtin_amdgcn_sched_barrier(0)
; template <class Epi>
; __device__ __forceinline__ void gemm_phase(LAS unsigned char* lds, const Gemm g, const StaticOrder& S, const Epi& E, int wave_) {
;     ...
;             PG8_STAGE(PG8_SB(1, 0), b3, voffB); PG8_STAGE(PG8_SB(1, 1), b3 + hstepB, voffB); PG8_STAGE(PG8_SA(1, 0), a3, voffA); PG8_LDA(At, 1, 1);
;             PG8_WAIT_V(8); PG8_WAIT_L(0); PG8_BAR; PG8_MMA(1, 0, At, B0); PG8_MMA(1, 1, At, B1); PG8_BAR; PG8_SCHED;
;         }
;         if (wr == 0) PG8_BAR;
;         E(acc, cur, wr, wc, fr, fq);
;         if (!has_next) break;
	v_mov_b32_e32 v128, v135
	s_nop 0
	s_nop 0
	s_nop 0
	s_nop 0
	v_xad_u32 v128, v128, 64, 0
	ds_read_b128 v[172:175], v129 offset:49152
	ds_read_b128 v[176:179], v129 offset:51200
	ds_read_b128 v[180:183], v128 offset:49152
	ds_read_b128 v[192:195], v128 offset:51200
	ds_read_b128 v[196:199], v129 offset:53248
	ds_read_b128 v[200:203], v129 offset:55296
	ds_read_b128 v[204:207], v128 offset:53248
	ds_read_b128 v[208:211], v128 offset:55296
	s_mov_b32 m0, s35
	s_nop 0
	global_load_lds_dwordx4 v131, s[36:37]
	s_mov_b32 m0, s33
	s_nop 0
	global_load_lds_dwordx4 v133, s[36:37]
	s_mov_b32 m0, s77
	s_nop 0
	global_load_lds_dwordx4 v131, s[56:57]
	s_mov_b32 m0, s3
	s_nop 0
	global_load_lds_dwordx4 v133, s[56:57]
	s_mov_b32 m0, s22
	s_nop 0
	global_load_lds_dwordx4 v130, s[30:31]
	s_mov_b32 m0, s2
	s_nop 0
	global_load_lds_dwordx4 v132, s[30:31]
	s_waitcnt vmcnt(8)
	s_waitcnt lgkmcnt(0)
	s_barrier
	s_setprio 1
	v_mfma_f32_16x16x32_bf16 v[60:63], v[138:141], v[172:175], v[60:63]
	v_mfma_f32_16x16x32_bf16 v[56:59], v[142:145], v[172:175], v[56:59]
	v_mfma_f32_16x16x32_bf16 v[52:55], v[138:141], v[176:179], v[52:55]
	v_mfma_f32_16x16x32_bf16 v[44:47], v[142:145], v[176:179], v[44:47]
	v_mfma_f32_16x16x32_bf16 v[36:39], v[138:141], v[196:199], v[36:39]
	v_mfma_f32_16x16x32_bf16 v[28:31], v[142:145], v[196:199], v[28:31]
	v_mfma_f32_16x16x32_bf16 v[20:23], v[138:141], v[200:203], v[20:23]
	v_mfma_f32_16x16x32_bf16 v[12:15], v[142:145], v[200:203], v[12:15]
	v_mfma_f32_16x16x32_bf16 v[60:63], v[146:149], v[180:183], v[60:63]
	v_mfma_f32_16x16x32_bf16 v[56:59], v[150:153], v[180:183], v[56:59]
	v_mfma_f32_16x16x32_bf16 v[52:55], v[146:149], v[192:195], v[52:55]
	v_mfma_f32_16x16x32_bf16 v[44:47], v[150:153], v[192:195], v[44:47]
	v_mfma_f32_16x16x32_bf16 v[36:39], v[146:149], v[204:207], v[36:39]
	v_mfma_f32_16x16x32_bf16 v[28:31], v[150:153], v[204:207], v[28:31]
	v_mfma_f32_16x16x32_bf16 v[20:23], v[146:149], v[208:211], v[20:23]
	v_mfma_f32_16x16x32_bf16 v[12:15], v[150:153], v[208:211], v[12:15]
	v_mfma_f32_16x16x32_bf16 v[48:51], v[154:157], v[172:175], v[48:51]
	v_mfma_f32_16x16x32_bf16 v[40:43], v[158:161], v[172:175], v[40:43]
	v_mfma_f32_16x16x32_bf16 v[32:35], v[154:157], v[176:179], v[32:35]
	v_mfma_f32_16x16x32_bf16 v[24:27], v[158:161], v[176:179], v[24:27]
	v_mfma_f32_16x16x32_bf16 v[16:19], v[154:157], v[196:199], v[16:19]
	v_mfma_f32_16x16x32_bf16 v[8:11], v[158:161], v[196:199], v[8:11]
	v_mfma_f32_16x16x32_bf16 v[4:7], v[154:157], v[200:203], v[4:7]
	v_mfma_f32_16x16x32_bf16 v[0:3], v[158:161], v[200:203], v[0:3]
	v_mfma_f32_16x16x32_bf16 v[48:51], v[162:165], v[180:183], v[48:51]
	v_mfma_f32_16x16x32_bf16 v[40:43], v[166:169], v[180:183], v[40:43]
	v_mfma_f32_16x16x32_bf16 v[32:35], v[162:165], v[192:195], v[32:35]
	v_mfma_f32_16x16x32_bf16 v[24:27], v[166:169], v[192:195], v[24:27]
	v_mfma_f32_16x16x32_bf16 v[16:19], v[162:165], v[204:207], v[16:19]
	v_mfma_f32_16x16x32_bf16 v[8:11], v[166:169], v[204:207], v[8:11]
	v_mfma_f32_16x16x32_bf16 v[4:7], v[162:165], v[208:211], v[4:7]
	v_mfma_f32_16x16x32_bf16 v[0:3], v[166:169], v[208:211], v[0:3]
	s_setprio 0
	s_barrier
	s_andn2_b64 vcc, exec, s[12:13]
	s_mov_b64 s[36:37], -1
	s_mov_b64 s[12:13], 0
	s_mov_b64 s[30:31], 0x100
	s_cbranch_vccz .LBB0_1342
	v_readlane_b32 s12, v253, 13
	v_readlane_b32 s13, v253, 14
	s_and_b64 vcc, exec, s[12:13]
	v_readlane_b32 s61, v255, 16
	s_cbranch_vccz .LBB0_1345
	s_barrier

; #define PG8_STAGE(bufoff, gbase, voff) do { _Pragma("unroll") for (int _i = 0; _i < 2; ++_i) \
;         dma16((const char*)(gbase), (voff)[_i], ldsb + (bufoff) + ldsw + _i * 8192); } while (0)
; #define PG8_LDA(dst, b, h) do { const int a1_ = opqv(aoff0) ^ 64; _Pragma("unroll") for (int m = 0; m < 4; ++m) { dst[m][0] = *(const LAS bf16x8*)(lds + PG8_SA(b, h) + aoff0 + m * 2048); dst[m][1] = *(const LAS bf16x8*)(lds + PG8_SA(b, h) + a1_ + m * 2048); } } while (0)
; #define PG8_LDB(dst, b, h) do { const int b1_ = opqv(boff0) ^ 64; _Pragma("unroll") for (int n = 0; n < 2; ++n) { dst[n][0] = *(const LAS bf16x8*)(lds + PG8_SB(b, h) + boff0 + n * 2048); dst[n][1] = *(const LAS bf16x8*)(lds + PG8_SB(b, h) + b1_ + n * 2048); } } while (0)
; #define PG8_MMA(ai, bj, At, Bt) do { __builtin_amdgcn_s_setprio(1); _Pragma("unroll") for (int m = 0; m < 4; ++m) _Pragma("unroll") for (int n = 0; n < 2; ++n) _Pragma("unroll") for (int k = 0; k < 2; ++k) \
;         acc[ai][bj][m][n] = __builtin_amdgcn_mfma_f32_16x16x32_bf16(Bt[n][k], At[m][k], acc[ai][bj][m][n], 0, 0, 0); __builtin_amdgcn_s_setprio(0); } while (0)
; #define PG8_WAIT_V(n) asm volatile("s_waitcnt vmcnt(" #n ")" ::: "memory")
; #define PG8_WAIT_L(n) asm volatile("s_waitcnt lgkmcnt(" #n ")" ::: "memory")
; #define PG8_BAR __builtin_amdgcn_s_barrier()
; #define PG8_SCHED __builtin_amdgcn_sched_barrier(0)
; template <class Epi>
; __device__ __forceinline__ void gemm_phase(LAS unsigned char* lds, const Gemm g, const StaticOrder& S, const Epi& E, int wave_) {
;     ...
;         for (int t = 0; t < nt; t += 2) {
;             const bool last = (t == nt - 2);
;             const char* a1 = cA + (size_t)(t + 1) * kstep;
;             const char* a2 = last ? nA : cA + (size_t)(t + 2) * kstep; const char* b2 = last ? nB : cB + (size_t)(t + 2) * kstep;
;             const char* a3 = a2 + kstep; const char* b3 = b2 + kstep;
;             PG8_STAGE(PG8_SA(1, 1), a1 + hstepA, voffA); PG8_LDB(B0, 0, 0); PG8_LDB(B1, 0, 1); PG8_SCHED; PG8_LDA(At, 0, 0);
;             PG8_WAIT_V(8); PG8_WAIT_L(0); PG8_BAR; PG8_MMA(0, 0, At, B0); PG8_MMA(0, 1, At, B1); PG8_BAR; PG8_SCHED;
;             PG8_STAGE(PG8_SB(0, 0), b2, voffB); PG8_STAGE(PG8_SB(0, 1), b2 + hstepB, voffB); PG8_STAGE(PG8_SA(0, 0), a2, voffA); PG8_LDA(At, 0, 1);
.LBB0_1552:
	s_add_u32 s36, s12, 0xffea0080
	s_addc_u32 s37, s13, -1
	s_cmpk_eq_i32 s59, 0x54
	s_cselect_b32 s46, s26, s36
	s_cselect_b32 s47, s27, s37
	s_cselect_b32 s40, s30, s16
	s_cselect_b32 s41, s31, s17
	s_add_u32 s36, s46, 0x80
	v_mov_b32_e32 v64, v219
	s_addc_u32 s37, s47, 0
	v_add_u32_e32 v68, s23, v219
	v_xad_u32 v76, v64, 64, s23
	v_mov_b32_e32 v80, v219
	s_add_i32 s60, 0, 0x14000
	ds_read_b128 v[64:67], v68
	ds_read_b128 v[68:71], v68 offset:2048
	ds_read_b128 v[72:75], v76
	ds_read_b128 v[76:79], v76 offset:2048
	v_add_u32_e32 v84, s60, v219
	v_xad_u32 v92, v80, 64, s60
	ds_read_b128 v[80:83], v84
	ds_read_b128 v[84:87], v84 offset:2048
	ds_read_b128 v[88:91], v92
	ds_read_b128 v[92:95], v92 offset:2048
	v_mov_b32_e32 v160, v218
	v_add_u32_e32 v191, 0, v218
	v_xad_u32 v190, v160, 64, 0
	ds_read_b128 v[160:163], v191
	ds_read_b128 v[164:167], v191 offset:2048
	ds_read_b128 v[168:171], v190
	ds_read_b128 v[172:175], v190 offset:2048
	ds_read_b128 v[176:179], v191 offset:4096
	ds_read_b128 v[180:183], v191 offset:6144
	ds_read_b128 v[192:195], v190 offset:4096
	ds_read_b128 v[196:199], v190 offset:6144
	s_mov_b32 m0, s14
	s_nop 0
	global_load_lds_dwordx4 v184, s[12:13]
	s_mov_b32 m0, s15
	s_nop 0
	global_load_lds_dwordx4 v215, s[12:13]
	s_waitcnt vmcnt(8)
	s_waitcnt lgkmcnt(0)
	s_barrier
	s_setprio 1
	v_mfma_f32_16x16x32_bf16 v[156:159], v[64:67], v[160:163], v[156:159]
	v_mfma_f32_16x16x32_bf16 v[152:155], v[68:71], v[160:163], v[152:155]
	v_mfma_f32_16x16x32_bf16 v[140:143], v[64:67], v[164:167], v[140:143]
	v_mfma_f32_16x16x32_bf16 v[136:139], v[68:71], v[164:167], v[136:139]
	v_mfma_f32_16x16x32_bf16 v[124:127], v[64:67], v[176:179], v[124:127]
	v_mfma_f32_16x16x32_bf16 v[120:123], v[68:71], v[176:179], v[120:123]
	v_mfma_f32_16x16x32_bf16 v[108:111], v[64:67], v[180:183], v[108:111]
	v_mfma_f32_16x16x32_bf16 v[104:107], v[68:71], v[180:183], v[104:107]
	v_mfma_f32_16x16x32_bf16 v[156:159], v[72:75], v[168:171], v[156:159]
	v_mfma_f32_16x16x32_bf16 v[152:155], v[76:79], v[168:171], v[152:155]
	v_mfma_f32_16x16x32_bf16 v[140:143], v[72:75], v[172:175], v[140:143]
	v_mfma_f32_16x16x32_bf16 v[136:139], v[76:79], v[172:175], v[136:139]
	v_mfma_f32_16x16x32_bf16 v[124:127], v[72:75], v[192:195], v[124:127]
	v_mfma_f32_16x16x32_bf16 v[120:123], v[76:79], v[192:195], v[120:123]
	v_mfma_f32_16x16x32_bf16 v[108:111], v[72:75], v[196:199], v[108:111]
	v_mfma_f32_16x16x32_bf16 v[104:107], v[76:79], v[196:199], v[104:107]
	v_mfma_f32_16x16x32_bf16 v[148:151], v[80:83], v[160:163], v[148:151]
	v_mfma_f32_16x16x32_bf16 v[144:147], v[84:87], v[160:163], v[144:147]
	v_mfma_f32_16x16x32_bf16 v[132:135], v[80:83], v[164:167], v[132:135]
	v_mfma_f32_16x16x32_bf16 v[128:131], v[84:87], v[164:167], v[128:131]
	v_mfma_f32_16x16x32_bf16 v[116:119], v[80:83], v[176:179], v[116:119]
	v_mfma_f32_16x16x32_bf16 v[112:115], v[84:87], v[176:179], v[112:115]
	v_mfma_f32_16x16x32_bf16 v[100:103], v[80:83], v[180:183], v[100:103]
	v_mfma_f32_16x16x32_bf16 v[96:99], v[84:87], v[180:183], v[96:99]
	v_mfma_f32_16x16x32_bf16 v[148:151], v[88:91], v[168:171], v[148:151]
	v_mfma_f32_16x16x32_bf16 v[144:147], v[92:95], v[168:171], v[144:147]
	v_mfma_f32_16x16x32_bf16 v[132:135], v[88:91], v[172:175], v[132:135]
	v_mfma_f32_16x16x32_bf16 v[128:131], v[92:95], v[172:175], v[128:131]
	v_mfma_f32_16x16x32_bf16 v[116:119], v[88:91], v[192:195], v[116:119]
	v_mfma_f32_16x16x32_bf16 v[112:115], v[92:95], v[192:195], v[112:115]
	v_mfma_f32_16x16x32_bf16 v[100:103], v[88:91], v[196:199], v[100:103]
	v_mfma_f32_16x16x32_bf16 v[96:99], v[92:95], v[196:199], v[96:99]
	s_setprio 0
	s_barrier
	v_mov_b32_e32 v160, v218
	s_add_u32 s60, s40, 0x160000
	s_addc_u32 s61, s41, 0
	s_nop 0
	s_nop 0
	s_nop 0
	v_xad_u32 v190, v160, 64, 0
	ds_read_b128 v[160:163], v191 offset:16384
	ds_read_b128 v[164:167], v191 offset:18432
	ds_read_b128 v[168:171], v190 offset:16384
	ds_read_b128 v[172:175], v190 offset:18432
	ds_read_b128 v[176:179], v191 offset:20480
	ds_read_b128 v[180:183], v191 offset:22528
	ds_read_b128 v[192:195], v190 offset:20480
	ds_read_b128 v[196:199], v190 offset:22528
	s_mov_b32 m0, s80
	s_nop 0
	global_load_lds_dwordx4 v214, s[40:41]
	s_mov_b32 m0, s81
	s_nop 0
	global_load_lds_dwordx4 v216, s[40:41]
	s_mov_b32 m0, s29
	s_nop 0
	global_load_lds_dwordx4 v214, s[60:61]
	s_mov_b32 m0, s88
	s_nop 0
	global_load_lds_dwordx4 v216, s[60:61]
	s_mov_b32 m0, s76
	s_nop 0
	global_load_lds_dwordx4 v184, s[46:47]
	s_mov_b32 m0, s89
	s_nop 0
	global_load_lds_dwordx4 v215, s[46:47]
	s_waitcnt vmcnt(8)
	s_waitcnt lgkmcnt(0)
	s_barrier
; #define PG8_STAGE(bufoff, gbase, voff) do { _Pragma("unroll") for (int _i = 0; _i < 2; ++_i) \
;         dma16((const char*)(gbase), (voff)[_i], ldsb + (bufoff) + ldsw + _i * 8192); } while (0)
; #define PG8_LDA(dst, b, h) do { const int a1_ = opqv(aoff0) ^ 64; _Pragma("unroll") for (int m = 0; m < 4; ++m) { dst[m][0] = *(const LAS bf16x8*)(lds + PG8_SA(b, h) + aoff0 + m * 2048); dst[m][1] = *(const LAS bf16x8*)(lds + PG8_SA(b, h) + a1_ + m * 2048); } } while (0)
; #define PG8_LDB(dst, b, h) do { const int b1_ = opqv(boff0) ^ 64; _Pragma("unroll") for (int n = 0; n < 2; ++n) { dst[n][0] = *(const LAS bf16x8*)(lds + PG8_SB(b, h) + boff0 + n * 2048); dst[n][1] = *(const LAS bf16x8*)(lds + PG8_SB(b, h) + b1_ + n * 2048); } } while (0)
; #define PG8_MMA(ai, bj, At, Bt) do { __builtin_amdgcn_s_setprio(1); _Pragma("unroll") for (int m = 0; m < 4; ++m) _Pragma("unroll") for (int n = 0; n < 2; ++n) _Pragma("unroll") for (int k = 0; k < 2; ++k) \
;         acc[ai][bj][m][n] = __builtin_amdgcn_mfma_f32_16x16x32_bf16(Bt[n][k], At[m][k], acc[ai][bj][m][n], 0, 0, 0); __builtin_amdgcn_s_setprio(0); } while (0)
; #define PG8_WAIT_V(n) asm volatile("s_waitcnt vmcnt(" #n ")" ::: "memory")
; #define PG8_WAIT_L(n) asm volatile("s_waitcnt lgkmcnt(" #n ")" ::: "memory")
; #define PG8_BAR __builtin_amdgcn_s_barrier()
; #define PG8_SCHED __builtin_amdgcn_sched_barrier(0)
; template <class Epi>
; __device__ __forceinline__ void gemm_phase(LAS unsigned char* lds, const Gemm g, const StaticOrder& S, const Epi& E, int wave_) {
;     ...
;             PG8_WAIT_V(8); PG8_WAIT_L(0); PG8_BAR; PG8_MMA(1, 0, At, B0); PG8_MMA(1, 1, At, B1); PG8_BAR; PG8_SCHED;
;             PG8_STAGE(PG8_SA(0, 1), a2 + hstepA, voffA); PG8_LDB(B0, 1, 0); PG8_LDB(B1, 1, 1); PG8_SCHED; PG8_LDA(At, 1, 0);
;             PG8_WAIT_V(8); PG8_WAIT_L(0); PG8_BAR; PG8_MMA(0, 0, At, B0); PG8_MMA(0, 1, At, B1); PG8_BAR; PG8_SCHED;
	s_setprio 1
	v_mfma_f32_16x16x32_bf16 v[60:63], v[64:67], v[160:163], v[60:63]
	v_mfma_f32_16x16x32_bf16 v[56:59], v[68:71], v[160:163], v[56:59]
	v_mfma_f32_16x16x32_bf16 v[44:47], v[64:67], v[164:167], v[44:47]
	v_mfma_f32_16x16x32_bf16 v[40:43], v[68:71], v[164:167], v[40:43]
	v_mfma_f32_16x16x32_bf16 v[28:31], v[64:67], v[176:179], v[28:31]
	v_mfma_f32_16x16x32_bf16 v[24:27], v[68:71], v[176:179], v[24:27]
	v_mfma_f32_16x16x32_bf16 v[12:15], v[64:67], v[180:183], v[12:15]
	v_mfma_f32_16x16x32_bf16 v[8:11], v[68:71], v[180:183], v[8:11]
	v_mfma_f32_16x16x32_bf16 v[60:63], v[72:75], v[168:171], v[60:63]
	v_mfma_f32_16x16x32_bf16 v[56:59], v[76:79], v[168:171], v[56:59]
	v_mfma_f32_16x16x32_bf16 v[44:47], v[72:75], v[172:175], v[44:47]
	v_mfma_f32_16x16x32_bf16 v[40:43], v[76:79], v[172:175], v[40:43]
	v_mfma_f32_16x16x32_bf16 v[28:31], v[72:75], v[192:195], v[28:31]
	v_mfma_f32_16x16x32_bf16 v[24:27], v[76:79], v[192:195], v[24:27]
	v_mfma_f32_16x16x32_bf16 v[12:15], v[72:75], v[196:199], v[12:15]
	v_mfma_f32_16x16x32_bf16 v[8:11], v[76:79], v[196:199], v[8:11]
	v_mfma_f32_16x16x32_bf16 v[52:55], v[80:83], v[160:163], v[52:55]
	v_mfma_f32_16x16x32_bf16 v[48:51], v[84:87], v[160:163], v[48:51]
	v_mfma_f32_16x16x32_bf16 v[36:39], v[80:83], v[164:167], v[36:39]
	v_mfma_f32_16x16x32_bf16 v[32:35], v[84:87], v[164:167], v[32:35]
	v_mfma_f32_16x16x32_bf16 v[20:23], v[80:83], v[176:179], v[20:23]
	v_mfma_f32_16x16x32_bf16 v[16:19], v[84:87], v[176:179], v[16:19]
	v_mfma_f32_16x16x32_bf16 v[4:7], v[80:83], v[180:183], v[4:7]
	v_mfma_f32_16x16x32_bf16 v[0:3], v[84:87], v[180:183], v[0:3]
	v_mfma_f32_16x16x32_bf16 v[52:55], v[88:91], v[168:171], v[52:55]
	v_mfma_f32_16x16x32_bf16 v[48:51], v[92:95], v[168:171], v[48:51]
	v_mfma_f32_16x16x32_bf16 v[36:39], v[88:91], v[172:175], v[36:39]
	v_mfma_f32_16x16x32_bf16 v[32:35], v[92:95], v[172:175], v[32:35]
	v_mfma_f32_16x16x32_bf16 v[20:23], v[88:91], v[192:195], v[20:23]
	v_mfma_f32_16x16x32_bf16 v[16:19], v[92:95], v[192:195], v[16:19]
	v_mfma_f32_16x16x32_bf16 v[4:7], v[88:91], v[196:199], v[4:7]
	v_mfma_f32_16x16x32_bf16 v[0:3], v[92:95], v[196:199], v[0:3]
	s_setprio 0
	s_barrier
	s_add_u32 s46, s46, 0x160000
	s_addc_u32 s47, s47, 0
	s_mov_b32 m0, s1
	s_nop 0
	global_load_lds_dwordx4 v184, s[46:47]
	v_mov_b32_e32 v64, v219
	s_mov_b32 m0, s69
	s_nop 0
	global_load_lds_dwordx4 v215, s[46:47]
	v_add_u32_e32 v68, s34, v219
	v_xad_u32 v76, v64, 64, s34
	v_mov_b32_e32 v80, v219
	s_add_i32 s46, 0, 0x1c000
	ds_read_b128 v[64:67], v68
	ds_read_b128 v[68:71], v68 offset:2048
	ds_read_b128 v[72:75], v76
	ds_read_b128 v[76:79], v76 offset:2048
	v_add_u32_e32 v84, s46, v219
	v_xad_u32 v92, v80, 64, s46
	ds_read_b128 v[80:83], v84
	ds_read_b128 v[84:87], v84 offset:2048
	ds_read_b128 v[88:91], v92
	ds_read_b128 v[92:95], v92 offset:2048
	v_mov_b32_e32 v160, v218
	s_nop 0
	v_xad_u32 v190, v160, 64, 0
	ds_read_b128 v[160:163], v191 offset:32768
	ds_read_b128 v[164:167], v191 offset:34816
	ds_read_b128 v[168:171], v190 offset:32768
	ds_read_b128 v[172:175], v190 offset:34816
	ds_read_b128 v[176:179], v191 offset:36864
	ds_read_b128 v[180:183], v191 offset:38912
	ds_read_b128 v[192:195], v190 offset:36864
	ds_read_b128 v[196:199], v190 offset:38912
	s_waitcnt vmcnt(8)
	s_waitcnt lgkmcnt(0)
	s_barrier
	s_setprio 1
	v_mfma_f32_16x16x32_bf16 v[156:159], v[64:67], v[160:163], v[156:159]
	v_mfma_f32_16x16x32_bf16 v[152:155], v[68:71], v[160:163], v[152:155]
	v_mfma_f32_16x16x32_bf16 v[140:143], v[64:67], v[164:167], v[140:143]
	v_mfma_f32_16x16x32_bf16 v[136:139], v[68:71], v[164:167], v[136:139]
	v_mfma_f32_16x16x32_bf16 v[124:127], v[64:67], v[176:179], v[124:127]
	v_mfma_f32_16x16x32_bf16 v[120:123], v[68:71], v[176:179], v[120:123]
	v_mfma_f32_16x16x32_bf16 v[108:111], v[64:67], v[180:183], v[108:111]
	v_mfma_f32_16x16x32_bf16 v[104:107], v[68:71], v[180:183], v[104:107]
	v_mfma_f32_16x16x32_bf16 v[156:159], v[72:75], v[168:171], v[156:159]
	v_mfma_f32_16x16x32_bf16 v[152:155], v[76:79], v[168:171], v[152:155]
	v_mfma_f32_16x16x32_bf16 v[140:143], v[72:75], v[172:175], v[140:143]
	v_mfma_f32_16x16x32_bf16 v[136:139], v[76:79], v[172:175], v[136:139]
	v_mfma_f32_16x16x32_bf16 v[124:127], v[72:75], v[192:195], v[124:127]
	v_mfma_f32_16x16x32_bf16 v[120:123], v[76:79], v[192:195], v[120:123]
	v_mfma_f32_16x16x32_bf16 v[108:111], v[72:75], v[196:199], v[108:111]
	v_mfma_f32_16x16x32_bf16 v[104:107], v[76:79], v[196:199], v[104:107]
	v_mfma_f32_16x16x32_bf16 v[148:151], v[80:83], v[160:163], v[148:151]
	s_add_u32 s46, s40, 0x80
	s_addc_u32 s47, s41, 0
	v_mfma_f32_16x16x32_bf16 v[144:147], v[84:87], v[160:163], v[144:147]
	v_mfma_f32_16x16x32_bf16 v[132:135], v[80:83], v[164:167], v[132:135]
	v_mfma_f32_16x16x32_bf16 v[128:131], v[84:87], v[164:167], v[128:131]
	v_mfma_f32_16x16x32_bf16 v[116:119], v[80:83], v[176:179], v[116:119]
	v_mfma_f32_16x16x32_bf16 v[112:115], v[84:87], v[176:179], v[112:115]
	v_mfma_f32_16x16x32_bf16 v[100:103], v[80:83], v[180:183], v[100:103]
	v_mfma_f32_16x16x32_bf16 v[96:99], v[84:87], v[180:183], v[96:99]
	v_mfma_f32_16x16x32_bf16 v[148:151], v[88:91], v[168:171], v[148:151]
	v_mfma_f32_16x16x32_bf16 v[144:147], v[92:95], v[168:171], v[144:147]
	v_mfma_f32_16x16x32_bf16 v[132:135], v[88:91], v[172:175], v[132:135]
	v_mfma_f32_16x16x32_bf16 v[128:131], v[92:95], v[172:175], v[128:131]
	v_mfma_f32_16x16x32_bf16 v[116:119], v[88:91], v[192:195], v[116:119]
	v_mfma_f32_16x16x32_bf16 v[112:115], v[92:95], v[192:195], v[112:115]
	v_mfma_f32_16x16x32_bf16 v[100:103], v[88:91], v[196:199], v[100:103]
	v_mfma_f32_16x16x32_bf16 v[96:99], v[92:95], v[196:199], v[96:99]
	s_setprio 0
	s_barrier
; #define PG8_STAGE(bufoff, gbase, voff) do { _Pragma("unroll") for (int _i = 0; _i < 2; ++_i) \
;         dma16((const char*)(gbase), (voff)[_i], ldsb + (bufoff) + ldsw + _i * 8192); } while (0)
; #define PG8_LDA(dst, b, h) do { const int a1_ = opqv(aoff0) ^ 64; _Pragma("unroll") for (int m = 0; m < 4; ++m) { dst[m][0] = *(const LAS bf16x8*)(lds + PG8_SA(b, h) + aoff0 + m * 2048); dst[m][1] = *(const LAS bf16x8*)(lds + PG8_SA(b, h) + a1_ + m * 2048); } } while (0)
; #define PG8_MMA(ai, bj, At, Bt) do { __builtin_amdgcn_s_setprio(1); _Pragma("unroll") for (int m = 0; m < 4; ++m) _Pragma("unroll") for (int n = 0; n < 2; ++n) _Pragma("unroll") for (int k = 0; k < 2; ++k) \
;         acc[ai][bj][m][n] = __builtin_amdgcn_mfma_f32_16x16x32_bf16(Bt[n][k], At[m][k], acc[ai][bj][m][n], 0, 0, 0); __builtin_amdgcn_s_setprio(0); } while (0)
; #define PG8_WAIT_V(n) asm volatile("s_waitcnt vmcnt(" #n ")" ::: "memory")
; #define PG8_WAIT_L(n) asm volatile("s_waitcnt lgkmcnt(" #n ")" ::: "memory")
; #define PG8_BAR __builtin_amdgcn_s_barrier()
; #define PG8_SCHED __builtin_amdgcn_sched_barrier(0)
; template <class Epi>
; __device__ __forceinline__ void gemm_phase(LAS unsigned char* lds, const Gemm g, const StaticOrder& S, const Epi& E, int wave_) {
;     ...
;             PG8_STAGE(PG8_SB(1, 0), b3, voffB); PG8_STAGE(PG8_SB(1, 1), b3 + hstepB, voffB); PG8_STAGE(PG8_SA(1, 0), a3, voffA); PG8_LDA(At, 1, 1);
;             PG8_WAIT_V(8); PG8_WAIT_L(0); PG8_BAR; PG8_MMA(1, 0, At, B0); PG8_MMA(1, 1, At, B1); PG8_BAR; PG8_SCHED;
;         }
;         if (wr == 0) PG8_BAR;
	s_add_u32 s40, s40, 0x160080
	s_addc_u32 s41, s41, 0
	v_mov_b32_e32 v160, v218
	s_nop 0
	s_nop 0
	v_xad_u32 v190, v160, 64, 0
	ds_read_b128 v[160:163], v191 offset:49152
	ds_read_b128 v[164:167], v191 offset:51200
	ds_read_b128 v[168:171], v190 offset:49152
	ds_read_b128 v[172:175], v190 offset:51200
	ds_read_b128 v[176:179], v191 offset:53248
	ds_read_b128 v[180:183], v191 offset:55296
	ds_read_b128 v[192:195], v190 offset:53248
	ds_read_b128 v[196:199], v190 offset:55296
	s_mov_b32 m0, s35
	s_nop 0
	global_load_lds_dwordx4 v214, s[46:47]
	s_mov_b32 m0, s33
	s_nop 0
	global_load_lds_dwordx4 v216, s[46:47]
	s_mov_b32 m0, s77
	s_nop 0
	global_load_lds_dwordx4 v214, s[40:41]
	s_mov_b32 m0, s3
	s_nop 0
	global_load_lds_dwordx4 v216, s[40:41]
	s_mov_b32 m0, s22
	s_nop 0
	global_load_lds_dwordx4 v184, s[36:37]
	s_mov_b32 m0, s2
	s_nop 0
	global_load_lds_dwordx4 v215, s[36:37]
	s_waitcnt vmcnt(8)
	s_waitcnt lgkmcnt(0)
	s_barrier
	s_setprio 1
	v_mfma_f32_16x16x32_bf16 v[60:63], v[64:67], v[160:163], v[60:63]
	v_mfma_f32_16x16x32_bf16 v[56:59], v[68:71], v[160:163], v[56:59]
	v_mfma_f32_16x16x32_bf16 v[44:47], v[64:67], v[164:167], v[44:47]
	v_mfma_f32_16x16x32_bf16 v[40:43], v[68:71], v[164:167], v[40:43]
	v_mfma_f32_16x16x32_bf16 v[28:31], v[64:67], v[176:179], v[28:31]
	v_mfma_f32_16x16x32_bf16 v[24:27], v[68:71], v[176:179], v[24:27]
	v_mfma_f32_16x16x32_bf16 v[12:15], v[64:67], v[180:183], v[12:15]
	v_mfma_f32_16x16x32_bf16 v[8:11], v[68:71], v[180:183], v[8:11]
	v_mfma_f32_16x16x32_bf16 v[60:63], v[72:75], v[168:171], v[60:63]
	v_mfma_f32_16x16x32_bf16 v[56:59], v[76:79], v[168:171], v[56:59]
	v_mfma_f32_16x16x32_bf16 v[44:47], v[72:75], v[172:175], v[44:47]
	v_mfma_f32_16x16x32_bf16 v[40:43], v[76:79], v[172:175], v[40:43]
	v_mfma_f32_16x16x32_bf16 v[28:31], v[72:75], v[192:195], v[28:31]
	v_mfma_f32_16x16x32_bf16 v[24:27], v[76:79], v[192:195], v[24:27]
	v_mfma_f32_16x16x32_bf16 v[12:15], v[72:75], v[196:199], v[12:15]
	v_mfma_f32_16x16x32_bf16 v[8:11], v[76:79], v[196:199], v[8:11]
	v_mfma_f32_16x16x32_bf16 v[52:55], v[80:83], v[160:163], v[52:55]
	v_mfma_f32_16x16x32_bf16 v[48:51], v[84:87], v[160:163], v[48:51]
	v_mfma_f32_16x16x32_bf16 v[36:39], v[80:83], v[164:167], v[36:39]
	v_mfma_f32_16x16x32_bf16 v[32:35], v[84:87], v[164:167], v[32:35]
	v_mfma_f32_16x16x32_bf16 v[20:23], v[80:83], v[176:179], v[20:23]
	v_mfma_f32_16x16x32_bf16 v[16:19], v[84:87], v[176:179], v[16:19]
	v_mfma_f32_16x16x32_bf16 v[4:7], v[80:83], v[180:183], v[4:7]
	v_mfma_f32_16x16x32_bf16 v[0:3], v[84:87], v[180:183], v[0:3]
	v_mfma_f32_16x16x32_bf16 v[52:55], v[88:91], v[168:171], v[52:55]
	v_mfma_f32_16x16x32_bf16 v[48:51], v[92:95], v[168:171], v[48:51]
	v_mfma_f32_16x16x32_bf16 v[36:39], v[88:91], v[172:175], v[36:39]
	v_mfma_f32_16x16x32_bf16 v[32:35], v[92:95], v[172:175], v[32:35]
	v_mfma_f32_16x16x32_bf16 v[20:23], v[88:91], v[192:195], v[20:23]
	v_mfma_f32_16x16x32_bf16 v[16:19], v[92:95], v[192:195], v[16:19]
	v_mfma_f32_16x16x32_bf16 v[4:7], v[88:91], v[196:199], v[4:7]
	v_mfma_f32_16x16x32_bf16 v[0:3], v[92:95], v[196:199], v[0:3]
	s_setprio 0
	s_barrier
	s_add_i32 s59, s59, 2
	s_add_u32 s16, s16, 0x100
	s_addc_u32 s17, s17, 0
	s_add_u32 s12, s12, 0x100
	s_addc_u32 s13, s13, 0
	s_cmpk_gt_u32 s59, 0x55
	s_cbranch_scc0 .LBB0_1552
	v_readlane_b32 s12, v253, 13
	v_readlane_b32 s13, v253, 14
	s_and_b64 vcc, exec, s[12:13]
	s_cbranch_vccz .LBB0_1555
	s_barrier

; #define PG8_STAGE(bufoff, gbase, voff) do { _Pragma("unroll") for (int _i = 0; _i < 2; ++_i) \
;         dma16((const char*)(gbase), (voff)[_i], ldsb + (bufoff) + ldsw + _i * 8192); } while (0)
; #define PG8_LDA(dst, b, h) do { const int a1_ = opqv(aoff0) ^ 64; _Pragma("unroll") for (int m = 0; m < 4; ++m) { dst[m][0] = *(const LAS bf16x8*)(lds + PG8_SA(b, h) + aoff0 + m * 2048); dst[m][1] = *(const LAS bf16x8*)(lds + PG8_SA(b, h) + a1_ + m * 2048); } } while (0)
; #define PG8_LDB(dst, b, h) do { const int b1_ = opqv(boff0) ^ 64; _Pragma("unroll") for (int n = 0; n < 2; ++n) { dst[n][0] = *(const LAS bf16x8*)(lds + PG8_SB(b, h) + boff0 + n * 2048); dst[n][1] = *(const LAS bf16x8*)(lds + PG8_SB(b, h) + b1_ + n * 2048); } } while (0)
; #define PG8_MMA(ai, bj, At, Bt) do { __builtin_amdgcn_s_setprio(1); _Pragma("unroll") for (int m = 0; m < 4; ++m) _Pragma("unroll") for (int n = 0; n < 2; ++n) _Pragma("unroll") for (int k = 0; k < 2; ++k) \
;         acc[ai][bj][m][n] = __builtin_amdgcn_mfma_f32_16x16x32_bf16(Bt[n][k], At[m][k], acc[ai][bj][m][n], 0, 0, 0); __builtin_amdgcn_s_setprio(0); } while (0)
; #define PG8_WAIT_V(n) asm volatile("s_waitcnt vmcnt(" #n ")" ::: "memory")
; #define PG8_WAIT_L(n) asm volatile("s_waitcnt lgkmcnt(" #n ")" ::: "memory")
; #define PG8_BAR __builtin_amdgcn_s_barrier()
; #define PG8_SCHED __builtin_amdgcn_sched_barrier(0)
; template <class Epi>
; __device__ __forceinline__ void gemm_phase(LAS unsigned char* lds, const Gemm g, const StaticOrder& S, const Epi& E, int wave_) {
;     ...
;         for (int t = 0; t < nt; t += 2) {
;             const bool last = (t == nt - 2);
;             const char* a1 = cA + (size_t)(t + 1) * kstep;
;             const char* a2 = last ? nA : cA + (size_t)(t + 2) * kstep; const char* b2 = last ? nB : cB + (size_t)(t + 2) * kstep;
;             const char* a3 = a2 + kstep; const char* b3 = b2 + kstep;
;             PG8_STAGE(PG8_SA(1, 1), a1 + hstepA, voffA); PG8_LDB(B0, 0, 0); PG8_LDB(B1, 0, 1); PG8_SCHED; PG8_LDA(At, 0, 0);
;             PG8_WAIT_V(8); PG8_WAIT_L(0); PG8_BAR; PG8_MMA(0, 0, At, B0); PG8_MMA(0, 1, At, B1); PG8_BAR; PG8_SCHED;
;             PG8_STAGE(PG8_SB(0, 0), b2, voffB); PG8_STAGE(PG8_SB(0, 1), b2 + hstepB, voffB); PG8_STAGE(PG8_SA(0, 0), a2, voffA); PG8_LDA(At, 0, 1);
.LBB0_1776:
	s_add_u32 s46, s12, 0xfff80080
	s_addc_u32 s47, s13, -1
	s_cmp_eq_u32 s79, 28
	s_cselect_b32 s64, s17, s46
	s_cselect_b32 s65, s16, s47
	s_cselect_b32 s48, s59, s75
	s_cselect_b32 s49, s57, s78
	s_add_u32 s46, s64, 0x80
	v_mov_b32_e32 v88, v238
	s_addc_u32 s47, s65, 0
	v_add_u32_e32 v92, s23, v238
	v_xad_u32 v100, v88, 64, s23
	v_mov_b32_e32 v108, v238
	s_add_i32 s82, 0, 0x14000
	ds_read_b128 v[88:91], v92
	ds_read_b128 v[92:95], v92 offset:2048
	ds_read_b128 v[96:99], v100
	ds_read_b128 v[100:103], v100 offset:2048
	v_add_u32_e32 v112, s82, v238
	v_xad_u32 v124, v108, 64, s82
	ds_read_b128 v[108:111], v112
	ds_read_b128 v[112:115], v112 offset:2048
	ds_read_b128 v[120:123], v124
	ds_read_b128 v[124:127], v124 offset:2048
	v_mov_b32_e32 v160, v237
	v_add_u32_e32 v191, 0, v237
	v_xad_u32 v190, v160, 64, 0
	ds_read_b128 v[160:163], v191
	ds_read_b128 v[164:167], v191 offset:2048
	ds_read_b128 v[168:171], v190
	ds_read_b128 v[172:175], v190 offset:2048
	ds_read_b128 v[176:179], v191 offset:4096
	ds_read_b128 v[180:183], v191 offset:6144
	ds_read_b128 v[192:195], v190 offset:4096
	ds_read_b128 v[196:199], v190 offset:6144
	s_mov_b32 m0, s14
	s_nop 0
	global_load_lds_dwordx4 v184, s[12:13]
	s_mov_b32 m0, s15
	s_nop 0
	global_load_lds_dwordx4 v234, s[12:13]
	s_waitcnt vmcnt(8)
	s_waitcnt lgkmcnt(0)
	s_barrier
	s_setprio 1
	v_mfma_f32_16x16x32_bf16 v[156:159], v[88:91], v[160:163], v[156:159]
	v_mfma_f32_16x16x32_bf16 v[152:155], v[92:95], v[160:163], v[152:155]
	v_mfma_f32_16x16x32_bf16 v[148:151], v[88:91], v[164:167], v[148:151]
	v_mfma_f32_16x16x32_bf16 v[144:147], v[92:95], v[164:167], v[144:147]
	v_mfma_f32_16x16x32_bf16 v[140:143], v[88:91], v[176:179], v[140:143]
	v_mfma_f32_16x16x32_bf16 v[136:139], v[92:95], v[176:179], v[136:139]
	v_mfma_f32_16x16x32_bf16 v[132:135], v[88:91], v[180:183], v[132:135]
	v_mfma_f32_16x16x32_bf16 v[128:131], v[92:95], v[180:183], v[128:131]
	v_mfma_f32_16x16x32_bf16 v[156:159], v[96:99], v[168:171], v[156:159]
	v_mfma_f32_16x16x32_bf16 v[152:155], v[100:103], v[168:171], v[152:155]
	v_mfma_f32_16x16x32_bf16 v[148:151], v[96:99], v[172:175], v[148:151]
	v_mfma_f32_16x16x32_bf16 v[144:147], v[100:103], v[172:175], v[144:147]
	v_mfma_f32_16x16x32_bf16 v[140:143], v[96:99], v[192:195], v[140:143]
	v_mfma_f32_16x16x32_bf16 v[136:139], v[100:103], v[192:195], v[136:139]
	v_mfma_f32_16x16x32_bf16 v[132:135], v[96:99], v[196:199], v[132:135]
	v_mfma_f32_16x16x32_bf16 v[128:131], v[100:103], v[196:199], v[128:131]
	v_mfma_f32_16x16x32_bf16 v[60:63], v[108:111], v[160:163], v[60:63]
	v_mfma_f32_16x16x32_bf16 v[56:59], v[112:115], v[160:163], v[56:59]
	v_mfma_f32_16x16x32_bf16 v[52:55], v[108:111], v[164:167], v[52:55]
	v_mfma_f32_16x16x32_bf16 v[48:51], v[112:115], v[164:167], v[48:51]
	v_mfma_f32_16x16x32_bf16 v[44:47], v[108:111], v[176:179], v[44:47]
	v_mfma_f32_16x16x32_bf16 v[40:43], v[112:115], v[176:179], v[40:43]
	v_mfma_f32_16x16x32_bf16 v[36:39], v[108:111], v[180:183], v[36:39]
	v_mfma_f32_16x16x32_bf16 v[32:35], v[112:115], v[180:183], v[32:35]
	v_mfma_f32_16x16x32_bf16 v[60:63], v[120:123], v[168:171], v[60:63]
	v_mfma_f32_16x16x32_bf16 v[56:59], v[124:127], v[168:171], v[56:59]
	v_mfma_f32_16x16x32_bf16 v[52:55], v[120:123], v[172:175], v[52:55]
	v_mfma_f32_16x16x32_bf16 v[48:51], v[124:127], v[172:175], v[48:51]
	v_mfma_f32_16x16x32_bf16 v[44:47], v[120:123], v[192:195], v[44:47]
	v_mfma_f32_16x16x32_bf16 v[40:43], v[124:127], v[192:195], v[40:43]
	v_mfma_f32_16x16x32_bf16 v[36:39], v[120:123], v[196:199], v[36:39]
	v_mfma_f32_16x16x32_bf16 v[32:35], v[124:127], v[196:199], v[32:35]
	s_setprio 0
	s_barrier
	v_mov_b32_e32 v160, v237
	s_add_u32 s82, s48, 0x80000
	s_addc_u32 s83, s49, 0
	s_nop 0
	s_nop 0
	s_nop 0
	v_xad_u32 v190, v160, 64, 0
	ds_read_b128 v[160:163], v191 offset:16384
	ds_read_b128 v[164:167], v191 offset:18432
	ds_read_b128 v[168:171], v190 offset:16384
	ds_read_b128 v[172:175], v190 offset:18432
	ds_read_b128 v[176:179], v191 offset:20480
	ds_read_b128 v[180:183], v191 offset:22528
	ds_read_b128 v[192:195], v190 offset:20480
	ds_read_b128 v[196:199], v190 offset:22528
	s_mov_b32 m0, s80
	s_nop 0
	global_load_lds_dwordx4 v233, s[48:49]
	s_mov_b32 m0, s81
	s_nop 0
	global_load_lds_dwordx4 v235, s[48:49]
	s_mov_b32 m0, s29
	s_nop 0
	global_load_lds_dwordx4 v233, s[82:83]
	s_mov_b32 m0, s88
	s_nop 0
	global_load_lds_dwordx4 v235, s[82:83]
	s_mov_b32 m0, s76
	s_nop 0
	global_load_lds_dwordx4 v184, s[64:65]
	s_mov_b32 m0, s89
	s_nop 0
	global_load_lds_dwordx4 v234, s[64:65]
	s_waitcnt vmcnt(8)
	s_waitcnt lgkmcnt(0)
	s_barrier
; #define PG8_STAGE(bufoff, gbase, voff) do { _Pragma("unroll") for (int _i = 0; _i < 2; ++_i) \
;         dma16((const char*)(gbase), (voff)[_i], ldsb + (bufoff) + ldsw + _i * 8192); } while (0)
; #define PG8_LDA(dst, b, h) do { const int a1_ = opqv(aoff0) ^ 64; _Pragma("unroll") for (int m = 0; m < 4; ++m) { dst[m][0] = *(const LAS bf16x8*)(lds + PG8_SA(b, h) + aoff0 + m * 2048); dst[m][1] = *(const LAS bf16x8*)(lds + PG8_SA(b, h) + a1_ + m * 2048); } } while (0)
; #define PG8_LDB(dst, b, h) do { const int b1_ = opqv(boff0) ^ 64; _Pragma("unroll") for (int n = 0; n < 2; ++n) { dst[n][0] = *(const LAS bf16x8*)(lds + PG8_SB(b, h) + boff0 + n * 2048); dst[n][1] = *(const LAS bf16x8*)(lds + PG8_SB(b, h) + b1_ + n * 2048); } } while (0)
; #define PG8_MMA(ai, bj, At, Bt) do { __builtin_amdgcn_s_setprio(1); _Pragma("unroll") for (int m = 0; m < 4; ++m) _Pragma("unroll") for (int n = 0; n < 2; ++n) _Pragma("unroll") for (int k = 0; k < 2; ++k) \
;         acc[ai][bj][m][n] = __builtin_amdgcn_mfma_f32_16x16x32_bf16(Bt[n][k], At[m][k], acc[ai][bj][m][n], 0, 0, 0); __builtin_amdgcn_s_setprio(0); } while (0)
; #define PG8_WAIT_V(n) asm volatile("s_waitcnt vmcnt(" #n ")" ::: "memory")
; #define PG8_WAIT_L(n) asm volatile("s_waitcnt lgkmcnt(" #n ")" ::: "memory")
; #define PG8_BAR __builtin_amdgcn_s_barrier()
; #define PG8_SCHED __builtin_amdgcn_sched_barrier(0)
; template <class Epi>
; __device__ __forceinline__ void gemm_phase(LAS unsigned char* lds, const Gemm g, const StaticOrder& S, const Epi& E, int wave_) {
;     ...
;             PG8_WAIT_V(8); PG8_WAIT_L(0); PG8_BAR; PG8_MMA(1, 0, At, B0); PG8_MMA(1, 1, At, B1); PG8_BAR; PG8_SCHED;
;             PG8_STAGE(PG8_SA(0, 1), a2 + hstepA, voffA); PG8_LDB(B0, 1, 0); PG8_LDB(B1, 1, 1); PG8_SCHED; PG8_LDA(At, 1, 0);
;             PG8_WAIT_V(8); PG8_WAIT_L(0); PG8_BAR; PG8_MMA(0, 0, At, B0); PG8_MMA(0, 1, At, B1); PG8_BAR; PG8_SCHED;
	s_setprio 1
	v_mfma_f32_16x16x32_bf16 v[116:119], v[88:91], v[160:163], v[116:119]
	v_mfma_f32_16x16x32_bf16 v[104:107], v[92:95], v[160:163], v[104:107]
	v_mfma_f32_16x16x32_bf16 v[84:87], v[88:91], v[164:167], v[84:87]
	v_mfma_f32_16x16x32_bf16 v[80:83], v[92:95], v[164:167], v[80:83]
	v_mfma_f32_16x16x32_bf16 v[76:79], v[88:91], v[176:179], v[76:79]
	v_mfma_f32_16x16x32_bf16 v[72:75], v[92:95], v[176:179], v[72:75]
	v_mfma_f32_16x16x32_bf16 v[68:71], v[88:91], v[180:183], v[68:71]
	v_mfma_f32_16x16x32_bf16 v[64:67], v[92:95], v[180:183], v[64:67]
	v_mfma_f32_16x16x32_bf16 v[116:119], v[96:99], v[168:171], v[116:119]
	v_mfma_f32_16x16x32_bf16 v[104:107], v[100:103], v[168:171], v[104:107]
	v_mfma_f32_16x16x32_bf16 v[84:87], v[96:99], v[172:175], v[84:87]
	v_mfma_f32_16x16x32_bf16 v[80:83], v[100:103], v[172:175], v[80:83]
	v_mfma_f32_16x16x32_bf16 v[76:79], v[96:99], v[192:195], v[76:79]
	v_mfma_f32_16x16x32_bf16 v[72:75], v[100:103], v[192:195], v[72:75]
	v_mfma_f32_16x16x32_bf16 v[68:71], v[96:99], v[196:199], v[68:71]
	v_mfma_f32_16x16x32_bf16 v[64:67], v[100:103], v[196:199], v[64:67]
	v_mfma_f32_16x16x32_bf16 v[28:31], v[108:111], v[160:163], v[28:31]
	v_mfma_f32_16x16x32_bf16 v[24:27], v[112:115], v[160:163], v[24:27]
	v_mfma_f32_16x16x32_bf16 v[20:23], v[108:111], v[164:167], v[20:23]
	v_mfma_f32_16x16x32_bf16 v[16:19], v[112:115], v[164:167], v[16:19]
	v_mfma_f32_16x16x32_bf16 v[12:15], v[108:111], v[176:179], v[12:15]
	v_mfma_f32_16x16x32_bf16 v[8:11], v[112:115], v[176:179], v[8:11]
	v_mfma_f32_16x16x32_bf16 v[4:7], v[108:111], v[180:183], v[4:7]
	v_mfma_f32_16x16x32_bf16 v[0:3], v[112:115], v[180:183], v[0:3]
	v_mfma_f32_16x16x32_bf16 v[28:31], v[120:123], v[168:171], v[28:31]
	v_mfma_f32_16x16x32_bf16 v[24:27], v[124:127], v[168:171], v[24:27]
	v_mfma_f32_16x16x32_bf16 v[20:23], v[120:123], v[172:175], v[20:23]
	v_mfma_f32_16x16x32_bf16 v[16:19], v[124:127], v[172:175], v[16:19]
	v_mfma_f32_16x16x32_bf16 v[12:15], v[120:123], v[192:195], v[12:15]
	v_mfma_f32_16x16x32_bf16 v[8:11], v[124:127], v[192:195], v[8:11]
	v_mfma_f32_16x16x32_bf16 v[4:7], v[120:123], v[196:199], v[4:7]
	v_mfma_f32_16x16x32_bf16 v[0:3], v[124:127], v[196:199], v[0:3]
	s_setprio 0
	s_barrier
	s_add_u32 s64, s64, 0x80000
	s_addc_u32 s65, s65, 0
	s_mov_b32 m0, s1
	s_nop 0
	global_load_lds_dwordx4 v184, s[64:65]
	v_mov_b32_e32 v88, v238
	s_mov_b32 m0, s69
	s_nop 0
	global_load_lds_dwordx4 v234, s[64:65]
	v_add_u32_e32 v92, s34, v238
	v_xad_u32 v100, v88, 64, s34
	v_mov_b32_e32 v108, v238
	s_add_i32 s64, 0, 0x1c000
	ds_read_b128 v[88:91], v92
	ds_read_b128 v[92:95], v92 offset:2048
	ds_read_b128 v[96:99], v100
	ds_read_b128 v[100:103], v100 offset:2048
	v_add_u32_e32 v112, s64, v238
	v_xad_u32 v124, v108, 64, s64
	ds_read_b128 v[108:111], v112
	ds_read_b128 v[112:115], v112 offset:2048
	ds_read_b128 v[120:123], v124
	ds_read_b128 v[124:127], v124 offset:2048
	v_mov_b32_e32 v160, v237
	s_nop 0
	v_xad_u32 v190, v160, 64, 0
	ds_read_b128 v[160:163], v191 offset:32768
	ds_read_b128 v[164:167], v191 offset:34816
	ds_read_b128 v[168:171], v190 offset:32768
	ds_read_b128 v[172:175], v190 offset:34816
	ds_read_b128 v[176:179], v191 offset:36864
	ds_read_b128 v[180:183], v191 offset:38912
	ds_read_b128 v[192:195], v190 offset:36864
	ds_read_b128 v[196:199], v190 offset:38912
	s_waitcnt vmcnt(8)
	s_waitcnt lgkmcnt(0)
	s_barrier
	s_setprio 1
	v_mfma_f32_16x16x32_bf16 v[156:159], v[88:91], v[160:163], v[156:159]
	v_mfma_f32_16x16x32_bf16 v[152:155], v[92:95], v[160:163], v[152:155]
	v_mfma_f32_16x16x32_bf16 v[148:151], v[88:91], v[164:167], v[148:151]
	v_mfma_f32_16x16x32_bf16 v[144:147], v[92:95], v[164:167], v[144:147]
	v_mfma_f32_16x16x32_bf16 v[140:143], v[88:91], v[176:179], v[140:143]
	v_mfma_f32_16x16x32_bf16 v[136:139], v[92:95], v[176:179], v[136:139]
	v_mfma_f32_16x16x32_bf16 v[132:135], v[88:91], v[180:183], v[132:135]
	v_mfma_f32_16x16x32_bf16 v[128:131], v[92:95], v[180:183], v[128:131]
	v_mfma_f32_16x16x32_bf16 v[156:159], v[96:99], v[168:171], v[156:159]
	v_mfma_f32_16x16x32_bf16 v[152:155], v[100:103], v[168:171], v[152:155]
	v_mfma_f32_16x16x32_bf16 v[148:151], v[96:99], v[172:175], v[148:151]
	v_mfma_f32_16x16x32_bf16 v[144:147], v[100:103], v[172:175], v[144:147]
	v_mfma_f32_16x16x32_bf16 v[140:143], v[96:99], v[192:195], v[140:143]
	v_mfma_f32_16x16x32_bf16 v[136:139], v[100:103], v[192:195], v[136:139]
	v_mfma_f32_16x16x32_bf16 v[132:135], v[96:99], v[196:199], v[132:135]
	v_mfma_f32_16x16x32_bf16 v[128:131], v[100:103], v[196:199], v[128:131]
	v_mfma_f32_16x16x32_bf16 v[60:63], v[108:111], v[160:163], v[60:63]
	s_add_u32 s64, s48, 0x80
	s_addc_u32 s65, s49, 0
	v_mfma_f32_16x16x32_bf16 v[56:59], v[112:115], v[160:163], v[56:59]
	v_mfma_f32_16x16x32_bf16 v[52:55], v[108:111], v[164:167], v[52:55]
	v_mfma_f32_16x16x32_bf16 v[48:51], v[112:115], v[164:167], v[48:51]
	v_mfma_f32_16x16x32_bf16 v[44:47], v[108:111], v[176:179], v[44:47]
	v_mfma_f32_16x16x32_bf16 v[40:43], v[112:115], v[176:179], v[40:43]
	v_mfma_f32_16x16x32_bf16 v[36:39], v[108:111], v[180:183], v[36:39]
	v_mfma_f32_16x16x32_bf16 v[32:35], v[112:115], v[180:183], v[32:35]
	v_mfma_f32_16x16x32_bf16 v[60:63], v[120:123], v[168:171], v[60:63]
	v_mfma_f32_16x16x32_bf16 v[56:59], v[124:127], v[168:171], v[56:59]
	v_mfma_f32_16x16x32_bf16 v[52:55], v[120:123], v[172:175], v[52:55]
	v_mfma_f32_16x16x32_bf16 v[48:51], v[124:127], v[172:175], v[48:51]
	v_mfma_f32_16x16x32_bf16 v[44:47], v[120:123], v[192:195], v[44:47]
	v_mfma_f32_16x16x32_bf16 v[40:43], v[124:127], v[192:195], v[40:43]
	v_mfma_f32_16x16x32_bf16 v[36:39], v[120:123], v[196:199], v[36:39]
	v_mfma_f32_16x16x32_bf16 v[32:35], v[124:127], v[196:199], v[32:35]
	s_setprio 0
	s_barrier
; #define PG8_STAGE(bufoff, gbase, voff) do { _Pragma("unroll") for (int _i = 0; _i < 2; ++_i) \
;         dma16((const char*)(gbase), (voff)[_i], ldsb + (bufoff) + ldsw + _i * 8192); } while (0)
; #define PG8_LDA(dst, b, h) do { const int a1_ = opqv(aoff0) ^ 64; _Pragma("unroll") for (int m = 0; m < 4; ++m) { dst[m][0] = *(const LAS bf16x8*)(lds + PG8_SA(b, h) + aoff0 + m * 2048); dst[m][1] = *(const LAS bf16x8*)(lds + PG8_SA(b, h) + a1_ + m * 2048); } } while (0)
; #define PG8_MMA(ai, bj, At, Bt) do { __builtin_amdgcn_s_setprio(1); _Pragma("unroll") for (int m = 0; m < 4; ++m) _Pragma("unroll") for (int n = 0; n < 2; ++n) _Pragma("unroll") for (int k = 0; k < 2; ++k) \
;         acc[ai][bj][m][n] = __builtin_amdgcn_mfma_f32_16x16x32_bf16(Bt[n][k], At[m][k], acc[ai][bj][m][n], 0, 0, 0); __builtin_amdgcn_s_setprio(0); } while (0)
; #define PG8_WAIT_V(n) asm volatile("s_waitcnt vmcnt(" #n ")" ::: "memory")
; #define PG8_WAIT_L(n) asm volatile("s_waitcnt lgkmcnt(" #n ")" ::: "memory")
; #define PG8_BAR __builtin_amdgcn_s_barrier()
; #define PG8_SCHED __builtin_amdgcn_sched_barrier(0)
; template <class Epi>
; __device__ __forceinline__ void gemm_phase(LAS unsigned char* lds, const Gemm g, const StaticOrder& S, const Epi& E, int wave_) {
;     ...
;             PG8_STAGE(PG8_SB(1, 0), b3, voffB); PG8_STAGE(PG8_SB(1, 1), b3 + hstepB, voffB); PG8_STAGE(PG8_SA(1, 0), a3, voffA); PG8_LDA(At, 1, 1);
;             PG8_WAIT_V(8); PG8_WAIT_L(0); PG8_BAR; PG8_MMA(1, 0, At, B0); PG8_MMA(1, 1, At, B1); PG8_BAR; PG8_SCHED;
;         }
;         if (wr == 0) PG8_BAR;
	s_add_u32 s48, s48, 0x80080
	s_addc_u32 s49, s49, 0
	v_mov_b32_e32 v160, v237
	s_nop 0
	s_nop 0
	v_xad_u32 v190, v160, 64, 0
	ds_read_b128 v[160:163], v191 offset:49152
	ds_read_b128 v[164:167], v191 offset:51200
	ds_read_b128 v[168:171], v190 offset:49152
	ds_read_b128 v[172:175], v190 offset:51200
	ds_read_b128 v[176:179], v191 offset:53248
	ds_read_b128 v[180:183], v191 offset:55296
	ds_read_b128 v[192:195], v190 offset:53248
	ds_read_b128 v[196:199], v190 offset:55296
	s_mov_b32 m0, s35
	s_nop 0
	global_load_lds_dwordx4 v233, s[64:65]
	s_mov_b32 m0, s33
	s_nop 0
	global_load_lds_dwordx4 v235, s[64:65]
	s_mov_b32 m0, s77
	s_nop 0
	global_load_lds_dwordx4 v233, s[48:49]
	s_mov_b32 m0, s3
	s_nop 0
	global_load_lds_dwordx4 v235, s[48:49]
	s_mov_b32 m0, s22
	s_nop 0
	global_load_lds_dwordx4 v184, s[46:47]
	s_mov_b32 m0, s2
	s_nop 0
	global_load_lds_dwordx4 v234, s[46:47]
	s_waitcnt vmcnt(8)
	s_waitcnt lgkmcnt(0)
	s_barrier
	s_setprio 1
	v_mfma_f32_16x16x32_bf16 v[116:119], v[88:91], v[160:163], v[116:119]
	v_mfma_f32_16x16x32_bf16 v[104:107], v[92:95], v[160:163], v[104:107]
	v_mfma_f32_16x16x32_bf16 v[84:87], v[88:91], v[164:167], v[84:87]
	v_mfma_f32_16x16x32_bf16 v[80:83], v[92:95], v[164:167], v[80:83]
	v_mfma_f32_16x16x32_bf16 v[76:79], v[88:91], v[176:179], v[76:79]
	v_mfma_f32_16x16x32_bf16 v[72:75], v[92:95], v[176:179], v[72:75]
	v_mfma_f32_16x16x32_bf16 v[68:71], v[88:91], v[180:183], v[68:71]
	v_mfma_f32_16x16x32_bf16 v[64:67], v[92:95], v[180:183], v[64:67]
	v_mfma_f32_16x16x32_bf16 v[116:119], v[96:99], v[168:171], v[116:119]
	v_mfma_f32_16x16x32_bf16 v[104:107], v[100:103], v[168:171], v[104:107]
	v_mfma_f32_16x16x32_bf16 v[84:87], v[96:99], v[172:175], v[84:87]
	v_mfma_f32_16x16x32_bf16 v[80:83], v[100:103], v[172:175], v[80:83]
	v_mfma_f32_16x16x32_bf16 v[76:79], v[96:99], v[192:195], v[76:79]
	v_mfma_f32_16x16x32_bf16 v[72:75], v[100:103], v[192:195], v[72:75]
	v_mfma_f32_16x16x32_bf16 v[68:71], v[96:99], v[196:199], v[68:71]
	v_mfma_f32_16x16x32_bf16 v[64:67], v[100:103], v[196:199], v[64:67]
	v_mfma_f32_16x16x32_bf16 v[28:31], v[108:111], v[160:163], v[28:31]
	v_mfma_f32_16x16x32_bf16 v[24:27], v[112:115], v[160:163], v[24:27]
	v_mfma_f32_16x16x32_bf16 v[20:23], v[108:111], v[164:167], v[20:23]
	v_mfma_f32_16x16x32_bf16 v[16:19], v[112:115], v[164:167], v[16:19]
	v_mfma_f32_16x16x32_bf16 v[12:15], v[108:111], v[176:179], v[12:15]
	v_mfma_f32_16x16x32_bf16 v[8:11], v[112:115], v[176:179], v[8:11]
	v_mfma_f32_16x16x32_bf16 v[4:7], v[108:111], v[180:183], v[4:7]
	v_mfma_f32_16x16x32_bf16 v[0:3], v[112:115], v[180:183], v[0:3]
	v_mfma_f32_16x16x32_bf16 v[28:31], v[120:123], v[168:171], v[28:31]
	v_mfma_f32_16x16x32_bf16 v[24:27], v[124:127], v[168:171], v[24:27]
	v_mfma_f32_16x16x32_bf16 v[20:23], v[120:123], v[172:175], v[20:23]
	v_mfma_f32_16x16x32_bf16 v[16:19], v[124:127], v[172:175], v[16:19]
	v_mfma_f32_16x16x32_bf16 v[12:15], v[120:123], v[192:195], v[12:15]
	v_mfma_f32_16x16x32_bf16 v[8:11], v[124:127], v[192:195], v[8:11]
	v_mfma_f32_16x16x32_bf16 v[4:7], v[120:123], v[196:199], v[4:7]
	v_mfma_f32_16x16x32_bf16 v[0:3], v[124:127], v[196:199], v[0:3]
	s_setprio 0
	s_barrier
	s_add_i32 s79, s79, 2
	s_add_u32 s75, s75, 0x100
	s_addc_u32 s78, s78, 0
	s_add_u32 s12, s12, 0x100
	s_addc_u32 s13, s13, 0
	s_cmp_gt_u32 s79, 29
	s_cbranch_scc0 .LBB0_1776
	v_readlane_b32 s12, v253, 13
	v_readlane_b32 s13, v253, 14
	s_and_b64 vcc, exec, s[12:13]
	s_cbranch_vccz .LBB0_1779
	s_barrier
